# v14jit4
# speedup vs baseline: 1.0459x; 1.0268x over previous
.LBB0_63:
	s_waitcnt vmcnt(2) lgkmcnt(0)
	s_barrier
	ds_read_b128 v[142:145], v132
	ds_read_b128 v[170:173], v154
	ds_read_b128 v[156:159], v132 offset:2048
	ds_read_b128 v[178:181], v154 offset:2048
	ds_read_b128 v[186:189], v154 offset:4096
	s_add_u32 s16, s63, s54
	s_addc_u32 s17, s64, 0
	s_mov_b32 m0, s39
	s_nop 0
	global_load_lds_dwordx4 v139, s[16:17]
	s_mov_b32 m0, s43
	s_nop 0
	global_load_lds_dwordx4 v152, s[16:17]
	s_waitcnt lgkmcnt(3)
	v_mfma_f32_16x16x32_bf16 v[128:131], v[142:145], v[170:173], v[128:131]
	s_waitcnt lgkmcnt(2)
	v_mfma_f32_16x16x32_bf16 v[124:127], v[156:159], v[170:173], v[124:127]
	ds_read_b128 v[194:197], v154 offset:6144
	s_waitcnt lgkmcnt(2)
	v_mfma_f32_16x16x32_bf16 v[112:115], v[142:145], v[178:181], v[112:115]
	v_mfma_f32_16x16x32_bf16 v[108:111], v[156:159], v[178:181], v[108:111]
	ds_read_b128 v[146:149], v132 offset:1024
	ds_read_b128 v[174:177], v154 offset:1024
	s_waitcnt lgkmcnt(3)
	v_mfma_f32_16x16x32_bf16 v[96:99], v[142:145], v[186:189], v[96:99]
	ds_read_b128 v[160:163], v132 offset:3072
	v_mfma_f32_16x16x32_bf16 v[92:95], v[156:159], v[186:189], v[92:95]
	ds_read_b128 v[182:185], v154 offset:3072
	s_waitcnt lgkmcnt(4)
	v_mfma_f32_16x16x32_bf16 v[80:83], v[142:145], v[194:197], v[80:83]
	v_mfma_f32_16x16x32_bf16 v[76:79], v[156:159], v[194:197], v[76:79]
	ds_read_b128 v[190:193], v154 offset:5120
	s_waitcnt lgkmcnt(3)
	v_mfma_f32_16x16x32_bf16 v[128:131], v[146:149], v[174:177], v[128:131]
	s_waitcnt lgkmcnt(2)
	v_mfma_f32_16x16x32_bf16 v[124:127], v[160:163], v[174:177], v[124:127]
	ds_read_b128 v[198:201], v154 offset:7168
	s_waitcnt lgkmcnt(2)
	v_mfma_f32_16x16x32_bf16 v[112:115], v[146:149], v[182:185], v[112:115]
	v_mfma_f32_16x16x32_bf16 v[108:111], v[160:163], v[182:185], v[108:111]
	ds_read_b128 v[202:205], v133
	s_waitcnt lgkmcnt(2)
	v_mfma_f32_16x16x32_bf16 v[96:99], v[146:149], v[190:193], v[96:99]
	ds_read_b128 v[210:213], v133 offset:2048
	v_mfma_f32_16x16x32_bf16 v[92:95], v[160:163], v[190:193], v[92:95]
	s_waitcnt lgkmcnt(2)
	v_mfma_f32_16x16x32_bf16 v[80:83], v[146:149], v[198:201], v[80:83]
	v_mfma_f32_16x16x32_bf16 v[76:79], v[160:163], v[198:201], v[76:79]
	s_add_u32 s16, s18, s54
	s_addc_u32 s17, s19, 0
	s_mov_b32 m0, s40
	s_nop 0
	global_load_lds_dwordx4 v138, s[16:17]
	s_mov_b32 m0, s44
	s_nop 0
	global_load_lds_dwordx4 v140, s[16:17]
	s_waitcnt lgkmcnt(1)
	v_mfma_f32_16x16x32_bf16 v[120:123], v[202:205], v[170:173], v[120:123]
	s_waitcnt lgkmcnt(0)
	v_mfma_f32_16x16x32_bf16 v[116:119], v[210:213], v[170:173], v[116:119]
	v_mfma_f32_16x16x32_bf16 v[104:107], v[202:205], v[178:181], v[104:107]
	v_mfma_f32_16x16x32_bf16 v[100:103], v[210:213], v[178:181], v[100:103]
	ds_read_b128 v[206:209], v133 offset:1024
	v_mfma_f32_16x16x32_bf16 v[88:91], v[202:205], v[186:189], v[88:91]
	ds_read_b128 v[214:217], v133 offset:3072
	v_mfma_f32_16x16x32_bf16 v[84:87], v[210:213], v[186:189], v[84:87]
	v_mfma_f32_16x16x32_bf16 v[72:75], v[202:205], v[194:197], v[72:75]
	v_mfma_f32_16x16x32_bf16 v[68:71], v[210:213], v[194:197], v[68:71]
	s_waitcnt lgkmcnt(1)
	v_mfma_f32_16x16x32_bf16 v[120:123], v[206:209], v[174:177], v[120:123]
	s_waitcnt lgkmcnt(0)
	v_mfma_f32_16x16x32_bf16 v[116:119], v[214:217], v[174:177], v[116:119]
	v_mfma_f32_16x16x32_bf16 v[104:107], v[206:209], v[182:185], v[104:107]
	v_mfma_f32_16x16x32_bf16 v[100:103], v[214:217], v[182:185], v[100:103]
	v_mfma_f32_16x16x32_bf16 v[88:91], v[206:209], v[190:193], v[88:91]
	v_mfma_f32_16x16x32_bf16 v[84:87], v[214:217], v[190:193], v[84:87]
	v_mfma_f32_16x16x32_bf16 v[72:75], v[206:209], v[198:201], v[72:75]
	v_mfma_f32_16x16x32_bf16 v[68:71], v[214:217], v[198:201], v[68:71]
	s_waitcnt vmcnt(4) lgkmcnt(0)
	s_barrier
	ds_read_b128 v[170:173], v154 offset:16384
	ds_read_b128 v[178:181], v154 offset:18432
	ds_read_b128 v[186:189], v154 offset:20480
	s_add_u32 s16, s61, s54
	s_addc_u32 s17, s62, 0
	s_mov_b32 m0, s41
	s_nop 0
	global_load_lds_dwordx4 v139, s[16:17]
	s_mov_b32 m0, s45
	s_nop 0
	global_load_lds_dwordx4 v152, s[16:17]
	s_waitcnt lgkmcnt(2)
	v_mfma_f32_16x16x32_bf16 v[64:67], v[142:145], v[170:173], v[64:67]
	v_mfma_f32_16x16x32_bf16 v[60:63], v[156:159], v[170:173], v[60:63]
	ds_read_b128 v[194:197], v154 offset:22528
	s_waitcnt lgkmcnt(2)
	v_mfma_f32_16x16x32_bf16 v[48:51], v[142:145], v[178:181], v[48:51]
	v_mfma_f32_16x16x32_bf16 v[44:47], v[156:159], v[178:181], v[44:47]
	ds_read_b128 v[174:177], v154 offset:17408
	s_waitcnt lgkmcnt(2)
	v_mfma_f32_16x16x32_bf16 v[32:35], v[142:145], v[186:189], v[32:35]
	v_mfma_f32_16x16x32_bf16 v[28:31], v[156:159], v[186:189], v[28:31]
	ds_read_b128 v[182:185], v154 offset:19456
	s_waitcnt lgkmcnt(2)
	v_mfma_f32_16x16x32_bf16 v[16:19], v[142:145], v[194:197], v[16:19]
	v_mfma_f32_16x16x32_bf16 v[12:15], v[156:159], v[194:197], v[12:15]
	ds_read_b128 v[190:193], v154 offset:21504
	s_waitcnt lgkmcnt(2)
	v_mfma_f32_16x16x32_bf16 v[64:67], v[146:149], v[174:177], v[64:67]
	v_mfma_f32_16x16x32_bf16 v[60:63], v[160:163], v[174:177], v[60:63]
	ds_read_b128 v[198:201], v154 offset:23552
	s_waitcnt lgkmcnt(2)
	v_mfma_f32_16x16x32_bf16 v[48:51], v[146:149], v[182:185], v[48:51]
	v_mfma_f32_16x16x32_bf16 v[44:47], v[160:163], v[182:185], v[44:47]
	s_waitcnt lgkmcnt(1)
	v_mfma_f32_16x16x32_bf16 v[32:35], v[146:149], v[190:193], v[32:35]
	v_mfma_f32_16x16x32_bf16 v[28:31], v[160:163], v[190:193], v[28:31]
	s_waitcnt lgkmcnt(0)
	v_mfma_f32_16x16x32_bf16 v[16:19], v[146:149], v[198:201], v[16:19]
	v_mfma_f32_16x16x32_bf16 v[12:15], v[160:163], v[198:201], v[12:15]
	s_add_u32 s16, s59, s54
	s_addc_u32 s17, s60, 0
	s_mov_b32 m0, s42
	s_nop 0
	global_load_lds_dwordx4 v138, s[16:17]
	s_mov_b32 m0, s46
	s_nop 0
	global_load_lds_dwordx4 v140, s[16:17]
	v_mfma_f32_16x16x32_bf16 v[56:59], v[202:205], v[170:173], v[56:59]
	s_add_u32 s16, s57, s54
	s_addc_u32 s17, s58, 0
	s_add_u32 s65, s55, s54
	v_mfma_f32_16x16x32_bf16 v[52:55], v[210:213], v[170:173], v[52:55]
	s_addc_u32 s66, s56, 0
	v_mfma_f32_16x16x32_bf16 v[40:43], v[202:205], v[178:181], v[40:43]
	v_mfma_f32_16x16x32_bf16 v[36:39], v[210:213], v[178:181], v[36:39]
	v_mfma_f32_16x16x32_bf16 v[24:27], v[202:205], v[186:189], v[24:27]
	v_mfma_f32_16x16x32_bf16 v[20:23], v[210:213], v[186:189], v[20:23]
	v_mfma_f32_16x16x32_bf16 v[8:11], v[202:205], v[194:197], v[8:11]
	v_mfma_f32_16x16x32_bf16 v[4:7], v[210:213], v[194:197], v[4:7]
	v_mfma_f32_16x16x32_bf16 v[56:59], v[206:209], v[174:177], v[56:59]
	v_mfma_f32_16x16x32_bf16 v[52:55], v[214:217], v[174:177], v[52:55]
	v_mfma_f32_16x16x32_bf16 v[40:43], v[206:209], v[182:185], v[40:43]
	v_mfma_f32_16x16x32_bf16 v[36:39], v[214:217], v[182:185], v[36:39]
	v_mfma_f32_16x16x32_bf16 v[24:27], v[206:209], v[190:193], v[24:27]
	v_mfma_f32_16x16x32_bf16 v[20:23], v[214:217], v[190:193], v[20:23]
	v_mfma_f32_16x16x32_bf16 v[8:11], v[206:209], v[198:201], v[8:11]
	v_mfma_f32_16x16x32_bf16 v[4:7], v[214:217], v[198:201], v[4:7]
	s_waitcnt vmcnt(2) lgkmcnt(0)
	s_barrier
; template <class Epi, class Sched>
; __device__ __forceinline__ void gemm_simple(PG8_LAS unsigned char* lds, const Gemm g, const Sched& S, const Epi& E, int wave_s) {
;     ...
;             const char* a2 = last ? nA : cA + (size_t)(t + 2) * kstep; const char* b2 = last ? nB : cB + (size_t)(t + 2) * kstep;
;             PG8_TILE(1, a2, b2, (!last || has_next));
	ds_read_b128 v[142:145], v134
	ds_read_b128 v[170:173], v154 offset:32768
	ds_read_b128 v[156:159], v134 offset:2048
	ds_read_b128 v[178:181], v154 offset:34816
	ds_read_b128 v[186:189], v154 offset:36864
	s_cmp_eq_u32 s54, s10
	s_cselect_b32 s17, s5, s17
	s_cselect_b32 s16, s4, s16
	s_cselect_b32 s67, s9, s66
	s_cselect_b32 s66, s8, s65
	s_mov_b32 m0, s26
	s_nop 0
	global_load_lds_dwordx4 v139, s[66:67]
	s_mov_b32 m0, s27
	s_nop 0
	global_load_lds_dwordx4 v152, s[66:67]
	s_waitcnt lgkmcnt(3)
	v_mfma_f32_16x16x32_bf16 v[128:131], v[142:145], v[170:173], v[128:131]
	s_waitcnt lgkmcnt(2)
	v_mfma_f32_16x16x32_bf16 v[124:127], v[156:159], v[170:173], v[124:127]
	ds_read_b128 v[194:197], v154 offset:38912
	s_waitcnt lgkmcnt(2)
	v_mfma_f32_16x16x32_bf16 v[112:115], v[142:145], v[178:181], v[112:115]
	v_mfma_f32_16x16x32_bf16 v[108:111], v[156:159], v[178:181], v[108:111]
	ds_read_b128 v[146:149], v134 offset:1024
	ds_read_b128 v[174:177], v154 offset:33792
	s_waitcnt lgkmcnt(3)
	v_mfma_f32_16x16x32_bf16 v[96:99], v[142:145], v[186:189], v[96:99]
	ds_read_b128 v[160:163], v134 offset:3072
	v_mfma_f32_16x16x32_bf16 v[92:95], v[156:159], v[186:189], v[92:95]
	ds_read_b128 v[182:185], v154 offset:35840
	s_waitcnt lgkmcnt(4)
	v_mfma_f32_16x16x32_bf16 v[80:83], v[142:145], v[194:197], v[80:83]
	v_mfma_f32_16x16x32_bf16 v[76:79], v[156:159], v[194:197], v[76:79]
	ds_read_b128 v[190:193], v154 offset:37888
	s_waitcnt lgkmcnt(3)
	v_mfma_f32_16x16x32_bf16 v[128:131], v[146:149], v[174:177], v[128:131]
	s_waitcnt lgkmcnt(2)
	v_mfma_f32_16x16x32_bf16 v[124:127], v[160:163], v[174:177], v[124:127]
	ds_read_b128 v[198:201], v154 offset:39936
	s_waitcnt lgkmcnt(2)
	v_mfma_f32_16x16x32_bf16 v[112:115], v[146:149], v[182:185], v[112:115]
	v_mfma_f32_16x16x32_bf16 v[108:111], v[160:163], v[182:185], v[108:111]
	ds_read_b128 v[202:205], v135
	s_waitcnt lgkmcnt(2)
	v_mfma_f32_16x16x32_bf16 v[96:99], v[146:149], v[190:193], v[96:99]
	ds_read_b128 v[210:213], v135 offset:2048
	v_mfma_f32_16x16x32_bf16 v[92:95], v[160:163], v[190:193], v[92:95]
	s_waitcnt lgkmcnt(2)
	v_mfma_f32_16x16x32_bf16 v[80:83], v[146:149], v[198:201], v[80:83]
	v_mfma_f32_16x16x32_bf16 v[76:79], v[160:163], v[198:201], v[76:79]
	s_mov_b32 m0, s25
	s_nop 0
	global_load_lds_dwordx4 v138, s[16:17]
	s_mov_b32 m0, s28
	s_nop 0
	global_load_lds_dwordx4 v140, s[16:17]
	s_waitcnt lgkmcnt(1)
	v_mfma_f32_16x16x32_bf16 v[120:123], v[202:205], v[170:173], v[120:123]
	s_waitcnt lgkmcnt(0)
	v_mfma_f32_16x16x32_bf16 v[116:119], v[210:213], v[170:173], v[116:119]
	v_mfma_f32_16x16x32_bf16 v[104:107], v[202:205], v[178:181], v[104:107]
	v_mfma_f32_16x16x32_bf16 v[100:103], v[210:213], v[178:181], v[100:103]
	ds_read_b128 v[206:209], v135 offset:1024
	v_mfma_f32_16x16x32_bf16 v[88:91], v[202:205], v[186:189], v[88:91]
	ds_read_b128 v[214:217], v135 offset:3072
	v_mfma_f32_16x16x32_bf16 v[84:87], v[210:213], v[186:189], v[84:87]
	v_mfma_f32_16x16x32_bf16 v[72:75], v[202:205], v[194:197], v[72:75]
	v_mfma_f32_16x16x32_bf16 v[68:71], v[210:213], v[194:197], v[68:71]
	s_waitcnt lgkmcnt(1)
	v_mfma_f32_16x16x32_bf16 v[120:123], v[206:209], v[174:177], v[120:123]
	s_waitcnt lgkmcnt(0)
	v_mfma_f32_16x16x32_bf16 v[116:119], v[214:217], v[174:177], v[116:119]
	v_mfma_f32_16x16x32_bf16 v[104:107], v[206:209], v[182:185], v[104:107]
	v_mfma_f32_16x16x32_bf16 v[100:103], v[214:217], v[182:185], v[100:103]
	v_mfma_f32_16x16x32_bf16 v[88:91], v[206:209], v[190:193], v[88:91]
	v_mfma_f32_16x16x32_bf16 v[84:87], v[214:217], v[190:193], v[84:87]
	v_mfma_f32_16x16x32_bf16 v[72:75], v[206:209], v[198:201], v[72:75]
	v_mfma_f32_16x16x32_bf16 v[68:71], v[214:217], v[198:201], v[68:71]
	s_waitcnt vmcnt(4) lgkmcnt(0)
	s_barrier
	ds_read_b128 v[170:173], v154 offset:49152
	ds_read_b128 v[178:181], v154 offset:51200
	ds_read_b128 v[186:189], v154 offset:53248
	s_add_u32 s66, s66, 0x160000
	s_addc_u32 s67, s67, 0
	s_mov_b32 m0, s29
	s_nop 0
	global_load_lds_dwordx4 v139, s[66:67]
	s_mov_b32 m0, s36
	s_nop 0
	global_load_lds_dwordx4 v152, s[66:67]
	s_waitcnt lgkmcnt(2)
	v_mfma_f32_16x16x32_bf16 v[64:67], v[142:145], v[170:173], v[64:67]
	v_mfma_f32_16x16x32_bf16 v[60:63], v[156:159], v[170:173], v[60:63]
	ds_read_b128 v[194:197], v154 offset:55296
	s_waitcnt lgkmcnt(2)
	v_mfma_f32_16x16x32_bf16 v[48:51], v[142:145], v[178:181], v[48:51]
	v_mfma_f32_16x16x32_bf16 v[44:47], v[156:159], v[178:181], v[44:47]
	ds_read_b128 v[174:177], v154 offset:50176
	s_waitcnt lgkmcnt(2)
	v_mfma_f32_16x16x32_bf16 v[32:35], v[142:145], v[186:189], v[32:35]
	v_mfma_f32_16x16x32_bf16 v[28:31], v[156:159], v[186:189], v[28:31]
	ds_read_b128 v[182:185], v154 offset:52224
	s_waitcnt lgkmcnt(2)
	v_mfma_f32_16x16x32_bf16 v[16:19], v[142:145], v[194:197], v[16:19]
	v_mfma_f32_16x16x32_bf16 v[12:15], v[156:159], v[194:197], v[12:15]
	ds_read_b128 v[190:193], v154 offset:54272
	s_waitcnt lgkmcnt(2)
	v_mfma_f32_16x16x32_bf16 v[64:67], v[146:149], v[174:177], v[64:67]
	v_mfma_f32_16x16x32_bf16 v[60:63], v[160:163], v[174:177], v[60:63]
	ds_read_b128 v[198:201], v154 offset:56320
	s_waitcnt lgkmcnt(2)
	v_mfma_f32_16x16x32_bf16 v[48:51], v[146:149], v[182:185], v[48:51]
	v_mfma_f32_16x16x32_bf16 v[44:47], v[160:163], v[182:185], v[44:47]
	s_waitcnt lgkmcnt(1)
	v_mfma_f32_16x16x32_bf16 v[32:35], v[146:149], v[190:193], v[32:35]
	v_mfma_f32_16x16x32_bf16 v[28:31], v[160:163], v[190:193], v[28:31]
	s_waitcnt lgkmcnt(0)
; __device__ __forceinline__ unsigned cvt_pk_bf16(float lo, float hi) { unsigned r; asm volatile("v_cvt_pk_bf16_f32 %0, %1, %2" : "=v"(r) : "v"(lo), "v"(hi)); return r; }
; __device__ __forceinline__ float bflo(unsigned w) { return __uint_as_float(w << 16); }
; __device__ __forceinline__ float bfhi(unsigned w) { return __uint_as_float(w & 0xffff0000u); }
;     __device__ __forceinline__ void operator()(const f32x4 (&acc)[2][2][4][2], const Unit& u, int wr, int wc, int fr, int fq, const LAS float* rt) const {
;         const int row0 = u.pm * 256 + wr * 64 + fr, col0 = u.pn * 256 + wc * 32 + 8 * fq, lane = fq * 16 + fr;
; #pragma unroll
;         for (int ai = 0; ai < 2; ++ai)
; #pragma unroll
;             for (int m = 0; m < 4; ++m) { const size_t row = (size_t)(row0 + ai * 128 + m * 16); const float rs = (MODE == 1) ? rt[ai * 128 + wr * 64 + m * 16 + fr] : 1.0f; float ss = 0.f;
; #pragma unroll
;                 for (int bj = 0; bj < 2; ++bj) { const size_t o = row * DM + col0 + bj * 128; const u32x4 xv = *(const u32x4*)(xin + o);
;                     f32x4 v0 = acc[ai][bj][m][0], v1 = acc[ai][bj][m][1];
;                     if (MODE == 1) { const u32x4 p = *(const u32x4*)(pe + o);
;                         v0[0] = sigmoidf_(v0[0] * rs) * bflo(p.x); v0[1] = sigmoidf_(v0[1] * rs) * bfhi(p.x); v0[2] = sigmoidf_(v0[2] * rs) * bflo(p.y); v0[3] = sigmoidf_(v0[3] * rs) * bfhi(p.y);
;                         v1[0] = sigmoidf_(v1[0] * rs) * bflo(p.z); v1[1] = sigmoidf_(v1[1] * rs) * bfhi(p.z); v1[2] = sigmoidf_(v1[2] * rs) * bflo(p.w); v1[3] = sigmoidf_(v1[3] * rs) * bfhi(p.w); }
;                     v0[0] += bflo(xv.x); v0[1] += bfhi(xv.x); v0[2] += bflo(xv.y); v0[3] += bfhi(xv.y); v1[0] += bflo(xv.z); v1[1] += bfhi(xv.z); v1[2] += bflo(xv.w); v1[3] += bfhi(xv.w);
;                     ss += (v0[0] * v0[0] + v0[1] * v0[1]) + (v0[2] * v0[2] + v0[3] * v0[3]) + (v1[0] * v1[0] + v1[1] * v1[1]) + (v1[2] * v1[2] + v1[3] * v1[3]);
;                     u32x4 w; w.x = cvt_pk_bf16(v0[0], v0[1]); w.y = cvt_pk_bf16(v0[2], v0[3]); w.z = cvt_pk_bf16(v1[0], v1[1]); w.w = cvt_pk_bf16(v1[2], v1[3]);
;                     __builtin_nontemporal_store(w, (u32x4*)(xout + o)); }
;                 ss += shx(ss, 16, lane); ss += shx(ss, 32, lane);
;                 if (fq == 0) ssq_out[row * 32 + u.pn * 4 + wc] = ss; }
	v_mfma_f32_16x16x32_bf16 v[16:19], v[146:149], v[198:201], v[16:19]
	v_mfma_f32_16x16x32_bf16 v[12:15], v[160:163], v[198:201], v[12:15]
	s_add_u32 s16, s16, 0x160000
	s_addc_u32 s17, s17, 0
	s_mov_b32 m0, s37
	s_nop 0
	global_load_lds_dwordx4 v138, s[16:17]
	s_mov_b32 m0, s38
	s_nop 0
	global_load_lds_dwordx4 v140, s[16:17]
	s_add_i32 s53, s53, 2
	s_add_u32 s10, s10, 0xffffff00
	s_addc_u32 s11, s11, -1
	s_add_u32 s55, s55, 0x100
	s_addc_u32 s56, s56, 0
	s_add_u32 s57, s57, 0x100
	s_addc_u32 s58, s58, 0
	s_add_u32 s59, s59, 0x100
	v_mfma_f32_16x16x32_bf16 v[56:59], v[202:205], v[170:173], v[56:59]
	s_addc_u32 s60, s60, 0
	s_add_u32 s61, s61, 0x100
	s_addc_u32 s62, s62, 0
	v_mfma_f32_16x16x32_bf16 v[52:55], v[210:213], v[170:173], v[52:55]
	s_add_u32 s18, s18, 0x100
	s_addc_u32 s19, s19, 0
	s_add_u32 s63, s63, 0x100
	v_mfma_f32_16x16x32_bf16 v[40:43], v[202:205], v[178:181], v[40:43]
	s_addc_u32 s64, s64, 0
	s_cmpk_lt_u32 s53, 0x56
	v_mfma_f32_16x16x32_bf16 v[36:39], v[210:213], v[178:181], v[36:39]
	v_mfma_f32_16x16x32_bf16 v[24:27], v[202:205], v[186:189], v[24:27]
	v_mfma_f32_16x16x32_bf16 v[20:23], v[210:213], v[186:189], v[20:23]
	v_mfma_f32_16x16x32_bf16 v[8:11], v[202:205], v[194:197], v[8:11]
	v_mfma_f32_16x16x32_bf16 v[4:7], v[210:213], v[194:197], v[4:7]
	v_mfma_f32_16x16x32_bf16 v[56:59], v[206:209], v[174:177], v[56:59]
	v_mfma_f32_16x16x32_bf16 v[52:55], v[214:217], v[174:177], v[52:55]
	v_mfma_f32_16x16x32_bf16 v[40:43], v[206:209], v[182:185], v[40:43]
	v_mfma_f32_16x16x32_bf16 v[36:39], v[214:217], v[182:185], v[36:39]
	v_mfma_f32_16x16x32_bf16 v[24:27], v[206:209], v[190:193], v[24:27]
	v_mfma_f32_16x16x32_bf16 v[20:23], v[214:217], v[190:193], v[20:23]
	v_mfma_f32_16x16x32_bf16 v[8:11], v[206:209], v[198:201], v[8:11]
	v_mfma_f32_16x16x32_bf16 v[4:7], v[214:217], v[198:201], v[4:7]
	s_cbranch_scc1 .LBB0_63
	v_mov_b32_e32 v132, v141
	s_lshl_b32 s10, s52, 8
	v_mbcnt_lo_u32_b32 v132, -1, v132
	v_mbcnt_hi_u32_b32 v135, -1, v132
	v_and_b32_e32 v136, 15, v135
	s_add_i32 s10, s10, s23
	v_or_b32_e32 v134, s10, v136
	s_lshl_b32 s10, s35, 8
	v_ashrrev_i32_e32 v137, 4, v135
	s_or_b32 s10, s10, s24
	v_lshl_add_u32 v132, v137, 3, s10
	v_lshlrev_b32_e32 v137, 6, v137
	v_lshlrev_b32_e32 v136, 2, v136
	s_movk_i32 s10, 0x80
	v_cmp_gt_u32_e32 vcc, 16, v135
	v_ashrrev_i32_e32 v135, 31, v134
	v_bitop3_b32 v156, v137, 64, v136 bitop3:0x36
	v_bitop3_b32 v155, v137, s10, v136 bitop3:0x36
	v_lshlrev_b64 v[136:137], 12, v[134:135]
	v_ashrrev_i32_e32 v133, 31, v132
	v_lshl_add_u64 v[136:137], s[94:95], 0, v[136:137]
	v_lshl_add_u64 v[136:137], v[132:133], 1, v[136:137]
	v_lshlrev_b32_e32 v236, 12, v134
	v_lshl_add_u32 v236, v132, 1, v236
	global_load_dwordx4 v[172:175], v236, s[94:95]
	global_load_dwordx4 v[176:179], v236, s[94:95] offset:256
	v_add_u32_e32 v237, 0x10000, v236
	global_load_dwordx4 v[180:183], v237, s[94:95]
	global_load_dwordx4 v[184:187], v237, s[94:95] offset:256
	v_add_u32_e32 v237, 0x20000, v236
	global_load_dwordx4 v[188:191], v237, s[94:95]
	global_load_dwordx4 v[192:195], v237, s[94:95] offset:256
	v_add_u32_e32 v237, 0x30000, v236
	global_load_dwordx4 v[196:199], v237, s[94:95]
	global_load_dwordx4 v[200:203], v237, s[94:95] offset:256
	v_add_u32_e32 v237, 0x80000, v236
	global_load_dwordx4 v[204:207], v237, s[94:95]
	global_load_dwordx4 v[208:211], v237, s[94:95] offset:256
	v_add_u32_e32 v237, 0x90000, v236
	global_load_dwordx4 v[212:215], v237, s[94:95]
	global_load_dwordx4 v[216:219], v237, s[94:95] offset:256
	v_add_u32_e32 v237, 0xa0000, v236
	global_load_dwordx4 v[220:223], v237, s[94:95]
	global_load_dwordx4 v[224:227], v237, s[94:95] offset:256
	v_add_u32_e32 v237, 0xb0000, v236
	global_load_dwordx4 v[228:231], v237, s[94:95]
	global_load_dwordx4 v[232:235], v237, s[94:95] offset:256
	s_lshl_b32 s10, s35, 2
	s_ashr_i32 s11, s10, 31
	s_waitcnt vmcnt(15)
	s_nop 1
	v_mov_b64_e32 v[142:143], v[172:173]
	v_mov_b64_e32 v[144:145], v[174:175]
	v_lshlrev_b32_e32 v146, 16, v142
	v_and_b32_e32 v142, 0xffff0000, v142
	v_add_f32_e32 v129, v129, v142
	v_lshlrev_b32_e32 v142, 16, v143
	v_add_f32_e32 v130, v130, v142
	v_and_b32_e32 v142, 0xffff0000, v143
	v_add_f32_e32 v131, v131, v142
	v_lshlrev_b32_e32 v142, 16, v144
	v_add_f32_e32 v142, v124, v142
	v_and_b32_e32 v124, 0xffff0000, v144
	v_add_f32_e32 v143, v125, v124
	v_lshlrev_b32_e32 v124, 16, v145
	v_add_f32_e32 v144, v126, v124
	v_and_b32_e32 v124, 0xffff0000, v145
	v_add_f32_e32 v128, v128, v146
	v_add_f32_e32 v127, v127, v124
	v_mul_f32_e32 v124, v129, v129
	v_mul_f32_e32 v125, v131, v131
	v_fmac_f32_e32 v124, v128, v128
	v_fmac_f32_e32 v125, v130, v130
	v_add_f32_e32 v124, v124, v125
	v_mul_f32_e32 v125, v143, v143
	v_fmac_f32_e32 v125, v142, v142
	v_add_f32_e32 v124, v125, v124
	v_mul_f32_e32 v125, v127, v127
	v_fmac_f32_e32 v125, v144, v144
	v_add_f32_e32 v145, v125, v124
	v_cvt_pk_bf16_f32 v124, v128, v129
	v_cvt_pk_bf16_f32 v125, v130, v131
	v_cvt_pk_bf16_f32 v126, v142, v143
	v_cvt_pk_bf16_f32 v127, v144, v127
	global_store_dwordx4 v[136:137], v[124:127], off nt
	s_waitcnt vmcnt(15)
	s_nop 1
	v_mov_b64_e32 v[124:125], v[176:177]
	v_mov_b64_e32 v[126:127], v[178:179]
	v_lshlrev_b32_e32 v128, 16, v124
	v_and_b32_e32 v124, 0xffff0000, v124
	v_add_f32_e32 v121, v121, v124
	v_lshlrev_b32_e32 v124, 16, v125
	v_add_f32_e32 v122, v122, v124
	v_and_b32_e32 v124, 0xffff0000, v125
	v_add_f32_e32 v123, v123, v124
	v_lshlrev_b32_e32 v124, 16, v126
	v_add_f32_e32 v124, v116, v124
	v_and_b32_e32 v116, 0xffff0000, v126
	v_add_f32_e32 v125, v117, v116
	v_lshlrev_b32_e32 v116, 16, v127
	v_add_f32_e32 v126, v118, v116
	v_and_b32_e32 v116, 0xffff0000, v127
	v_add_f32_e32 v120, v120, v128
	v_add_f32_e32 v119, v119, v116
	v_mul_f32_e32 v116, v121, v121
	v_mul_f32_e32 v117, v123, v123
	v_fmac_f32_e32 v116, v120, v120
	v_fmac_f32_e32 v117, v122, v122
	v_add_f32_e32 v116, v116, v117
	v_mul_f32_e32 v117, v125, v125
	v_fmac_f32_e32 v117, v124, v124
	v_add_f32_e32 v116, v117, v116
	v_mul_f32_e32 v117, v119, v119
	v_fmac_f32_e32 v117, v126, v126
	v_add_f32_e32 v116, v117, v116
	v_add_f32_e32 v127, v145, v116
	v_cvt_pk_bf16_f32 v116, v120, v121
	v_cvt_pk_bf16_f32 v117, v122, v123
	v_cvt_pk_bf16_f32 v118, v124, v125
	v_cvt_pk_bf16_f32 v119, v126, v119
	global_store_dwordx4 v[136:137], v[116:119], off offset:256 nt
	ds_bpermute_b32 v116, v156, v127
	s_waitcnt lgkmcnt(0)
	v_add_f32_e32 v116, v127, v116
	ds_bpermute_b32 v117, v155, v116
	s_and_saveexec_b64 s[16:17], vcc
	s_cbranch_execz .LBB0_66
	v_readlane_b32 s18, v255, 2
	v_lshlrev_b64 v[118:119], 7, v[134:135]
	v_readlane_b32 s19, v255, 3
	s_lshl_b32 s84, s22, 2
	s_mov_b32 s69, 0xf800000
	v_lshl_add_u64 v[118:119], s[18:19], 0, v[118:119]
	v_lshl_add_u64 v[118:119], s[10:11], 2, v[118:119]
	v_lshl_add_u64 v[118:119], v[118:119], 0, s[84:85]
	s_waitcnt lgkmcnt(0)
	v_add_f32_e32 v116, v116, v117
	global_store_dword v[118:119], v116, off

.LBB0_95:
	s_waitcnt vmcnt(2) lgkmcnt(0)
	s_barrier
	ds_read_b128 v[142:145], v132
	ds_read_b128 v[174:177], v156
	ds_read_b128 v[158:161], v132 offset:2048
	ds_read_b128 v[182:185], v156 offset:2048
	ds_read_b128 v[190:193], v156 offset:4096
	s_add_u32 s64, s10, s63
	s_addc_u32 s65, s11, 0
	s_add_u32 s28, s64, 0x80
	s_addc_u32 s29, s65, 0
	s_mov_b32 m0, s48
	s_nop 0
	global_load_lds_dwordx4 v140, s[28:29]
	s_mov_b32 m0, s52
	s_nop 0
	global_load_lds_dwordx4 v153, s[28:29]
	s_waitcnt lgkmcnt(3)
	v_mfma_f32_16x16x32_bf16 v[124:127], v[142:145], v[174:177], v[124:127]
	s_waitcnt lgkmcnt(2)
	v_mfma_f32_16x16x32_bf16 v[116:119], v[158:161], v[174:177], v[116:119]
	ds_read_b128 v[198:201], v156 offset:6144
	s_waitcnt lgkmcnt(2)
	v_mfma_f32_16x16x32_bf16 v[108:111], v[142:145], v[182:185], v[108:111]
	v_mfma_f32_16x16x32_bf16 v[100:103], v[158:161], v[182:185], v[100:103]
	ds_read_b128 v[146:149], v132 offset:1024
	ds_read_b128 v[178:181], v156 offset:1024
	s_waitcnt lgkmcnt(3)
	v_mfma_f32_16x16x32_bf16 v[92:95], v[142:145], v[190:193], v[92:95]
	ds_read_b128 v[170:173], v132 offset:3072
	v_mfma_f32_16x16x32_bf16 v[84:87], v[158:161], v[190:193], v[84:87]
	ds_read_b128 v[186:189], v156 offset:3072
	s_waitcnt lgkmcnt(4)
	v_mfma_f32_16x16x32_bf16 v[76:79], v[142:145], v[198:201], v[76:79]
	v_mfma_f32_16x16x32_bf16 v[68:71], v[158:161], v[198:201], v[68:71]
	ds_read_b128 v[194:197], v156 offset:5120
	s_waitcnt lgkmcnt(3)
	v_mfma_f32_16x16x32_bf16 v[124:127], v[146:149], v[178:181], v[124:127]
	s_waitcnt lgkmcnt(2)
	v_mfma_f32_16x16x32_bf16 v[116:119], v[170:173], v[178:181], v[116:119]
	ds_read_b128 v[202:205], v156 offset:7168
	s_waitcnt lgkmcnt(2)
	v_mfma_f32_16x16x32_bf16 v[108:111], v[146:149], v[186:189], v[108:111]
	v_mfma_f32_16x16x32_bf16 v[100:103], v[170:173], v[186:189], v[100:103]
	ds_read_b128 v[206:209], v133
	s_waitcnt lgkmcnt(2)
	v_mfma_f32_16x16x32_bf16 v[92:95], v[146:149], v[194:197], v[92:95]
	ds_read_b128 v[214:217], v133 offset:2048
	v_mfma_f32_16x16x32_bf16 v[84:87], v[170:173], v[194:197], v[84:87]
	s_waitcnt lgkmcnt(2)
	v_mfma_f32_16x16x32_bf16 v[76:79], v[146:149], v[202:205], v[76:79]
	v_mfma_f32_16x16x32_bf16 v[68:71], v[170:173], v[202:205], v[68:71]
	s_add_u32 s66, s24, s63
	s_addc_u32 s67, s25, 0
	s_add_u32 s28, s66, 0x80
	s_addc_u32 s29, s67, 0
	s_mov_b32 m0, s49
	s_nop 0
	global_load_lds_dwordx4 v139, s[28:29]
	s_mov_b32 m0, s53
	s_nop 0
	global_load_lds_dwordx4 v152, s[28:29]
	s_waitcnt lgkmcnt(1)
	v_mfma_f32_16x16x32_bf16 v[128:131], v[206:209], v[174:177], v[128:131]
	s_waitcnt lgkmcnt(0)
	v_mfma_f32_16x16x32_bf16 v[120:123], v[214:217], v[174:177], v[120:123]
	v_mfma_f32_16x16x32_bf16 v[112:115], v[206:209], v[182:185], v[112:115]
	v_mfma_f32_16x16x32_bf16 v[104:107], v[214:217], v[182:185], v[104:107]
	ds_read_b128 v[210:213], v133 offset:1024
	v_mfma_f32_16x16x32_bf16 v[96:99], v[206:209], v[190:193], v[96:99]
	ds_read_b128 v[218:221], v133 offset:3072
	v_mfma_f32_16x16x32_bf16 v[88:91], v[214:217], v[190:193], v[88:91]
	v_mfma_f32_16x16x32_bf16 v[80:83], v[206:209], v[198:201], v[80:83]
	v_mfma_f32_16x16x32_bf16 v[72:75], v[214:217], v[198:201], v[72:75]
	s_waitcnt lgkmcnt(1)
	v_mfma_f32_16x16x32_bf16 v[128:131], v[210:213], v[178:181], v[128:131]
	s_waitcnt lgkmcnt(0)
	v_mfma_f32_16x16x32_bf16 v[120:123], v[218:221], v[178:181], v[120:123]
	v_mfma_f32_16x16x32_bf16 v[112:115], v[210:213], v[186:189], v[112:115]
	v_mfma_f32_16x16x32_bf16 v[104:107], v[218:221], v[186:189], v[104:107]
	v_mfma_f32_16x16x32_bf16 v[96:99], v[210:213], v[194:197], v[96:99]
	v_mfma_f32_16x16x32_bf16 v[88:91], v[218:221], v[194:197], v[88:91]
	v_mfma_f32_16x16x32_bf16 v[80:83], v[210:213], v[202:205], v[80:83]
	v_mfma_f32_16x16x32_bf16 v[72:75], v[218:221], v[202:205], v[72:75]
	s_waitcnt vmcnt(4) lgkmcnt(0)
	s_barrier
	ds_read_b128 v[174:177], v156 offset:16384
	ds_read_b128 v[182:185], v156 offset:18432
	ds_read_b128 v[190:193], v156 offset:20480
	s_add_u32 s28, s64, 0x80080
	s_addc_u32 s29, s65, 0
	s_mov_b32 m0, s50
	s_nop 0
	global_load_lds_dwordx4 v140, s[28:29]
	s_mov_b32 m0, s54
	s_nop 0
	global_load_lds_dwordx4 v153, s[28:29]
	s_waitcnt lgkmcnt(2)
	v_mfma_f32_16x16x32_bf16 v[60:63], v[142:145], v[174:177], v[60:63]
	v_mfma_f32_16x16x32_bf16 v[52:55], v[158:161], v[174:177], v[52:55]
	ds_read_b128 v[198:201], v156 offset:22528
	s_waitcnt lgkmcnt(2)
	v_mfma_f32_16x16x32_bf16 v[44:47], v[142:145], v[182:185], v[44:47]
	v_mfma_f32_16x16x32_bf16 v[36:39], v[158:161], v[182:185], v[36:39]
	ds_read_b128 v[178:181], v156 offset:17408
	s_waitcnt lgkmcnt(2)
	v_mfma_f32_16x16x32_bf16 v[28:31], v[142:145], v[190:193], v[28:31]
	v_mfma_f32_16x16x32_bf16 v[20:23], v[158:161], v[190:193], v[20:23]
	ds_read_b128 v[186:189], v156 offset:19456
	s_waitcnt lgkmcnt(2)
	v_mfma_f32_16x16x32_bf16 v[8:11], v[142:145], v[198:201], v[8:11]
	v_mfma_f32_16x16x32_bf16 v[4:7], v[158:161], v[198:201], v[4:7]
	ds_read_b128 v[194:197], v156 offset:21504
	s_waitcnt lgkmcnt(2)
	v_mfma_f32_16x16x32_bf16 v[60:63], v[146:149], v[178:181], v[60:63]
	v_mfma_f32_16x16x32_bf16 v[52:55], v[170:173], v[178:181], v[52:55]
	ds_read_b128 v[202:205], v156 offset:23552
	s_waitcnt lgkmcnt(2)
	v_mfma_f32_16x16x32_bf16 v[44:47], v[146:149], v[186:189], v[44:47]
	v_mfma_f32_16x16x32_bf16 v[36:39], v[170:173], v[186:189], v[36:39]
	s_waitcnt lgkmcnt(1)
	v_mfma_f32_16x16x32_bf16 v[28:31], v[146:149], v[194:197], v[28:31]
	v_mfma_f32_16x16x32_bf16 v[20:23], v[170:173], v[194:197], v[20:23]
	s_waitcnt lgkmcnt(0)
	v_mfma_f32_16x16x32_bf16 v[8:11], v[146:149], v[202:205], v[8:11]
	v_mfma_f32_16x16x32_bf16 v[4:7], v[170:173], v[202:205], v[4:7]
	s_add_u32 s28, s66, 0x80080
	s_addc_u32 s29, s67, 0
	s_mov_b32 m0, s51
	s_nop 0
	global_load_lds_dwordx4 v139, s[28:29]
	s_mov_b32 m0, s55
	s_nop 0
	global_load_lds_dwordx4 v152, s[28:29]
	v_mfma_f32_16x16x32_bf16 v[64:67], v[206:209], v[174:177], v[64:67]
	s_add_u32 s28, s66, 0x100
	s_addc_u32 s29, s67, 0
	s_add_u32 s64, s64, 0x100
	v_mfma_f32_16x16x32_bf16 v[56:59], v[214:217], v[174:177], v[56:59]
	s_addc_u32 s65, s65, 0
	v_mfma_f32_16x16x32_bf16 v[48:51], v[206:209], v[182:185], v[48:51]
	v_mfma_f32_16x16x32_bf16 v[40:43], v[214:217], v[182:185], v[40:43]
	v_mfma_f32_16x16x32_bf16 v[32:35], v[206:209], v[190:193], v[32:35]
	v_mfma_f32_16x16x32_bf16 v[24:27], v[214:217], v[190:193], v[24:27]
	v_mfma_f32_16x16x32_bf16 v[16:19], v[206:209], v[198:201], v[16:19]
	v_mfma_f32_16x16x32_bf16 v[12:15], v[214:217], v[198:201], v[12:15]
	v_mfma_f32_16x16x32_bf16 v[64:67], v[210:213], v[178:181], v[64:67]
	v_mfma_f32_16x16x32_bf16 v[56:59], v[218:221], v[178:181], v[56:59]
	v_mfma_f32_16x16x32_bf16 v[48:51], v[210:213], v[186:189], v[48:51]
	v_mfma_f32_16x16x32_bf16 v[40:43], v[218:221], v[186:189], v[40:43]
	v_mfma_f32_16x16x32_bf16 v[32:35], v[210:213], v[194:197], v[32:35]
	v_mfma_f32_16x16x32_bf16 v[24:27], v[218:221], v[194:197], v[24:27]
	v_mfma_f32_16x16x32_bf16 v[16:19], v[210:213], v[202:205], v[16:19]
	v_mfma_f32_16x16x32_bf16 v[12:15], v[218:221], v[202:205], v[12:15]
	s_waitcnt vmcnt(2) lgkmcnt(0)
	s_barrier
; template <class Epi, class Sched>
; __device__ __forceinline__ void gemm_simple(PG8_LAS unsigned char* lds, const Gemm g, const Sched& S, const Epi& E, int wave_s) {
;     ...
;             const char* a2 = last ? nA : cA + (size_t)(t + 2) * kstep; const char* b2 = last ? nB : cB + (size_t)(t + 2) * kstep;
;             PG8_TILE(1, a2, b2, (!last || has_next));
	ds_read_b128 v[142:145], v134
	ds_read_b128 v[174:177], v156 offset:32768
	ds_read_b128 v[158:161], v134 offset:2048
	ds_read_b128 v[182:185], v156 offset:34816
	ds_read_b128 v[190:193], v156 offset:36864
	s_cmp_eq_u32 s63, s26
	s_cselect_b32 s29, s17, s29
	s_cselect_b32 s28, s60, s28
	s_cselect_b32 s65, s5, s65
	s_cselect_b32 s64, s61, s64
	s_mov_b32 m0, s35
	s_nop 0
	global_load_lds_dwordx4 v140, s[64:65]
	s_mov_b32 m0, s39
	s_nop 0
	global_load_lds_dwordx4 v153, s[64:65]
	s_waitcnt lgkmcnt(3)
	v_mfma_f32_16x16x32_bf16 v[124:127], v[142:145], v[174:177], v[124:127]
	s_waitcnt lgkmcnt(2)
	v_mfma_f32_16x16x32_bf16 v[116:119], v[158:161], v[174:177], v[116:119]
	ds_read_b128 v[198:201], v156 offset:38912
	s_waitcnt lgkmcnt(2)
	v_mfma_f32_16x16x32_bf16 v[108:111], v[142:145], v[182:185], v[108:111]
	v_mfma_f32_16x16x32_bf16 v[100:103], v[158:161], v[182:185], v[100:103]
	ds_read_b128 v[146:149], v134 offset:1024
	ds_read_b128 v[178:181], v156 offset:33792
	s_waitcnt lgkmcnt(3)
	v_mfma_f32_16x16x32_bf16 v[92:95], v[142:145], v[190:193], v[92:95]
	ds_read_b128 v[170:173], v134 offset:3072
	v_mfma_f32_16x16x32_bf16 v[84:87], v[158:161], v[190:193], v[84:87]
	ds_read_b128 v[186:189], v156 offset:35840
	s_waitcnt lgkmcnt(4)
	v_mfma_f32_16x16x32_bf16 v[76:79], v[142:145], v[198:201], v[76:79]
	v_mfma_f32_16x16x32_bf16 v[68:71], v[158:161], v[198:201], v[68:71]
	ds_read_b128 v[194:197], v156 offset:37888
	s_waitcnt lgkmcnt(3)
	v_mfma_f32_16x16x32_bf16 v[124:127], v[146:149], v[178:181], v[124:127]
	s_waitcnt lgkmcnt(2)
	v_mfma_f32_16x16x32_bf16 v[116:119], v[170:173], v[178:181], v[116:119]
	ds_read_b128 v[202:205], v156 offset:39936
	s_waitcnt lgkmcnt(2)
	v_mfma_f32_16x16x32_bf16 v[108:111], v[146:149], v[186:189], v[108:111]
	v_mfma_f32_16x16x32_bf16 v[100:103], v[170:173], v[186:189], v[100:103]
	ds_read_b128 v[206:209], v135
	s_waitcnt lgkmcnt(2)
	v_mfma_f32_16x16x32_bf16 v[92:95], v[146:149], v[194:197], v[92:95]
	ds_read_b128 v[214:217], v135 offset:2048
	v_mfma_f32_16x16x32_bf16 v[84:87], v[170:173], v[194:197], v[84:87]
	s_waitcnt lgkmcnt(2)
	v_mfma_f32_16x16x32_bf16 v[76:79], v[146:149], v[202:205], v[76:79]
	v_mfma_f32_16x16x32_bf16 v[68:71], v[170:173], v[202:205], v[68:71]
	s_mov_b32 m0, s23
	s_nop 0
	global_load_lds_dwordx4 v139, s[28:29]
	s_mov_b32 m0, s40
	s_nop 0
	global_load_lds_dwordx4 v152, s[28:29]
	s_waitcnt lgkmcnt(1)
	v_mfma_f32_16x16x32_bf16 v[128:131], v[206:209], v[174:177], v[128:131]
	s_waitcnt lgkmcnt(0)
	v_mfma_f32_16x16x32_bf16 v[120:123], v[214:217], v[174:177], v[120:123]
	v_mfma_f32_16x16x32_bf16 v[112:115], v[206:209], v[182:185], v[112:115]
	v_mfma_f32_16x16x32_bf16 v[104:107], v[214:217], v[182:185], v[104:107]
	ds_read_b128 v[210:213], v135 offset:1024
	v_mfma_f32_16x16x32_bf16 v[96:99], v[206:209], v[190:193], v[96:99]
	ds_read_b128 v[218:221], v135 offset:3072
	v_mfma_f32_16x16x32_bf16 v[88:91], v[214:217], v[190:193], v[88:91]
	v_mfma_f32_16x16x32_bf16 v[80:83], v[206:209], v[198:201], v[80:83]
	v_mfma_f32_16x16x32_bf16 v[72:75], v[214:217], v[198:201], v[72:75]
	s_waitcnt lgkmcnt(1)
	v_mfma_f32_16x16x32_bf16 v[128:131], v[210:213], v[178:181], v[128:131]
	s_waitcnt lgkmcnt(0)
	v_mfma_f32_16x16x32_bf16 v[120:123], v[218:221], v[178:181], v[120:123]
	v_mfma_f32_16x16x32_bf16 v[112:115], v[210:213], v[186:189], v[112:115]
	v_mfma_f32_16x16x32_bf16 v[104:107], v[218:221], v[186:189], v[104:107]
	v_mfma_f32_16x16x32_bf16 v[96:99], v[210:213], v[194:197], v[96:99]
	v_mfma_f32_16x16x32_bf16 v[88:91], v[218:221], v[194:197], v[88:91]
	v_mfma_f32_16x16x32_bf16 v[80:83], v[210:213], v[202:205], v[80:83]
	v_mfma_f32_16x16x32_bf16 v[72:75], v[218:221], v[202:205], v[72:75]
	s_waitcnt vmcnt(4) lgkmcnt(0)
	s_barrier
; #define LAS __attribute__((address_space(3)))
; __device__ __forceinline__ void rstd_table(const float* ssq, LAS unsigned char* lds, const Unit& u, int tid, int par) {
;     if (tid < 256) { const f32x4* p = (const f32x4*)(ssq + (size_t)(u.pm * 256 + tid) * 32); f32x4 a = p[0];
; #pragma unroll
;         for (int i = 1; i < 8; ++i) a += p[i];
;         ((LAS float*)(lds + 131072 + par * 1024))[tid] = 1.0f / sqrtf(((a[0] + a[1]) + (a[2] + a[3])) * (1.0f / DM) + 1e-6f); }
	ds_read_b128 v[174:177], v156 offset:49152
	ds_read_b128 v[182:185], v156 offset:51200
	ds_read_b128 v[190:193], v156 offset:53248
	s_add_u32 s64, s64, 0x80000
	s_addc_u32 s65, s65, 0
	s_mov_b32 m0, s41
	s_nop 0
	global_load_lds_dwordx4 v140, s[64:65]
	s_mov_b32 m0, s42
	s_nop 0
	global_load_lds_dwordx4 v153, s[64:65]
	s_waitcnt lgkmcnt(2)
	v_mfma_f32_16x16x32_bf16 v[60:63], v[142:145], v[174:177], v[60:63]
	v_mfma_f32_16x16x32_bf16 v[52:55], v[158:161], v[174:177], v[52:55]
	ds_read_b128 v[198:201], v156 offset:55296
	s_waitcnt lgkmcnt(2)
	v_mfma_f32_16x16x32_bf16 v[44:47], v[142:145], v[182:185], v[44:47]
	v_mfma_f32_16x16x32_bf16 v[36:39], v[158:161], v[182:185], v[36:39]
	ds_read_b128 v[178:181], v156 offset:50176
	s_waitcnt lgkmcnt(2)
	v_mfma_f32_16x16x32_bf16 v[28:31], v[142:145], v[190:193], v[28:31]
	v_mfma_f32_16x16x32_bf16 v[20:23], v[158:161], v[190:193], v[20:23]
	ds_read_b128 v[186:189], v156 offset:52224
	s_waitcnt lgkmcnt(2)
	v_mfma_f32_16x16x32_bf16 v[8:11], v[142:145], v[198:201], v[8:11]
	v_mfma_f32_16x16x32_bf16 v[4:7], v[158:161], v[198:201], v[4:7]
	ds_read_b128 v[194:197], v156 offset:54272
	s_waitcnt lgkmcnt(2)
	v_mfma_f32_16x16x32_bf16 v[60:63], v[146:149], v[178:181], v[60:63]
	v_mfma_f32_16x16x32_bf16 v[52:55], v[170:173], v[178:181], v[52:55]
	ds_read_b128 v[202:205], v156 offset:56320
	s_waitcnt lgkmcnt(2)
	v_mfma_f32_16x16x32_bf16 v[44:47], v[146:149], v[186:189], v[44:47]
	v_mfma_f32_16x16x32_bf16 v[36:39], v[170:173], v[186:189], v[36:39]
	s_waitcnt lgkmcnt(1)
	v_mfma_f32_16x16x32_bf16 v[28:31], v[146:149], v[194:197], v[28:31]
	v_mfma_f32_16x16x32_bf16 v[20:23], v[170:173], v[194:197], v[20:23]
	s_waitcnt lgkmcnt(0)
	v_mfma_f32_16x16x32_bf16 v[8:11], v[146:149], v[202:205], v[8:11]
	v_mfma_f32_16x16x32_bf16 v[4:7], v[170:173], v[202:205], v[4:7]
	s_add_u32 s28, s28, 0x80000
	s_addc_u32 s29, s29, 0
	s_mov_b32 m0, s43
	s_nop 0
	global_load_lds_dwordx4 v139, s[28:29]
	s_mov_b32 m0, s44
	s_nop 0
	global_load_lds_dwordx4 v152, s[28:29]
	v_mfma_f32_16x16x32_bf16 v[64:67], v[206:209], v[174:177], v[64:67]
	s_add_i32 s62, s62, 2
	s_add_u32 s26, s26, 0xffffff00
	s_addc_u32 s27, s27, -1
	v_mfma_f32_16x16x32_bf16 v[56:59], v[214:217], v[174:177], v[56:59]
	s_add_u32 s24, s24, 0x100
	s_addc_u32 s25, s25, 0
	s_add_u32 s10, s10, 0x100
	v_mfma_f32_16x16x32_bf16 v[48:51], v[206:209], v[182:185], v[48:51]
	s_addc_u32 s11, s11, 0
	s_cmp_lt_u32 s62, 30
	v_mfma_f32_16x16x32_bf16 v[40:43], v[214:217], v[182:185], v[40:43]
	v_mfma_f32_16x16x32_bf16 v[32:35], v[206:209], v[190:193], v[32:35]
	v_mfma_f32_16x16x32_bf16 v[24:27], v[214:217], v[190:193], v[24:27]
	v_mfma_f32_16x16x32_bf16 v[16:19], v[206:209], v[198:201], v[16:19]
	v_mfma_f32_16x16x32_bf16 v[12:15], v[214:217], v[198:201], v[12:15]
	v_mfma_f32_16x16x32_bf16 v[64:67], v[210:213], v[178:181], v[64:67]
	v_mfma_f32_16x16x32_bf16 v[56:59], v[218:221], v[178:181], v[56:59]
	v_mfma_f32_16x16x32_bf16 v[48:51], v[210:213], v[186:189], v[48:51]
	v_mfma_f32_16x16x32_bf16 v[40:43], v[218:221], v[186:189], v[40:43]
	v_mfma_f32_16x16x32_bf16 v[32:35], v[210:213], v[194:197], v[32:35]
	v_mfma_f32_16x16x32_bf16 v[24:27], v[218:221], v[194:197], v[24:27]
	v_mfma_f32_16x16x32_bf16 v[16:19], v[210:213], v[202:205], v[16:19]
	v_mfma_f32_16x16x32_bf16 v[12:15], v[218:221], v[202:205], v[12:15]
	s_cbranch_scc1 .LBB0_95
	s_nor_b64 s[10:11], s[6:7], s[8:9]
	s_and_saveexec_b64 s[24:25], s[10:11]
	s_cbranch_execz .LBB0_89
	v_lshl_add_u32 v132, s16, 8, v138
	v_ashrrev_i32_e32 v133, 31, v132
	v_lshlrev_b64 v[132:133], 7, v[132:133]
	v_lshl_add_u64 v[136:137], s[0:1], 0, v[132:133]
	global_load_dwordx4 v[132:135], v[136:137], off offset:48
	global_load_dwordx4 v[142:145], v[136:137], off offset:32
	global_load_dwordx4 v[146:149], v[136:137], off
	global_load_dwordx4 v[158:161], v[136:137], off offset:16
	s_lshl_b32 s5, s57, 10
	s_and_b32 s5, s5, 0x400
	s_waitcnt vmcnt(0)
	v_pk_add_f32 v[148:149], v[148:149], v[160:161]
	v_pk_add_f32 v[146:147], v[146:147], v[158:159]
	v_pk_add_f32 v[144:145], v[148:149], v[144:145]
	v_pk_add_f32 v[142:143], v[146:147], v[142:143]
	v_pk_add_f32 v[162:163], v[144:145], v[134:135]
	v_pk_add_f32 v[170:171], v[142:143], v[132:133]
	global_load_dwordx4 v[132:135], v[136:137], off offset:112
	global_load_dwordx4 v[142:145], v[136:137], off offset:96
	global_load_dwordx4 v[146:149], v[136:137], off offset:80
	global_load_dwordx4 v[158:161], v[136:137], off offset:64
	s_waitcnt vmcnt(0)
	v_pk_add_f32 v[136:137], v[162:163], v[160:161]
	v_pk_add_f32 v[158:159], v[170:171], v[158:159]
	v_pk_add_f32 v[136:137], v[136:137], v[148:149]
	v_pk_add_f32 v[146:147], v[158:159], v[146:147]
	v_pk_add_f32 v[136:137], v[136:137], v[144:145]
	v_pk_add_f32 v[142:143], v[146:147], v[142:143]
	v_pk_add_f32 v[134:135], v[136:137], v[134:135]
	v_pk_add_f32 v[132:133], v[142:143], v[132:133]
	s_nop 0
	v_pk_mov_b32 v[136:137], v[132:133], v[134:135] op_sel:[1,0]
	v_mov_b32_e32 v133, v135
	v_pk_add_f32 v[132:133], v[136:137], v[132:133]
	s_nop 0
	v_add_f32_e32 v132, v132, v133
	v_fmamk_f32 v132, v132, 0x3a000000, v164
	v_cmp_gt_f32_e32 vcc, s69, v132
	v_mul_f32_e32 v133, 0x4f800000, v132
	s_nop 0
	v_cndmask_b32_e32 v132, v132, v133, vcc
	v_sqrt_f32_e32 v133, v132
	s_nop 0
	v_add_u32_e32 v134, -1, v133
	v_fma_f32 v135, -v134, v133, v132
	v_cmp_ge_f32_e64 s[10:11], 0, v135
	v_add_u32_e32 v135, 1, v133
	s_nop 0
	v_cndmask_b32_e64 v134, v133, v134, s[10:11]
	v_fma_f32 v133, -v135, v133, v132
	v_cmp_lt_f32_e64 s[10:11], 0, v133
	s_nop 1
	v_cndmask_b32_e64 v133, v134, v135, s[10:11]
	v_mul_f32_e32 v134, 0x37800000, v133
	v_cndmask_b32_e32 v133, v133, v134, vcc
	v_cmp_class_f32_e32 vcc, v132, v165
	s_nop 1
	v_cndmask_b32_e32 v132, v133, v132, vcc
	v_div_scale_f32 v133, s[10:11], v132, v132, 1.0
	v_rcp_f32_e32 v134, v133
	s_nop 0
	v_fma_f32 v135, -v133, v134, 1.0
	v_fmac_f32_e32 v134, v135, v134
	v_div_scale_f32 v135, vcc, 1.0, v132, 1.0
	v_mul_f32_e32 v136, v135, v134
	v_fma_f32 v137, -v133, v136, v135
	v_fmac_f32_e32 v136, v137, v134
	v_fma_f32 v133, -v133, v136, v135
	v_div_fmas_f32 v133, v133, v134, v136
	v_div_fixup_f32 v132, v133, v132, 1.0
	v_add_u32_e32 v133, s5, v154
	ds_write_b32 v133, v132
	s_branch .LBB0_89

; template <class Epi, class Sched>
; __device__ __forceinline__ void gemm_simple(PG8_LAS unsigned char* lds, const Gemm g, const Sched& S, const Epi& E, int wave_s) {
;     ...
;         for (; t < nt; t += 2) {
;             const bool last = (t == nt - 2);
;             PG8_TILE(0, cA + (size_t)(t + 1) * kstep, cB + (size_t)(t + 1) * kstep, true);
;             const char* a2 = last ? nA : cA + (size_t)(t + 2) * kstep; const char* b2 = last ? nB : cB + (size_t)(t + 2) * kstep;
;             PG8_TILE(1, a2, b2, (!last || has_next));
.LBB0_119:
	s_waitcnt vmcnt(2) lgkmcnt(0)
	s_barrier
	ds_read_b128 v[146:149], v132
	ds_read_b128 v[174:177], v154
	ds_read_b128 v[160:163], v132 offset:2048
	ds_read_b128 v[182:185], v154 offset:2048
	ds_read_b128 v[190:193], v154 offset:4096
	s_add_u32 s26, s69, s58
	s_addc_u32 s27, s70, 0
	s_mov_b32 m0, s47
	s_nop 0
	global_load_lds_dwordx4 v139, s[26:27]
	s_mov_b32 m0, s51
	s_nop 0
	global_load_lds_dwordx4 v152, s[26:27]
	s_waitcnt lgkmcnt(3)
	v_mfma_f32_16x16x32_bf16 v[128:131], v[146:149], v[174:177], v[128:131]
	s_waitcnt lgkmcnt(2)
	v_mfma_f32_16x16x32_bf16 v[124:127], v[160:163], v[174:177], v[124:127]
	ds_read_b128 v[198:201], v154 offset:6144
	s_waitcnt lgkmcnt(2)
	v_mfma_f32_16x16x32_bf16 v[112:115], v[146:149], v[182:185], v[112:115]
	v_mfma_f32_16x16x32_bf16 v[108:111], v[160:163], v[182:185], v[108:111]
	ds_read_b128 v[156:159], v132 offset:1024
	ds_read_b128 v[178:181], v154 offset:1024
	s_waitcnt lgkmcnt(3)
	v_mfma_f32_16x16x32_bf16 v[96:99], v[146:149], v[190:193], v[96:99]
	ds_read_b128 v[170:173], v132 offset:3072
	v_mfma_f32_16x16x32_bf16 v[92:95], v[160:163], v[190:193], v[92:95]
	ds_read_b128 v[186:189], v154 offset:3072
	s_waitcnt lgkmcnt(4)
	v_mfma_f32_16x16x32_bf16 v[80:83], v[146:149], v[198:201], v[80:83]
	v_mfma_f32_16x16x32_bf16 v[76:79], v[160:163], v[198:201], v[76:79]
	ds_read_b128 v[194:197], v154 offset:5120
	s_waitcnt lgkmcnt(3)
	v_mfma_f32_16x16x32_bf16 v[128:131], v[156:159], v[178:181], v[128:131]
	s_waitcnt lgkmcnt(2)
	v_mfma_f32_16x16x32_bf16 v[124:127], v[170:173], v[178:181], v[124:127]
	ds_read_b128 v[202:205], v154 offset:7168
	s_waitcnt lgkmcnt(2)
	v_mfma_f32_16x16x32_bf16 v[112:115], v[156:159], v[186:189], v[112:115]
	v_mfma_f32_16x16x32_bf16 v[108:111], v[170:173], v[186:189], v[108:111]
	ds_read_b128 v[206:209], v133
	s_waitcnt lgkmcnt(2)
	v_mfma_f32_16x16x32_bf16 v[96:99], v[156:159], v[194:197], v[96:99]
	ds_read_b128 v[214:217], v133 offset:2048
	v_mfma_f32_16x16x32_bf16 v[92:95], v[170:173], v[194:197], v[92:95]
	s_waitcnt lgkmcnt(2)
	v_mfma_f32_16x16x32_bf16 v[80:83], v[156:159], v[202:205], v[80:83]
	v_mfma_f32_16x16x32_bf16 v[76:79], v[170:173], v[202:205], v[76:79]
	s_add_u32 s26, s67, s58
	s_addc_u32 s27, s68, 0
	s_mov_b32 m0, s48
	s_nop 0
	global_load_lds_dwordx4 v138, s[26:27]
	s_mov_b32 m0, s52
	s_nop 0
	global_load_lds_dwordx4 v140, s[26:27]
	s_waitcnt lgkmcnt(1)
	v_mfma_f32_16x16x32_bf16 v[120:123], v[206:209], v[174:177], v[120:123]
	s_waitcnt lgkmcnt(0)
	v_mfma_f32_16x16x32_bf16 v[116:119], v[214:217], v[174:177], v[116:119]
	v_mfma_f32_16x16x32_bf16 v[104:107], v[206:209], v[182:185], v[104:107]
	v_mfma_f32_16x16x32_bf16 v[100:103], v[214:217], v[182:185], v[100:103]
	ds_read_b128 v[210:213], v133 offset:1024
	v_mfma_f32_16x16x32_bf16 v[88:91], v[206:209], v[190:193], v[88:91]
	ds_read_b128 v[218:221], v133 offset:3072
	v_mfma_f32_16x16x32_bf16 v[84:87], v[214:217], v[190:193], v[84:87]
	v_mfma_f32_16x16x32_bf16 v[72:75], v[206:209], v[198:201], v[72:75]
	v_mfma_f32_16x16x32_bf16 v[68:71], v[214:217], v[198:201], v[68:71]
	s_waitcnt lgkmcnt(1)
	v_mfma_f32_16x16x32_bf16 v[120:123], v[210:213], v[178:181], v[120:123]
	s_waitcnt lgkmcnt(0)
	v_mfma_f32_16x16x32_bf16 v[116:119], v[218:221], v[178:181], v[116:119]
	v_mfma_f32_16x16x32_bf16 v[104:107], v[210:213], v[186:189], v[104:107]
	v_mfma_f32_16x16x32_bf16 v[100:103], v[218:221], v[186:189], v[100:103]
	v_mfma_f32_16x16x32_bf16 v[88:91], v[210:213], v[194:197], v[88:91]
	v_mfma_f32_16x16x32_bf16 v[84:87], v[218:221], v[194:197], v[84:87]
	v_mfma_f32_16x16x32_bf16 v[72:75], v[210:213], v[202:205], v[72:75]
	v_mfma_f32_16x16x32_bf16 v[68:71], v[218:221], v[202:205], v[68:71]
	s_waitcnt vmcnt(4) lgkmcnt(0)
	s_barrier
	ds_read_b128 v[174:177], v154 offset:16384
	ds_read_b128 v[182:185], v154 offset:18432
	ds_read_b128 v[190:193], v154 offset:20480
	s_add_u32 s26, s65, s58
	s_addc_u32 s27, s66, 0
	s_mov_b32 m0, s49
	s_nop 0
	global_load_lds_dwordx4 v139, s[26:27]
	s_mov_b32 m0, s53
	s_nop 0
	global_load_lds_dwordx4 v152, s[26:27]
	s_waitcnt lgkmcnt(2)
	v_mfma_f32_16x16x32_bf16 v[64:67], v[146:149], v[174:177], v[64:67]
	v_mfma_f32_16x16x32_bf16 v[60:63], v[160:163], v[174:177], v[60:63]
	ds_read_b128 v[198:201], v154 offset:22528
	s_waitcnt lgkmcnt(2)
	v_mfma_f32_16x16x32_bf16 v[48:51], v[146:149], v[182:185], v[48:51]
	v_mfma_f32_16x16x32_bf16 v[44:47], v[160:163], v[182:185], v[44:47]
	ds_read_b128 v[178:181], v154 offset:17408
	s_waitcnt lgkmcnt(2)
	v_mfma_f32_16x16x32_bf16 v[32:35], v[146:149], v[190:193], v[32:35]
	v_mfma_f32_16x16x32_bf16 v[28:31], v[160:163], v[190:193], v[28:31]
	ds_read_b128 v[186:189], v154 offset:19456
	s_waitcnt lgkmcnt(2)
	v_mfma_f32_16x16x32_bf16 v[16:19], v[146:149], v[198:201], v[16:19]
	v_mfma_f32_16x16x32_bf16 v[12:15], v[160:163], v[198:201], v[12:15]
	ds_read_b128 v[194:197], v154 offset:21504
	s_waitcnt lgkmcnt(2)
	v_mfma_f32_16x16x32_bf16 v[64:67], v[156:159], v[178:181], v[64:67]
	v_mfma_f32_16x16x32_bf16 v[60:63], v[170:173], v[178:181], v[60:63]
	ds_read_b128 v[202:205], v154 offset:23552
	s_waitcnt lgkmcnt(2)
	v_mfma_f32_16x16x32_bf16 v[48:51], v[156:159], v[186:189], v[48:51]
	v_mfma_f32_16x16x32_bf16 v[44:47], v[170:173], v[186:189], v[44:47]
	s_waitcnt lgkmcnt(1)
	v_mfma_f32_16x16x32_bf16 v[32:35], v[156:159], v[194:197], v[32:35]
	v_mfma_f32_16x16x32_bf16 v[28:31], v[170:173], v[194:197], v[28:31]
	s_waitcnt lgkmcnt(0)
	v_mfma_f32_16x16x32_bf16 v[16:19], v[156:159], v[202:205], v[16:19]
	v_mfma_f32_16x16x32_bf16 v[12:15], v[170:173], v[202:205], v[12:15]
	s_add_u32 s26, s63, s58
	s_addc_u32 s27, s64, 0
	s_mov_b32 m0, s50
	s_nop 0
	global_load_lds_dwordx4 v138, s[26:27]
	s_mov_b32 m0, s54
	s_nop 0
	global_load_lds_dwordx4 v140, s[26:27]
	v_mfma_f32_16x16x32_bf16 v[56:59], v[206:209], v[174:177], v[56:59]
	s_add_u32 s26, s61, s58
	s_addc_u32 s27, s62, 0
	s_add_u32 s71, s59, s58
	v_mfma_f32_16x16x32_bf16 v[52:55], v[214:217], v[174:177], v[52:55]
	s_addc_u32 s72, s60, 0
	v_mfma_f32_16x16x32_bf16 v[40:43], v[206:209], v[182:185], v[40:43]
	v_mfma_f32_16x16x32_bf16 v[36:39], v[214:217], v[182:185], v[36:39]
	v_mfma_f32_16x16x32_bf16 v[24:27], v[206:209], v[190:193], v[24:27]
	v_mfma_f32_16x16x32_bf16 v[20:23], v[214:217], v[190:193], v[20:23]
	v_mfma_f32_16x16x32_bf16 v[8:11], v[206:209], v[198:201], v[8:11]
	v_mfma_f32_16x16x32_bf16 v[4:7], v[214:217], v[198:201], v[4:7]
	v_mfma_f32_16x16x32_bf16 v[56:59], v[210:213], v[178:181], v[56:59]
	v_mfma_f32_16x16x32_bf16 v[52:55], v[218:221], v[178:181], v[52:55]
	v_mfma_f32_16x16x32_bf16 v[40:43], v[210:213], v[186:189], v[40:43]
	v_mfma_f32_16x16x32_bf16 v[36:39], v[218:221], v[186:189], v[36:39]
	v_mfma_f32_16x16x32_bf16 v[24:27], v[210:213], v[194:197], v[24:27]
	v_mfma_f32_16x16x32_bf16 v[20:23], v[218:221], v[194:197], v[20:23]
	v_mfma_f32_16x16x32_bf16 v[8:11], v[210:213], v[202:205], v[8:11]
	v_mfma_f32_16x16x32_bf16 v[4:7], v[218:221], v[202:205], v[4:7]
	s_waitcnt vmcnt(2) lgkmcnt(0)
	s_barrier
; template <class Epi, class Sched>
; __device__ __forceinline__ void gemm_simple(PG8_LAS unsigned char* lds, const Gemm g, const Sched& S, const Epi& E, int wave_s) {
;     ...
;         for (; t < nt; t += 2) {
;             const bool last = (t == nt - 2);
;             PG8_TILE(0, cA + (size_t)(t + 1) * kstep, cB + (size_t)(t + 1) * kstep, true);
;             const char* a2 = last ? nA : cA + (size_t)(t + 2) * kstep; const char* b2 = last ? nB : cB + (size_t)(t + 2) * kstep;
;             PG8_TILE(1, a2, b2, (!last || has_next));
	ds_read_b128 v[146:149], v134
	ds_read_b128 v[174:177], v154 offset:32768
	ds_read_b128 v[160:163], v134 offset:2048
	ds_read_b128 v[182:185], v154 offset:34816
	ds_read_b128 v[190:193], v154 offset:36864
	s_cmp_eq_u32 s58, s24
	s_cselect_b32 s27, s11, s27
	s_cselect_b32 s26, s21, s26
	s_cselect_b32 s73, s5, s72
	s_cselect_b32 s72, s23, s71
	s_mov_b32 m0, s40
	s_nop 0
	global_load_lds_dwordx4 v139, s[72:73]
	s_mov_b32 m0, s41
	s_nop 0
	global_load_lds_dwordx4 v152, s[72:73]
	s_waitcnt lgkmcnt(3)
	v_mfma_f32_16x16x32_bf16 v[128:131], v[146:149], v[174:177], v[128:131]
	s_waitcnt lgkmcnt(2)
	v_mfma_f32_16x16x32_bf16 v[124:127], v[160:163], v[174:177], v[124:127]
	ds_read_b128 v[198:201], v154 offset:38912
	s_waitcnt lgkmcnt(2)
	v_mfma_f32_16x16x32_bf16 v[112:115], v[146:149], v[182:185], v[112:115]
	v_mfma_f32_16x16x32_bf16 v[108:111], v[160:163], v[182:185], v[108:111]
	ds_read_b128 v[156:159], v134 offset:1024
	ds_read_b128 v[178:181], v154 offset:33792
	s_waitcnt lgkmcnt(3)
	v_mfma_f32_16x16x32_bf16 v[96:99], v[146:149], v[190:193], v[96:99]
	ds_read_b128 v[170:173], v134 offset:3072
	v_mfma_f32_16x16x32_bf16 v[92:95], v[160:163], v[190:193], v[92:95]
	ds_read_b128 v[186:189], v154 offset:35840
	s_waitcnt lgkmcnt(4)
	v_mfma_f32_16x16x32_bf16 v[80:83], v[146:149], v[198:201], v[80:83]
	v_mfma_f32_16x16x32_bf16 v[76:79], v[160:163], v[198:201], v[76:79]
	ds_read_b128 v[194:197], v154 offset:37888
	s_waitcnt lgkmcnt(3)
	v_mfma_f32_16x16x32_bf16 v[128:131], v[156:159], v[178:181], v[128:131]
	s_waitcnt lgkmcnt(2)
	v_mfma_f32_16x16x32_bf16 v[124:127], v[170:173], v[178:181], v[124:127]
	ds_read_b128 v[202:205], v154 offset:39936
	s_waitcnt lgkmcnt(2)
	v_mfma_f32_16x16x32_bf16 v[112:115], v[156:159], v[186:189], v[112:115]
	v_mfma_f32_16x16x32_bf16 v[108:111], v[170:173], v[186:189], v[108:111]
	ds_read_b128 v[206:209], v135
	s_waitcnt lgkmcnt(2)
	v_mfma_f32_16x16x32_bf16 v[96:99], v[156:159], v[194:197], v[96:99]
	ds_read_b128 v[214:217], v135 offset:2048
	v_mfma_f32_16x16x32_bf16 v[92:95], v[170:173], v[194:197], v[92:95]
	s_waitcnt lgkmcnt(2)
	v_mfma_f32_16x16x32_bf16 v[80:83], v[156:159], v[202:205], v[80:83]
	v_mfma_f32_16x16x32_bf16 v[76:79], v[170:173], v[202:205], v[76:79]
	s_mov_b32 m0, s39
	s_nop 0
	global_load_lds_dwordx4 v138, s[26:27]
	s_mov_b32 m0, s42
	s_nop 0
	global_load_lds_dwordx4 v140, s[26:27]
	s_waitcnt lgkmcnt(1)
	v_mfma_f32_16x16x32_bf16 v[120:123], v[206:209], v[174:177], v[120:123]
	s_waitcnt lgkmcnt(0)
	v_mfma_f32_16x16x32_bf16 v[116:119], v[214:217], v[174:177], v[116:119]
	v_mfma_f32_16x16x32_bf16 v[104:107], v[206:209], v[182:185], v[104:107]
	v_mfma_f32_16x16x32_bf16 v[100:103], v[214:217], v[182:185], v[100:103]
	ds_read_b128 v[210:213], v135 offset:1024
	v_mfma_f32_16x16x32_bf16 v[88:91], v[206:209], v[190:193], v[88:91]
	ds_read_b128 v[218:221], v135 offset:3072
	v_mfma_f32_16x16x32_bf16 v[84:87], v[214:217], v[190:193], v[84:87]
	v_mfma_f32_16x16x32_bf16 v[72:75], v[206:209], v[198:201], v[72:75]
	v_mfma_f32_16x16x32_bf16 v[68:71], v[214:217], v[198:201], v[68:71]
	s_waitcnt lgkmcnt(1)
	v_mfma_f32_16x16x32_bf16 v[120:123], v[210:213], v[178:181], v[120:123]
	s_waitcnt lgkmcnt(0)
	v_mfma_f32_16x16x32_bf16 v[116:119], v[218:221], v[178:181], v[116:119]
	v_mfma_f32_16x16x32_bf16 v[104:107], v[210:213], v[186:189], v[104:107]
	v_mfma_f32_16x16x32_bf16 v[100:103], v[218:221], v[186:189], v[100:103]
	v_mfma_f32_16x16x32_bf16 v[88:91], v[210:213], v[194:197], v[88:91]
	v_mfma_f32_16x16x32_bf16 v[84:87], v[218:221], v[194:197], v[84:87]
	v_mfma_f32_16x16x32_bf16 v[72:75], v[210:213], v[202:205], v[72:75]
	v_mfma_f32_16x16x32_bf16 v[68:71], v[218:221], v[202:205], v[68:71]
	s_waitcnt vmcnt(4) lgkmcnt(0)
	s_barrier
	ds_read_b128 v[174:177], v154 offset:49152
	ds_read_b128 v[182:185], v154 offset:51200
	ds_read_b128 v[190:193], v154 offset:53248
	s_add_u32 s72, s72, 0x80000
	s_addc_u32 s73, s73, 0
	s_mov_b32 m0, s43
	s_nop 0
	global_load_lds_dwordx4 v139, s[72:73]
	s_mov_b32 m0, s44
	s_nop 0
	global_load_lds_dwordx4 v152, s[72:73]
	s_waitcnt lgkmcnt(2)
	v_mfma_f32_16x16x32_bf16 v[64:67], v[146:149], v[174:177], v[64:67]
	v_mfma_f32_16x16x32_bf16 v[60:63], v[160:163], v[174:177], v[60:63]
	ds_read_b128 v[198:201], v154 offset:55296
	s_waitcnt lgkmcnt(2)
	v_mfma_f32_16x16x32_bf16 v[48:51], v[146:149], v[182:185], v[48:51]
	v_mfma_f32_16x16x32_bf16 v[44:47], v[160:163], v[182:185], v[44:47]
	ds_read_b128 v[178:181], v154 offset:50176
	s_waitcnt lgkmcnt(2)
	v_mfma_f32_16x16x32_bf16 v[32:35], v[146:149], v[190:193], v[32:35]
	v_mfma_f32_16x16x32_bf16 v[28:31], v[160:163], v[190:193], v[28:31]
	ds_read_b128 v[186:189], v154 offset:52224
	s_waitcnt lgkmcnt(2)
	v_mfma_f32_16x16x32_bf16 v[16:19], v[146:149], v[198:201], v[16:19]
	v_mfma_f32_16x16x32_bf16 v[12:15], v[160:163], v[198:201], v[12:15]
	ds_read_b128 v[194:197], v154 offset:54272
	s_waitcnt lgkmcnt(2)
	v_mfma_f32_16x16x32_bf16 v[64:67], v[156:159], v[178:181], v[64:67]
	v_mfma_f32_16x16x32_bf16 v[60:63], v[170:173], v[178:181], v[60:63]
	ds_read_b128 v[202:205], v154 offset:56320
	s_waitcnt lgkmcnt(2)
	v_mfma_f32_16x16x32_bf16 v[48:51], v[156:159], v[186:189], v[48:51]
	v_mfma_f32_16x16x32_bf16 v[44:47], v[170:173], v[186:189], v[44:47]
	s_waitcnt lgkmcnt(1)
	v_mfma_f32_16x16x32_bf16 v[32:35], v[156:159], v[194:197], v[32:35]
	v_mfma_f32_16x16x32_bf16 v[28:31], v[170:173], v[194:197], v[28:31]
	s_waitcnt lgkmcnt(0)
; template <class Epi, class Sched>
; __device__ __forceinline__ void gemm_simple(PG8_LAS unsigned char* lds, const Gemm g, const Sched& S, const Epi& E, int wave_s) {
;     ...
;         for (; t < nt; t += 2) {
;             const bool last = (t == nt - 2);
;             PG8_TILE(0, cA + (size_t)(t + 1) * kstep, cB + (size_t)(t + 1) * kstep, true);
;             const char* a2 = last ? nA : cA + (size_t)(t + 2) * kstep; const char* b2 = last ? nB : cB + (size_t)(t + 2) * kstep;
;             PG8_TILE(1, a2, b2, (!last || has_next));
;     __device__ __forceinline__ void operator()(const f32x4 (&acc)[2][2][4][2], const Unit& u, int wr, int wc, int fr, int fq, const LAS float* rt) const {
;         const int row0 = u.pm * 256 + wr * 64 + fr, col0 = u.pn * 256 + wc * 32 + 8 * fq, lane = fq * 16 + fr;
; #pragma unroll
;         for (int ai = 0; ai < 2; ++ai)
; #pragma unroll
;             for (int m = 0; m < 4; ++m) { const size_t row = (size_t)(row0 + ai * 128 + m * 16); const float rs = (MODE == 1) ? rt[ai * 128 + wr * 64 + m * 16 + fr] : 1.0f; float ss = 0.f;
; #pragma unroll
;                 for (int bj = 0; bj < 2; ++bj) { const size_t o = row * DM + col0 + bj * 128; const u32x4 xv = *(const u32x4*)(xin + o);
;                     f32x4 v0 = acc[ai][bj][m][0], v1 = acc[ai][bj][m][1];
;                     if (MODE == 1) { const u32x4 p = *(const u32x4*)(pe + o);
;                         v0[0] = sigmoidf_(v0[0] * rs) * bflo(p.x); v0[1] = sigmoidf_(v0[1] * rs) * bfhi(p.x); v0[2] = sigmoidf_(v0[2] * rs) * bflo(p.y); v0[3] = sigmoidf_(v0[3] * rs) * bfhi(p.y);
;                         v1[0] = sigmoidf_(v1[0] * rs) * bflo(p.z); v1[1] = sigmoidf_(v1[1] * rs) * bfhi(p.z); v1[2] = sigmoidf_(v1[2] * rs) * bflo(p.w); v1[3] = sigmoidf_(v1[3] * rs) * bfhi(p.w); }
;                     v0[0] += bflo(xv.x); v0[1] += bfhi(xv.x); v0[2] += bflo(xv.y); v0[3] += bfhi(xv.y); v1[0] += bflo(xv.z); v1[1] += bfhi(xv.z); v1[2] += bflo(xv.w); v1[3] += bfhi(xv.w);
;                     ss += (v0[0] * v0[0] + v0[1] * v0[1]) + (v0[2] * v0[2] + v0[3] * v0[3]) + (v1[0] * v1[0] + v1[1] * v1[1]) + (v1[2] * v1[2] + v1[3] * v1[3]);
;                     u32x4 w; w.x = cvt_pk_bf16(v0[0], v0[1]); w.y = cvt_pk_bf16(v0[2], v0[3]); w.z = cvt_pk_bf16(v1[0], v1[1]); w.w = cvt_pk_bf16(v1[2], v1[3]);
;                     __builtin_nontemporal_store(w, (u32x4*)(xout + o)); }
	v_mfma_f32_16x16x32_bf16 v[16:19], v[156:159], v[202:205], v[16:19]
	v_mfma_f32_16x16x32_bf16 v[12:15], v[170:173], v[202:205], v[12:15]
	s_add_u32 s26, s26, 0x80000
	s_addc_u32 s27, s27, 0
	s_mov_b32 m0, s45
	s_nop 0
	global_load_lds_dwordx4 v138, s[26:27]
	s_mov_b32 m0, s46
	s_nop 0
	global_load_lds_dwordx4 v140, s[26:27]
	s_add_i32 s35, s35, 2
	s_add_u32 s24, s24, 0xffffff00
	s_addc_u32 s25, s25, -1
	s_add_u32 s59, s59, 0x100
	s_addc_u32 s60, s60, 0
	s_add_u32 s61, s61, 0x100
	s_addc_u32 s62, s62, 0
	s_add_u32 s63, s63, 0x100
	v_mfma_f32_16x16x32_bf16 v[56:59], v[206:209], v[174:177], v[56:59]
	s_addc_u32 s64, s64, 0
	s_add_u32 s65, s65, 0x100
	s_addc_u32 s66, s66, 0
	v_mfma_f32_16x16x32_bf16 v[52:55], v[214:217], v[174:177], v[52:55]
	s_add_u32 s67, s67, 0x100
	s_addc_u32 s68, s68, 0
	s_add_u32 s69, s69, 0x100
	v_mfma_f32_16x16x32_bf16 v[40:43], v[206:209], v[182:185], v[40:43]
	s_addc_u32 s70, s70, 0
	s_cmp_lt_u32 s35, 30
	v_mfma_f32_16x16x32_bf16 v[36:39], v[214:217], v[182:185], v[36:39]
	v_mfma_f32_16x16x32_bf16 v[24:27], v[206:209], v[190:193], v[24:27]
	v_mfma_f32_16x16x32_bf16 v[20:23], v[214:217], v[190:193], v[20:23]
	v_mfma_f32_16x16x32_bf16 v[8:11], v[206:209], v[198:201], v[8:11]
	v_mfma_f32_16x16x32_bf16 v[4:7], v[214:217], v[198:201], v[4:7]
	v_mfma_f32_16x16x32_bf16 v[56:59], v[210:213], v[178:181], v[56:59]
	v_mfma_f32_16x16x32_bf16 v[52:55], v[218:221], v[178:181], v[52:55]
	v_mfma_f32_16x16x32_bf16 v[40:43], v[210:213], v[186:189], v[40:43]
	v_mfma_f32_16x16x32_bf16 v[36:39], v[218:221], v[186:189], v[36:39]
	v_mfma_f32_16x16x32_bf16 v[24:27], v[210:213], v[194:197], v[24:27]
	v_mfma_f32_16x16x32_bf16 v[20:23], v[218:221], v[194:197], v[20:23]
	v_mfma_f32_16x16x32_bf16 v[8:11], v[210:213], v[202:205], v[8:11]
	v_mfma_f32_16x16x32_bf16 v[4:7], v[218:221], v[202:205], v[4:7]
	s_cbranch_scc1 .LBB0_119
	v_mov_b32_e32 v132, v141
	s_lshl_b32 s5, s22, 8
	v_mbcnt_lo_u32_b32 v132, -1, v132
	v_mbcnt_hi_u32_b32 v135, -1, v132
	v_and_b32_e32 v136, 15, v135
	s_add_i32 s5, s5, s37
	v_or_b32_e32 v134, s5, v136
	s_lshl_b32 s5, s20, 8
	v_ashrrev_i32_e32 v137, 4, v135
	s_or_b32 s5, s5, s38
	v_lshl_add_u32 v132, v137, 3, s5
	v_lshlrev_b32_e32 v137, 6, v137
	v_lshlrev_b32_e32 v136, 2, v136
	s_movk_i32 s5, 0x80
	v_cmp_gt_u32_e32 vcc, 16, v135
	v_ashrrev_i32_e32 v135, 31, v134
	v_bitop3_b32 v156, v137, 64, v136 bitop3:0x36
	v_bitop3_b32 v155, v137, s5, v136 bitop3:0x36
	v_lshlrev_b64 v[136:137], 12, v[134:135]
	v_ashrrev_i32_e32 v133, 31, v132
	v_lshl_add_u64 v[136:137], s[94:95], 0, v[136:137]
	v_lshl_add_u64 v[136:137], v[132:133], 1, v[136:137]
	v_lshlrev_b32_e32 v236, 12, v134
	v_lshl_add_u32 v236, v132, 1, v236
	global_load_dwordx4 v[172:175], v236, s[94:95]
	global_load_dwordx4 v[176:179], v236, s[94:95] offset:256
	v_add_u32_e32 v237, 0x10000, v236
	global_load_dwordx4 v[180:183], v237, s[94:95]
	global_load_dwordx4 v[184:187], v237, s[94:95] offset:256
	v_add_u32_e32 v237, 0x20000, v236
	global_load_dwordx4 v[188:191], v237, s[94:95]
	global_load_dwordx4 v[192:195], v237, s[94:95] offset:256
	v_add_u32_e32 v237, 0x30000, v236
	global_load_dwordx4 v[196:199], v237, s[94:95]
	global_load_dwordx4 v[200:203], v237, s[94:95] offset:256
	v_add_u32_e32 v237, 0x80000, v236
	global_load_dwordx4 v[204:207], v237, s[94:95]
	global_load_dwordx4 v[208:211], v237, s[94:95] offset:256
	v_add_u32_e32 v237, 0x90000, v236
	global_load_dwordx4 v[212:215], v237, s[94:95]
	global_load_dwordx4 v[216:219], v237, s[94:95] offset:256
	v_add_u32_e32 v237, 0xa0000, v236
	global_load_dwordx4 v[220:223], v237, s[94:95]
	global_load_dwordx4 v[224:227], v237, s[94:95] offset:256
	v_add_u32_e32 v237, 0xb0000, v236
	global_load_dwordx4 v[228:231], v237, s[94:95]
	global_load_dwordx4 v[232:235], v237, s[94:95] offset:256
	s_lshl_b32 s20, s20, 2
	s_ashr_i32 s21, s20, 31
	s_waitcnt vmcnt(15)
	s_nop 1
	v_mov_b64_e32 v[146:147], v[172:173]
	v_mov_b64_e32 v[148:149], v[174:175]
	v_lshlrev_b32_e32 v142, 16, v146
	v_add_f32_e32 v128, v128, v142
	v_and_b32_e32 v142, 0xffff0000, v146
	v_add_f32_e32 v129, v129, v142
	v_lshlrev_b32_e32 v142, 16, v147
	v_add_f32_e32 v130, v130, v142
	v_and_b32_e32 v142, 0xffff0000, v147
	v_add_f32_e32 v131, v131, v142
	v_lshlrev_b32_e32 v142, 16, v148
	v_add_f32_e32 v142, v124, v142
	v_and_b32_e32 v124, 0xffff0000, v148
	v_add_f32_e32 v143, v125, v124
	v_lshlrev_b32_e32 v124, 16, v149
	v_add_f32_e32 v144, v126, v124
	v_and_b32_e32 v124, 0xffff0000, v149
	v_add_f32_e32 v127, v127, v124
	v_mul_f32_e32 v124, v129, v129
	v_mul_f32_e32 v125, v131, v131
	v_fmac_f32_e32 v124, v128, v128
	v_fmac_f32_e32 v125, v130, v130
	v_add_f32_e32 v124, v124, v125
	v_mul_f32_e32 v125, v143, v143
	v_fmac_f32_e32 v125, v142, v142
	v_add_f32_e32 v124, v125, v124
	v_mul_f32_e32 v125, v127, v127
	v_fmac_f32_e32 v125, v144, v144
	v_add_f32_e32 v145, v125, v124
	v_cvt_pk_bf16_f32 v124, v128, v129
	v_cvt_pk_bf16_f32 v125, v130, v131
	v_cvt_pk_bf16_f32 v126, v142, v143
	v_cvt_pk_bf16_f32 v127, v144, v127
	global_store_dwordx4 v[136:137], v[124:127], off nt
	s_waitcnt vmcnt(15)
	s_nop 1
	v_mov_b64_e32 v[124:125], v[176:177]
	v_mov_b64_e32 v[126:127], v[178:179]
	v_lshlrev_b32_e32 v128, 16, v124
	v_and_b32_e32 v124, 0xffff0000, v124
	v_add_f32_e32 v121, v121, v124
	v_lshlrev_b32_e32 v124, 16, v125
	v_add_f32_e32 v122, v122, v124
	v_and_b32_e32 v124, 0xffff0000, v125
	v_add_f32_e32 v123, v123, v124
	v_lshlrev_b32_e32 v124, 16, v126
	v_add_f32_e32 v124, v116, v124
	v_and_b32_e32 v116, 0xffff0000, v126
	v_add_f32_e32 v125, v117, v116
	v_lshlrev_b32_e32 v116, 16, v127
	v_add_f32_e32 v126, v118, v116
	v_and_b32_e32 v116, 0xffff0000, v127
	v_add_f32_e32 v120, v120, v128
	v_add_f32_e32 v119, v119, v116
	v_mul_f32_e32 v116, v121, v121
	v_mul_f32_e32 v117, v123, v123
	v_fmac_f32_e32 v116, v120, v120
	v_fmac_f32_e32 v117, v122, v122
	v_add_f32_e32 v116, v116, v117
	v_mul_f32_e32 v117, v125, v125
	v_fmac_f32_e32 v117, v124, v124
	v_add_f32_e32 v116, v117, v116
	v_mul_f32_e32 v117, v119, v119
	v_fmac_f32_e32 v117, v126, v126
	v_add_f32_e32 v116, v117, v116
	v_add_f32_e32 v127, v145, v116
	v_cvt_pk_bf16_f32 v116, v120, v121
	v_cvt_pk_bf16_f32 v117, v122, v123
	v_cvt_pk_bf16_f32 v118, v124, v125
	v_cvt_pk_bf16_f32 v119, v126, v119
	global_store_dwordx4 v[136:137], v[116:119], off offset:256 nt
	ds_bpermute_b32 v116, v156, v127
	s_waitcnt lgkmcnt(0)
	v_add_f32_e32 v116, v127, v116
	ds_bpermute_b32 v117, v155, v116
	s_and_saveexec_b64 s[22:23], vcc
	s_cbranch_execz .LBB0_122
	v_lshlrev_b64 v[118:119], 7, v[134:135]
	v_lshl_add_u64 v[118:119], s[0:1], 0, v[118:119]
	v_lshl_add_u64 v[118:119], s[20:21], 2, v[118:119]
	s_lshl_b32 s84, s36, 2
	v_lshl_add_u64 v[118:119], v[118:119], 0, s[84:85]
	s_waitcnt lgkmcnt(0)
	v_add_f32_e32 v116, v116, v117
	global_store_dword v[118:119], v116, off

; template <class Epi, class Sched>
; __device__ __forceinline__ void gemm_simple(PG8_LAS unsigned char* lds, const Gemm g, const Sched& S, const Epi& E, int wave_s) {
;     ...
;         for (; t < nt; t += 2) {
;             const bool last = (t == nt - 2);
;             PG8_TILE(0, cA + (size_t)(t + 1) * kstep, cB + (size_t)(t + 1) * kstep, true);
;             const char* a2 = last ? nA : cA + (size_t)(t + 2) * kstep; const char* b2 = last ? nB : cB + (size_t)(t + 2) * kstep;
;             PG8_TILE(1, a2, b2, (!last || has_next));
.LBB0_173:
	s_waitcnt vmcnt(2) lgkmcnt(0)
	s_barrier
	ds_read_b128 v[146:149], v132
	ds_read_b128 v[174:177], v152
	ds_read_b128 v[158:161], v132 offset:2048
	ds_read_b128 v[182:185], v152 offset:2048
	ds_read_b128 v[190:193], v152 offset:4096
	s_add_u32 s60, s20, s59
	s_addc_u32 s61, s21, 0
	s_add_u32 s26, s60, 0x80
	s_addc_u32 s27, s61, 0
	s_mov_b32 m0, s46
	s_nop 0
	global_load_lds_dwordx4 v137, s[26:27]
	s_mov_b32 m0, s50
	s_nop 0
	global_load_lds_dwordx4 v139, s[26:27]
	s_waitcnt lgkmcnt(3)
	v_mfma_f32_16x16x32_bf16 v[128:131], v[146:149], v[174:177], v[128:131]
	s_waitcnt lgkmcnt(2)
	v_mfma_f32_16x16x32_bf16 v[124:127], v[158:161], v[174:177], v[124:127]
	ds_read_b128 v[198:201], v152 offset:6144
	s_waitcnt lgkmcnt(2)
	v_mfma_f32_16x16x32_bf16 v[112:115], v[146:149], v[182:185], v[112:115]
	v_mfma_f32_16x16x32_bf16 v[108:111], v[158:161], v[182:185], v[108:111]
	ds_read_b128 v[154:157], v132 offset:1024
	ds_read_b128 v[178:181], v152 offset:1024
	s_waitcnt lgkmcnt(3)
	v_mfma_f32_16x16x32_bf16 v[96:99], v[146:149], v[190:193], v[96:99]
	ds_read_b128 v[170:173], v132 offset:3072
	v_mfma_f32_16x16x32_bf16 v[92:95], v[158:161], v[190:193], v[92:95]
	ds_read_b128 v[186:189], v152 offset:3072
	s_waitcnt lgkmcnt(4)
	v_mfma_f32_16x16x32_bf16 v[80:83], v[146:149], v[198:201], v[80:83]
	v_mfma_f32_16x16x32_bf16 v[76:79], v[158:161], v[198:201], v[76:79]
	ds_read_b128 v[194:197], v152 offset:5120
	s_waitcnt lgkmcnt(3)
	v_mfma_f32_16x16x32_bf16 v[128:131], v[154:157], v[178:181], v[128:131]
	s_waitcnt lgkmcnt(2)
	v_mfma_f32_16x16x32_bf16 v[124:127], v[170:173], v[178:181], v[124:127]
	ds_read_b128 v[202:205], v152 offset:7168
	s_waitcnt lgkmcnt(2)
	v_mfma_f32_16x16x32_bf16 v[112:115], v[154:157], v[186:189], v[112:115]
	v_mfma_f32_16x16x32_bf16 v[108:111], v[170:173], v[186:189], v[108:111]
	ds_read_b128 v[206:209], v133
	s_waitcnt lgkmcnt(2)
	v_mfma_f32_16x16x32_bf16 v[96:99], v[154:157], v[194:197], v[96:99]
	ds_read_b128 v[214:217], v133 offset:2048
	v_mfma_f32_16x16x32_bf16 v[92:95], v[170:173], v[194:197], v[92:95]
	s_waitcnt lgkmcnt(2)
	v_mfma_f32_16x16x32_bf16 v[80:83], v[154:157], v[202:205], v[80:83]
	v_mfma_f32_16x16x32_bf16 v[76:79], v[170:173], v[202:205], v[76:79]
	s_add_u32 s62, s22, s59
	s_addc_u32 s63, s23, 0
	s_add_u32 s26, s62, 0x80
	s_addc_u32 s27, s63, 0
	s_mov_b32 m0, s47
	s_nop 0
	global_load_lds_dwordx4 v136, s[26:27]
	s_mov_b32 m0, s51
	s_nop 0
	global_load_lds_dwordx4 v138, s[26:27]
	s_waitcnt lgkmcnt(1)
	v_mfma_f32_16x16x32_bf16 v[120:123], v[206:209], v[174:177], v[120:123]
	s_waitcnt lgkmcnt(0)
	v_mfma_f32_16x16x32_bf16 v[116:119], v[214:217], v[174:177], v[116:119]
	v_mfma_f32_16x16x32_bf16 v[104:107], v[206:209], v[182:185], v[104:107]
	v_mfma_f32_16x16x32_bf16 v[100:103], v[214:217], v[182:185], v[100:103]
	ds_read_b128 v[210:213], v133 offset:1024
	v_mfma_f32_16x16x32_bf16 v[88:91], v[206:209], v[190:193], v[88:91]
	ds_read_b128 v[218:221], v133 offset:3072
	v_mfma_f32_16x16x32_bf16 v[84:87], v[214:217], v[190:193], v[84:87]
	v_mfma_f32_16x16x32_bf16 v[72:75], v[206:209], v[198:201], v[72:75]
	v_mfma_f32_16x16x32_bf16 v[68:71], v[214:217], v[198:201], v[68:71]
	s_waitcnt lgkmcnt(1)
	v_mfma_f32_16x16x32_bf16 v[120:123], v[210:213], v[178:181], v[120:123]
	s_waitcnt lgkmcnt(0)
	v_mfma_f32_16x16x32_bf16 v[116:119], v[218:221], v[178:181], v[116:119]
	v_mfma_f32_16x16x32_bf16 v[104:107], v[210:213], v[186:189], v[104:107]
	v_mfma_f32_16x16x32_bf16 v[100:103], v[218:221], v[186:189], v[100:103]
	v_mfma_f32_16x16x32_bf16 v[88:91], v[210:213], v[194:197], v[88:91]
	v_mfma_f32_16x16x32_bf16 v[84:87], v[218:221], v[194:197], v[84:87]
	v_mfma_f32_16x16x32_bf16 v[72:75], v[210:213], v[202:205], v[72:75]
	v_mfma_f32_16x16x32_bf16 v[68:71], v[218:221], v[202:205], v[68:71]
	s_waitcnt vmcnt(4) lgkmcnt(0)
	s_barrier
	ds_read_b128 v[174:177], v152 offset:16384
	ds_read_b128 v[182:185], v152 offset:18432
	ds_read_b128 v[190:193], v152 offset:20480
	s_add_u32 s26, s60, 0x40080
	s_addc_u32 s27, s61, 0
	s_mov_b32 m0, s48
	s_nop 0
	global_load_lds_dwordx4 v137, s[26:27]
	s_mov_b32 m0, s52
	s_nop 0
	global_load_lds_dwordx4 v139, s[26:27]
	s_waitcnt lgkmcnt(2)
	v_mfma_f32_16x16x32_bf16 v[64:67], v[146:149], v[174:177], v[64:67]
	v_mfma_f32_16x16x32_bf16 v[60:63], v[158:161], v[174:177], v[60:63]
	ds_read_b128 v[198:201], v152 offset:22528
	s_waitcnt lgkmcnt(2)
	v_mfma_f32_16x16x32_bf16 v[48:51], v[146:149], v[182:185], v[48:51]
	v_mfma_f32_16x16x32_bf16 v[44:47], v[158:161], v[182:185], v[44:47]
	ds_read_b128 v[178:181], v152 offset:17408
	s_waitcnt lgkmcnt(2)
	v_mfma_f32_16x16x32_bf16 v[32:35], v[146:149], v[190:193], v[32:35]
	v_mfma_f32_16x16x32_bf16 v[28:31], v[158:161], v[190:193], v[28:31]
	ds_read_b128 v[186:189], v152 offset:19456
	s_waitcnt lgkmcnt(2)
	v_mfma_f32_16x16x32_bf16 v[16:19], v[146:149], v[198:201], v[16:19]
	v_mfma_f32_16x16x32_bf16 v[12:15], v[158:161], v[198:201], v[12:15]
	ds_read_b128 v[194:197], v152 offset:21504
	s_waitcnt lgkmcnt(2)
	v_mfma_f32_16x16x32_bf16 v[64:67], v[154:157], v[178:181], v[64:67]
	v_mfma_f32_16x16x32_bf16 v[60:63], v[170:173], v[178:181], v[60:63]
	ds_read_b128 v[202:205], v152 offset:23552
	s_waitcnt lgkmcnt(2)
	v_mfma_f32_16x16x32_bf16 v[48:51], v[154:157], v[186:189], v[48:51]
	v_mfma_f32_16x16x32_bf16 v[44:47], v[170:173], v[186:189], v[44:47]
	s_waitcnt lgkmcnt(1)
	v_mfma_f32_16x16x32_bf16 v[32:35], v[154:157], v[194:197], v[32:35]
	v_mfma_f32_16x16x32_bf16 v[28:31], v[170:173], v[194:197], v[28:31]
	s_waitcnt lgkmcnt(0)
	v_mfma_f32_16x16x32_bf16 v[16:19], v[154:157], v[202:205], v[16:19]
	v_mfma_f32_16x16x32_bf16 v[12:15], v[170:173], v[202:205], v[12:15]
	s_add_u32 s26, s62, 0x40080
	s_addc_u32 s27, s63, 0
	s_mov_b32 m0, s49
	s_nop 0
	global_load_lds_dwordx4 v136, s[26:27]
	s_mov_b32 m0, s53
	s_nop 0
	global_load_lds_dwordx4 v138, s[26:27]
	v_mfma_f32_16x16x32_bf16 v[56:59], v[206:209], v[174:177], v[56:59]
	s_add_u32 s26, s62, 0x100
	s_addc_u32 s27, s63, 0
	s_add_u32 s60, s60, 0x100
	v_mfma_f32_16x16x32_bf16 v[52:55], v[214:217], v[174:177], v[52:55]
	s_addc_u32 s61, s61, 0
	v_mfma_f32_16x16x32_bf16 v[40:43], v[206:209], v[182:185], v[40:43]
	v_mfma_f32_16x16x32_bf16 v[36:39], v[214:217], v[182:185], v[36:39]
	v_mfma_f32_16x16x32_bf16 v[24:27], v[206:209], v[190:193], v[24:27]
	v_mfma_f32_16x16x32_bf16 v[20:23], v[214:217], v[190:193], v[20:23]
	v_mfma_f32_16x16x32_bf16 v[4:7], v[206:209], v[198:201], v[4:7]
	v_mfma_f32_16x16x32_bf16 v[8:11], v[214:217], v[198:201], v[8:11]
	v_mfma_f32_16x16x32_bf16 v[56:59], v[210:213], v[178:181], v[56:59]
	v_mfma_f32_16x16x32_bf16 v[52:55], v[218:221], v[178:181], v[52:55]
	v_mfma_f32_16x16x32_bf16 v[40:43], v[210:213], v[186:189], v[40:43]
	v_mfma_f32_16x16x32_bf16 v[36:39], v[218:221], v[186:189], v[36:39]
	v_mfma_f32_16x16x32_bf16 v[24:27], v[210:213], v[194:197], v[24:27]
	v_mfma_f32_16x16x32_bf16 v[20:23], v[218:221], v[194:197], v[20:23]
	v_mfma_f32_16x16x32_bf16 v[4:7], v[210:213], v[202:205], v[4:7]
	v_mfma_f32_16x16x32_bf16 v[8:11], v[218:221], v[202:205], v[8:11]
	s_waitcnt vmcnt(2) lgkmcnt(0)
	s_barrier
; template <class Epi, class Sched>
; __device__ __forceinline__ void gemm_simple(PG8_LAS unsigned char* lds, const Gemm g, const Sched& S, const Epi& E, int wave_s) {
;     ...
;         for (; t < nt; t += 2) {
;             const bool last = (t == nt - 2);
;             PG8_TILE(0, cA + (size_t)(t + 1) * kstep, cB + (size_t)(t + 1) * kstep, true);
;             const char* a2 = last ? nA : cA + (size_t)(t + 2) * kstep; const char* b2 = last ? nB : cB + (size_t)(t + 2) * kstep;
;             PG8_TILE(1, a2, b2, (!last || has_next));
	ds_read_b128 v[146:149], v134
	ds_read_b128 v[174:177], v152 offset:32768
	ds_read_b128 v[158:161], v134 offset:2048
	ds_read_b128 v[182:185], v152 offset:34816
	ds_read_b128 v[190:193], v152 offset:36864
	s_cmp_eq_u32 s59, s24
	s_cselect_b32 s27, s9, s27
	s_cselect_b32 s26, s56, s26
	s_cselect_b32 s61, s5, s61
	s_cselect_b32 s60, s57, s60
	s_mov_b32 m0, s39
	s_nop 0
	global_load_lds_dwordx4 v137, s[60:61]
	s_mov_b32 m0, s40
	s_nop 0
	global_load_lds_dwordx4 v139, s[60:61]
	s_waitcnt lgkmcnt(3)
	v_mfma_f32_16x16x32_bf16 v[128:131], v[146:149], v[174:177], v[128:131]
	s_waitcnt lgkmcnt(2)
	v_mfma_f32_16x16x32_bf16 v[124:127], v[158:161], v[174:177], v[124:127]
	ds_read_b128 v[198:201], v152 offset:38912
	s_waitcnt lgkmcnt(2)
	v_mfma_f32_16x16x32_bf16 v[112:115], v[146:149], v[182:185], v[112:115]
	v_mfma_f32_16x16x32_bf16 v[108:111], v[158:161], v[182:185], v[108:111]
	ds_read_b128 v[154:157], v134 offset:1024
	ds_read_b128 v[178:181], v152 offset:33792
	s_waitcnt lgkmcnt(3)
	v_mfma_f32_16x16x32_bf16 v[96:99], v[146:149], v[190:193], v[96:99]
	ds_read_b128 v[170:173], v134 offset:3072
	v_mfma_f32_16x16x32_bf16 v[92:95], v[158:161], v[190:193], v[92:95]
	ds_read_b128 v[186:189], v152 offset:35840
	s_waitcnt lgkmcnt(4)
	v_mfma_f32_16x16x32_bf16 v[80:83], v[146:149], v[198:201], v[80:83]
	v_mfma_f32_16x16x32_bf16 v[76:79], v[158:161], v[198:201], v[76:79]
	ds_read_b128 v[194:197], v152 offset:37888
	s_waitcnt lgkmcnt(3)
	v_mfma_f32_16x16x32_bf16 v[128:131], v[154:157], v[178:181], v[128:131]
	s_waitcnt lgkmcnt(2)
	v_mfma_f32_16x16x32_bf16 v[124:127], v[170:173], v[178:181], v[124:127]
	ds_read_b128 v[202:205], v152 offset:39936
	s_waitcnt lgkmcnt(2)
	v_mfma_f32_16x16x32_bf16 v[112:115], v[154:157], v[186:189], v[112:115]
	v_mfma_f32_16x16x32_bf16 v[108:111], v[170:173], v[186:189], v[108:111]
	ds_read_b128 v[206:209], v135
	s_waitcnt lgkmcnt(2)
	v_mfma_f32_16x16x32_bf16 v[96:99], v[154:157], v[194:197], v[96:99]
	ds_read_b128 v[214:217], v135 offset:2048
	v_mfma_f32_16x16x32_bf16 v[92:95], v[170:173], v[194:197], v[92:95]
	s_waitcnt lgkmcnt(2)
	v_mfma_f32_16x16x32_bf16 v[80:83], v[154:157], v[202:205], v[80:83]
	v_mfma_f32_16x16x32_bf16 v[76:79], v[170:173], v[202:205], v[76:79]
	s_mov_b32 m0, s19
	s_nop 0
	global_load_lds_dwordx4 v136, s[26:27]
	s_mov_b32 m0, s41
	s_nop 0
	global_load_lds_dwordx4 v138, s[26:27]
	s_waitcnt lgkmcnt(1)
	v_mfma_f32_16x16x32_bf16 v[120:123], v[206:209], v[174:177], v[120:123]
	s_waitcnt lgkmcnt(0)
	v_mfma_f32_16x16x32_bf16 v[116:119], v[214:217], v[174:177], v[116:119]
	v_mfma_f32_16x16x32_bf16 v[104:107], v[206:209], v[182:185], v[104:107]
	v_mfma_f32_16x16x32_bf16 v[100:103], v[214:217], v[182:185], v[100:103]
	ds_read_b128 v[210:213], v135 offset:1024
	v_mfma_f32_16x16x32_bf16 v[88:91], v[206:209], v[190:193], v[88:91]
	ds_read_b128 v[218:221], v135 offset:3072
	v_mfma_f32_16x16x32_bf16 v[84:87], v[214:217], v[190:193], v[84:87]
	v_mfma_f32_16x16x32_bf16 v[72:75], v[206:209], v[198:201], v[72:75]
	v_mfma_f32_16x16x32_bf16 v[68:71], v[214:217], v[198:201], v[68:71]
	s_waitcnt lgkmcnt(1)
	v_mfma_f32_16x16x32_bf16 v[120:123], v[210:213], v[178:181], v[120:123]
	s_waitcnt lgkmcnt(0)
	v_mfma_f32_16x16x32_bf16 v[116:119], v[218:221], v[178:181], v[116:119]
	v_mfma_f32_16x16x32_bf16 v[104:107], v[210:213], v[186:189], v[104:107]
	v_mfma_f32_16x16x32_bf16 v[100:103], v[218:221], v[186:189], v[100:103]
	v_mfma_f32_16x16x32_bf16 v[88:91], v[210:213], v[194:197], v[88:91]
	v_mfma_f32_16x16x32_bf16 v[84:87], v[218:221], v[194:197], v[84:87]
	v_mfma_f32_16x16x32_bf16 v[72:75], v[210:213], v[202:205], v[72:75]
	v_mfma_f32_16x16x32_bf16 v[68:71], v[218:221], v[202:205], v[68:71]
	s_waitcnt vmcnt(4) lgkmcnt(0)
	s_barrier
	ds_read_b128 v[174:177], v152 offset:49152
	ds_read_b128 v[182:185], v152 offset:51200
	ds_read_b128 v[190:193], v152 offset:53248
	s_add_u32 s60, s60, 0x40000
	s_addc_u32 s61, s61, 0
	s_mov_b32 m0, s42
	s_nop 0
	global_load_lds_dwordx4 v137, s[60:61]
	s_mov_b32 m0, s43
	s_nop 0
	global_load_lds_dwordx4 v139, s[60:61]
	s_waitcnt lgkmcnt(2)
	v_mfma_f32_16x16x32_bf16 v[64:67], v[146:149], v[174:177], v[64:67]
	v_mfma_f32_16x16x32_bf16 v[60:63], v[158:161], v[174:177], v[60:63]
	ds_read_b128 v[198:201], v152 offset:55296
	s_waitcnt lgkmcnt(2)
	v_mfma_f32_16x16x32_bf16 v[48:51], v[146:149], v[182:185], v[48:51]
	v_mfma_f32_16x16x32_bf16 v[44:47], v[158:161], v[182:185], v[44:47]
	ds_read_b128 v[178:181], v152 offset:50176
	s_waitcnt lgkmcnt(2)
	v_mfma_f32_16x16x32_bf16 v[32:35], v[146:149], v[190:193], v[32:35]
	v_mfma_f32_16x16x32_bf16 v[28:31], v[158:161], v[190:193], v[28:31]
	ds_read_b128 v[186:189], v152 offset:52224
	s_waitcnt lgkmcnt(2)
	v_mfma_f32_16x16x32_bf16 v[16:19], v[146:149], v[198:201], v[16:19]
	v_mfma_f32_16x16x32_bf16 v[12:15], v[158:161], v[198:201], v[12:15]
	ds_read_b128 v[194:197], v152 offset:54272
	s_waitcnt lgkmcnt(2)
	v_mfma_f32_16x16x32_bf16 v[64:67], v[154:157], v[178:181], v[64:67]
	v_mfma_f32_16x16x32_bf16 v[60:63], v[170:173], v[178:181], v[60:63]
	ds_read_b128 v[202:205], v152 offset:56320
	s_waitcnt lgkmcnt(2)
	v_mfma_f32_16x16x32_bf16 v[48:51], v[154:157], v[186:189], v[48:51]
	v_mfma_f32_16x16x32_bf16 v[44:47], v[170:173], v[186:189], v[44:47]
	s_waitcnt lgkmcnt(1)
	v_mfma_f32_16x16x32_bf16 v[32:35], v[154:157], v[194:197], v[32:35]
	v_mfma_f32_16x16x32_bf16 v[28:31], v[170:173], v[194:197], v[28:31]
	s_waitcnt lgkmcnt(0)
	v_mfma_f32_16x16x32_bf16 v[16:19], v[154:157], v[202:205], v[16:19]
	v_mfma_f32_16x16x32_bf16 v[12:15], v[170:173], v[202:205], v[12:15]
	s_add_u32 s26, s26, 0x40000
	s_addc_u32 s27, s27, 0
	s_mov_b32 m0, s44
	s_nop 0
	global_load_lds_dwordx4 v136, s[26:27]
	s_mov_b32 m0, s45
	s_nop 0
	global_load_lds_dwordx4 v138, s[26:27]
	v_mfma_f32_16x16x32_bf16 v[56:59], v[206:209], v[174:177], v[56:59]
	s_add_i32 s58, s58, 2
	s_add_u32 s24, s24, 0xffffff00
	s_addc_u32 s25, s25, -1
	v_mfma_f32_16x16x32_bf16 v[52:55], v[214:217], v[174:177], v[52:55]
	s_add_u32 s20, s20, 0x100
	s_addc_u32 s21, s21, 0
	s_add_u32 s22, s22, 0x100
	v_mfma_f32_16x16x32_bf16 v[40:43], v[206:209], v[182:185], v[40:43]
	s_addc_u32 s23, s23, 0
	s_cmp_lt_u32 s58, 14
	v_mfma_f32_16x16x32_bf16 v[36:39], v[214:217], v[182:185], v[36:39]
	v_mfma_f32_16x16x32_bf16 v[24:27], v[206:209], v[190:193], v[24:27]
	v_mfma_f32_16x16x32_bf16 v[20:23], v[214:217], v[190:193], v[20:23]
	v_mfma_f32_16x16x32_bf16 v[4:7], v[206:209], v[198:201], v[4:7]
	v_mfma_f32_16x16x32_bf16 v[8:11], v[214:217], v[198:201], v[8:11]
	v_mfma_f32_16x16x32_bf16 v[56:59], v[210:213], v[178:181], v[56:59]
	v_mfma_f32_16x16x32_bf16 v[52:55], v[218:221], v[178:181], v[52:55]
	v_mfma_f32_16x16x32_bf16 v[40:43], v[210:213], v[186:189], v[40:43]
	v_mfma_f32_16x16x32_bf16 v[36:39], v[218:221], v[186:189], v[36:39]
	v_mfma_f32_16x16x32_bf16 v[24:27], v[210:213], v[194:197], v[24:27]
	v_mfma_f32_16x16x32_bf16 v[20:23], v[218:221], v[194:197], v[20:23]
	v_mfma_f32_16x16x32_bf16 v[4:7], v[210:213], v[202:205], v[4:7]
	v_mfma_f32_16x16x32_bf16 v[8:11], v[218:221], v[202:205], v[8:11]
	s_cbranch_scc1 .LBB0_173
; __device__ __forceinline__ unsigned cvt_pk_bf16(float lo, float hi) { unsigned r; asm volatile("v_cvt_pk_bf16_f32 %0, %1, %2" : "=v"(r) : "v"(lo), "v"(hi)); return r; }
; #define LAS __attribute__((address_space(3)))
; __device__ __forceinline__ float bflo(unsigned w) { return __uint_as_float(w << 16); }
; __device__ __forceinline__ float bfhi(unsigned w) { return __uint_as_float(w & 0xffff0000u); }
;     __device__ __forceinline__ void operator()(const f32x4 (&acc)[2][2][4][2], const Unit& u, int wr, int wc, int fr, int fq, const LAS float*) const {
;         const int row0 = u.pm * 256 + wr * 64 + fr, col0 = u.pn * 256 + wc * 32 + 8 * fq;
; #pragma unroll
;         for (int ai = 0; ai < 2; ++ai)
; #pragma unroll
;             for (int m = 0; m < 4; ++m) { const size_t row = (size_t)(row0 + ai * 128 + m * 16);
; #pragma unroll
;                 for (int bj = 0; bj < 2; ++bj) { const int col = col0 + bj * 128;
;                     const u32x4 g = *(const u32x4*)(G + row * NGATE + MODE * DM + col);
;                     f32x4 v0 = acc[ai][bj][m][0], v1 = acc[ai][bj][m][1];
;                     v0[0] *= bflo(g.x); v0[1] *= bfhi(g.x); v0[2] *= bflo(g.y); v0[3] *= bfhi(g.y); v1[0] *= bflo(g.z); v1[1] *= bfhi(g.z); v1[2] *= bflo(g.w); v1[3] *= bfhi(g.w);
;                     bf16_t* tp = T + row * DM + col;
;                     if (MODE == 1) { const u32x4 t = *(const u32x4*)tp;
;                         v0[0] += bflo(t.x); v0[1] += bfhi(t.x); v0[2] += bflo(t.y); v0[3] += bfhi(t.y); v1[0] += bflo(t.z); v1[1] += bfhi(t.z); v1[2] += bflo(t.w); v1[3] += bfhi(t.w); }
;                     u32x4 w; w.x = cvt_pk_bf16(v0[0], v0[1]); w.y = cvt_pk_bf16(v0[2], v0[3]); w.z = cvt_pk_bf16(v1[0], v1[1]); w.w = cvt_pk_bf16(v1[2], v1[3]);
;                     *(u32x4*)tp = w; } }
	v_mov_b32_e32 v132, v141
	s_lshl_b32 s5, s18, 8
	v_mbcnt_lo_u32_b32 v132, -1, v132
	v_mbcnt_hi_u32_b32 v132, -1, v132
	s_add_i32 s5, s5, s37
	v_and_or_b32 v134, v132, 15, s5
	s_lshl_b32 s5, s35, 8
	v_ashrrev_i32_e32 v132, 1, v132
	s_or_b32 s5, s5, s38
	v_and_b32_e32 v132, -8, v132
	v_add_u32_e32 v132, s5, v132
	v_ashrrev_i32_e32 v135, 31, v134
	v_lshlrev_b64 v[142:143], 13, v[134:135]
	v_ashrrev_i32_e32 v133, 31, v132
	v_lshl_add_u64 v[142:143], s[2:3], 0, v[142:143]
	v_lshlrev_b64 v[132:133], 1, v[132:133]
	v_lshl_add_u64 v[142:143], v[142:143], 0, v[132:133]
	s_mov_b64 s[20:21], 0x1000
	v_lshl_add_u64 v[154:155], v[142:143], 0, s[20:21]
	v_add_co_u32_e32 v142, vcc, s76, v142
	v_lshlrev_b64 v[144:145], 12, v[134:135]
	s_nop 0
	v_addc_co_u32_e32 v143, vcc, 0, v143, vcc
	v_lshlrev_b32_e32 v236, 13, v134
	v_add_u32_e32 v236, v236, v132
	v_add_u32_e32 v236, 0x1000, v236
	v_lshlrev_b32_e32 v238, 12, v134
	v_add_u32_e32 v238, v238, v132
	global_load_dwordx4 v[172:175], v236, s[2:3]
	global_load_dwordx4 v[176:179], v238, s[12:13]
	global_load_dwordx4 v[180:183], v236, s[2:3] offset:256
	global_load_dwordx4 v[184:187], v238, s[12:13] offset:256
	v_add_u32_e32 v237, 0x20000, v236
	v_add_u32_e32 v239, 0x10000, v238
	global_load_dwordx4 v[188:191], v237, s[2:3]
	global_load_dwordx4 v[192:195], v239, s[12:13]
	global_load_dwordx4 v[196:199], v237, s[2:3] offset:256
	global_load_dwordx4 v[200:203], v239, s[12:13] offset:256
	v_add_u32_e32 v237, 0x40000, v236
	v_add_u32_e32 v239, 0x20000, v238
	global_load_dwordx4 v[204:207], v237, s[2:3]
	global_load_dwordx4 v[208:211], v239, s[12:13]
	global_load_dwordx4 v[212:215], v237, s[2:3] offset:256
	global_load_dwordx4 v[216:219], v239, s[12:13] offset:256
	v_add_u32_e32 v237, 0x60000, v236
	v_add_u32_e32 v239, 0x30000, v238
	global_load_dwordx4 v[220:223], v237, s[2:3]
	global_load_dwordx4 v[224:227], v239, s[12:13]
	global_load_dwordx4 v[228:231], v237, s[2:3] offset:256
	global_load_dwordx4 v[232:235], v239, s[12:13] offset:256
	v_lshl_add_u64 v[142:143], s[12:13], 0, v[144:145]
	v_lshl_add_u64 v[142:143], v[142:143], 0, v[132:133]
	s_mov_b32 s35, s4
	s_mov_b32 s18, s8
	s_mov_b64 s[22:23], s[10:11]
	s_mov_b32 s9, s55
	s_waitcnt vmcnt(15)
	s_nop 1
	v_mov_b64_e32 v[146:147], v[172:173]
	v_mov_b64_e32 v[148:149], v[174:175]
	v_lshlrev_b32_e32 v135, 16, v146
	v_and_b32_e32 v153, 0xffff0000, v146
	v_lshlrev_b32_e32 v156, 16, v147
	v_and_b32_e32 v157, 0xffff0000, v147
	v_lshlrev_b32_e32 v158, 16, v148
	v_and_b32_e32 v159, 0xffff0000, v148
	v_lshlrev_b32_e32 v160, 16, v149
	v_and_b32_e32 v161, 0xffff0000, v149
	s_waitcnt vmcnt(14)
	s_nop 1
	v_mov_b64_e32 v[146:147], v[176:177]
	v_mov_b64_e32 v[148:149], v[178:179]
	v_lshlrev_b32_e32 v144, 16, v146
	v_fmac_f32_e32 v144, v128, v135
	v_and_b32_e32 v128, 0xffff0000, v146
	v_fmac_f32_e32 v128, v129, v153
	v_lshlrev_b32_e32 v129, 16, v147
	v_fmac_f32_e32 v129, v130, v156
	v_and_b32_e32 v130, 0xffff0000, v147
	v_fmac_f32_e32 v130, v131, v157
	v_lshlrev_b32_e32 v131, 16, v148
	v_and_b32_e32 v135, 0xffff0000, v148
	v_lshlrev_b32_e32 v145, 16, v149
	v_and_b32_e32 v146, 0xffff0000, v149
	v_fmac_f32_e32 v131, v124, v158
	v_fmac_f32_e32 v135, v125, v159
	v_fmac_f32_e32 v145, v126, v160
	v_fmac_f32_e32 v146, v127, v161
	v_cvt_pk_bf16_f32 v124, v144, v128
	v_cvt_pk_bf16_f32 v125, v129, v130
	v_cvt_pk_bf16_f32 v126, v131, v135
	v_cvt_pk_bf16_f32 v127, v145, v146
	global_store_dwordx4 v[142:143], v[124:127], off
	s_waitcnt vmcnt(14)
	s_nop 1
	v_mov_b64_e32 v[124:125], v[180:181]
	v_mov_b64_e32 v[126:127], v[182:183]
	v_lshlrev_b32_e32 v128, 16, v124
	v_and_b32_e32 v129, 0xffff0000, v124
	v_lshlrev_b32_e32 v130, 16, v125
	v_and_b32_e32 v131, 0xffff0000, v125
	v_lshlrev_b32_e32 v135, 16, v126
	v_and_b32_e32 v144, 0xffff0000, v126
	v_lshlrev_b32_e32 v145, 16, v127
	v_and_b32_e32 v146, 0xffff0000, v127
	s_waitcnt vmcnt(13)
	s_nop 1
	v_mov_b64_e32 v[124:125], v[184:185]
	v_mov_b64_e32 v[126:127], v[186:187]
	v_lshlrev_b32_e32 v147, 16, v124
	v_fmac_f32_e32 v147, v120, v128
	v_and_b32_e32 v120, 0xffff0000, v124
	v_fmac_f32_e32 v120, v121, v129
	v_lshlrev_b32_e32 v121, 16, v125
	v_fmac_f32_e32 v121, v122, v130
	v_and_b32_e32 v122, 0xffff0000, v125
	v_fmac_f32_e32 v122, v123, v131
	v_lshlrev_b32_e32 v123, 16, v126
	v_fmac_f32_e32 v123, v116, v135
	v_and_b32_e32 v124, 0xffff0000, v126
	v_lshlrev_b32_e32 v125, 16, v127
	v_and_b32_e32 v126, 0xffff0000, v127
	v_cvt_pk_bf16_f32 v116, v147, v120
	v_fmac_f32_e32 v124, v117, v144
	v_fmac_f32_e32 v125, v118, v145
	v_fmac_f32_e32 v126, v119, v146
	v_cvt_pk_bf16_f32 v117, v121, v122
	v_cvt_pk_bf16_f32 v118, v123, v124
	v_cvt_pk_bf16_f32 v119, v125, v126
	global_store_dwordx4 v[142:143], v[116:119], off offset:256
	v_add_u32_e32 v237, 0x100000, v236
	v_add_u32_e32 v239, 0x80000, v238
	global_load_dwordx4 v[172:175], v237, s[2:3]
	global_load_dwordx4 v[176:179], v239, s[12:13]
	global_load_dwordx4 v[180:183], v237, s[2:3] offset:256
	global_load_dwordx4 v[184:187], v239, s[12:13] offset:256
	s_nop 1
	v_or_b32_e32 v116, 16, v134
	v_ashrrev_i32_e32 v117, 31, v116
	v_lshlrev_b64 v[118:119], 13, v[116:117]
	v_lshlrev_b64 v[122:123], 12, v[116:117]
	v_lshl_add_u64 v[116:117], s[2:3], 0, v[118:119]
	v_lshl_add_u64 v[118:119], v[116:117], 0, v[132:133]
	v_lshl_add_u64 v[116:117], v[118:119], 0, s[20:21]
	v_add_co_u32_e32 v118, vcc, s76, v118
	s_nop 1
	v_addc_co_u32_e32 v119, vcc, 0, v119, vcc
	s_waitcnt vmcnt(17)
; __device__ __forceinline__ unsigned cvt_pk_bf16(float lo, float hi) { unsigned r; asm volatile("v_cvt_pk_bf16_f32 %0, %1, %2" : "=v"(r) : "v"(lo), "v"(hi)); return r; }
; #define LAS __attribute__((address_space(3)))
; __device__ __forceinline__ float bflo(unsigned w) { return __uint_as_float(w << 16); }
; __device__ __forceinline__ float bfhi(unsigned w) { return __uint_as_float(w & 0xffff0000u); }
;     __device__ __forceinline__ void operator()(const f32x4 (&acc)[2][2][4][2], const Unit& u, int wr, int wc, int fr, int fq, const LAS float*) const {
;         const int row0 = u.pm * 256 + wr * 64 + fr, col0 = u.pn * 256 + wc * 32 + 8 * fq;
; #pragma unroll
;         for (int ai = 0; ai < 2; ++ai)
; #pragma unroll
;             for (int m = 0; m < 4; ++m) { const size_t row = (size_t)(row0 + ai * 128 + m * 16);
; #pragma unroll
;                 for (int bj = 0; bj < 2; ++bj) { const int col = col0 + bj * 128;
;                     const u32x4 g = *(const u32x4*)(G + row * NGATE + MODE * DM + col);
;                     f32x4 v0 = acc[ai][bj][m][0], v1 = acc[ai][bj][m][1];
;                     v0[0] *= bflo(g.x); v0[1] *= bfhi(g.x); v0[2] *= bflo(g.y); v0[3] *= bfhi(g.y); v1[0] *= bflo(g.z); v1[1] *= bfhi(g.z); v1[2] *= bflo(g.w); v1[3] *= bfhi(g.w);
;                     bf16_t* tp = T + row * DM + col;
;                     if (MODE == 1) { const u32x4 t = *(const u32x4*)tp;
;                         v0[0] += bflo(t.x); v0[1] += bfhi(t.x); v0[2] += bflo(t.y); v0[3] += bfhi(t.y); v1[0] += bflo(t.z); v1[1] += bfhi(t.z); v1[2] += bflo(t.w); v1[3] += bfhi(t.w); }
;                     u32x4 w; w.x = cvt_pk_bf16(v0[0], v0[1]); w.y = cvt_pk_bf16(v0[2], v0[3]); w.z = cvt_pk_bf16(v1[0], v1[1]); w.w = cvt_pk_bf16(v1[2], v1[3]);
;                     *(u32x4*)tp = w; } }
	s_nop 1
	v_mov_b64_e32 v[118:119], v[188:189]
	v_mov_b64_e32 v[120:121], v[190:191]
	v_lshlrev_b32_e32 v124, 16, v118
	v_and_b32_e32 v125, 0xffff0000, v118
	v_lshlrev_b32_e32 v126, 16, v119
	v_and_b32_e32 v127, 0xffff0000, v119
	v_lshl_add_u64 v[118:119], s[12:13], 0, v[122:123]
	v_lshl_add_u64 v[122:123], v[118:119], 0, v[132:133]
	v_lshlrev_b32_e32 v128, 16, v120
	v_and_b32_e32 v129, 0xffff0000, v120
	v_lshlrev_b32_e32 v130, 16, v121
	v_and_b32_e32 v131, 0xffff0000, v121
	s_waitcnt vmcnt(16)
	s_nop 1
	v_mov_b64_e32 v[118:119], v[192:193]
	v_mov_b64_e32 v[120:121], v[194:195]
	v_lshlrev_b32_e32 v135, 16, v118
	v_fmac_f32_e32 v135, v112, v124
	v_and_b32_e32 v112, 0xffff0000, v118
	v_fmac_f32_e32 v112, v113, v125
	v_lshlrev_b32_e32 v113, 16, v119
	v_fmac_f32_e32 v113, v114, v126
	v_and_b32_e32 v114, 0xffff0000, v119
	v_fmac_f32_e32 v114, v115, v127
	v_lshlrev_b32_e32 v115, 16, v120
	v_and_b32_e32 v118, 0xffff0000, v120
	v_lshlrev_b32_e32 v119, 16, v121
	v_and_b32_e32 v120, 0xffff0000, v121
	v_fmac_f32_e32 v115, v108, v128
	v_fmac_f32_e32 v118, v109, v129
	v_fmac_f32_e32 v119, v110, v130
	v_fmac_f32_e32 v120, v111, v131
	v_cvt_pk_bf16_f32 v108, v135, v112
	v_cvt_pk_bf16_f32 v109, v113, v114
	v_cvt_pk_bf16_f32 v110, v115, v118
	v_cvt_pk_bf16_f32 v111, v119, v120
	global_store_dwordx4 v[122:123], v[108:111], off
	s_waitcnt vmcnt(16)
	s_nop 1
	v_mov_b64_e32 v[108:109], v[196:197]
	v_mov_b64_e32 v[110:111], v[198:199]
	v_lshlrev_b32_e32 v112, 16, v108
	v_and_b32_e32 v113, 0xffff0000, v108
	v_lshlrev_b32_e32 v114, 16, v109
	v_and_b32_e32 v115, 0xffff0000, v109
	v_lshlrev_b32_e32 v116, 16, v110
	v_and_b32_e32 v117, 0xffff0000, v110
	v_lshlrev_b32_e32 v118, 16, v111
	v_and_b32_e32 v119, 0xffff0000, v111
	s_waitcnt vmcnt(15)
	s_nop 1
	v_mov_b64_e32 v[108:109], v[200:201]
	v_mov_b64_e32 v[110:111], v[202:203]
	v_lshlrev_b32_e32 v120, 16, v108
	v_fmac_f32_e32 v120, v104, v112
	v_and_b32_e32 v104, 0xffff0000, v108
	v_fmac_f32_e32 v104, v105, v113
	v_lshlrev_b32_e32 v105, 16, v109
	v_fmac_f32_e32 v105, v106, v114
	v_and_b32_e32 v106, 0xffff0000, v109
	v_fmac_f32_e32 v106, v107, v115
	v_lshlrev_b32_e32 v107, 16, v110
	v_fmac_f32_e32 v107, v100, v116
	v_and_b32_e32 v108, 0xffff0000, v110
	v_lshlrev_b32_e32 v109, 16, v111
	v_and_b32_e32 v110, 0xffff0000, v111
	v_cvt_pk_bf16_f32 v100, v120, v104
	v_fmac_f32_e32 v108, v101, v117
	v_fmac_f32_e32 v109, v102, v118
	v_fmac_f32_e32 v110, v103, v119
	v_cvt_pk_bf16_f32 v101, v105, v106
	v_cvt_pk_bf16_f32 v102, v107, v108
	v_cvt_pk_bf16_f32 v103, v109, v110
	global_store_dwordx4 v[122:123], v[100:103], off offset:256
	v_add_u32_e32 v237, 0x120000, v236
	v_add_u32_e32 v239, 0x90000, v238
	global_load_dwordx4 v[188:191], v237, s[2:3]
	global_load_dwordx4 v[192:195], v239, s[12:13]
	global_load_dwordx4 v[196:199], v237, s[2:3] offset:256
	global_load_dwordx4 v[200:203], v239, s[12:13] offset:256
	s_nop 1
	v_or_b32_e32 v100, 32, v134
	v_ashrrev_i32_e32 v101, 31, v100
	v_lshlrev_b64 v[102:103], 13, v[100:101]
	v_lshlrev_b64 v[106:107], 12, v[100:101]
	v_lshl_add_u64 v[100:101], s[2:3], 0, v[102:103]
	v_lshl_add_u64 v[102:103], v[100:101], 0, v[132:133]
	v_lshl_add_u64 v[100:101], v[102:103], 0, s[20:21]
	v_add_co_u32_e32 v102, vcc, s76, v102
	s_nop 1
	v_addc_co_u32_e32 v103, vcc, 0, v103, vcc
	s_waitcnt vmcnt(19)
	s_nop 1
	v_mov_b64_e32 v[102:103], v[204:205]
	v_mov_b64_e32 v[104:105], v[206:207]
	v_lshlrev_b32_e32 v108, 16, v102
	v_and_b32_e32 v109, 0xffff0000, v102
	v_lshlrev_b32_e32 v110, 16, v103
	v_and_b32_e32 v111, 0xffff0000, v103
	v_lshl_add_u64 v[102:103], s[12:13], 0, v[106:107]
	v_lshl_add_u64 v[106:107], v[102:103], 0, v[132:133]
	v_lshlrev_b32_e32 v112, 16, v104
	v_and_b32_e32 v113, 0xffff0000, v104
	v_lshlrev_b32_e32 v114, 16, v105
	v_and_b32_e32 v115, 0xffff0000, v105
	s_waitcnt vmcnt(18)
	s_nop 1
	v_mov_b64_e32 v[102:103], v[208:209]
	v_mov_b64_e32 v[104:105], v[210:211]
	v_lshlrev_b32_e32 v116, 16, v102
	v_fmac_f32_e32 v116, v96, v108
	v_and_b32_e32 v96, 0xffff0000, v102
	v_fmac_f32_e32 v96, v97, v109
	v_lshlrev_b32_e32 v97, 16, v103
	v_fmac_f32_e32 v97, v98, v110
	v_and_b32_e32 v98, 0xffff0000, v103
	v_fmac_f32_e32 v98, v99, v111
	v_lshlrev_b32_e32 v99, 16, v104
	v_and_b32_e32 v102, 0xffff0000, v104
	v_lshlrev_b32_e32 v103, 16, v105
	v_and_b32_e32 v104, 0xffff0000, v105
	v_fmac_f32_e32 v99, v92, v112
	v_fmac_f32_e32 v102, v93, v113
	v_fmac_f32_e32 v103, v94, v114
	v_fmac_f32_e32 v104, v95, v115
	v_cvt_pk_bf16_f32 v92, v116, v96
	v_cvt_pk_bf16_f32 v93, v97, v98
	v_cvt_pk_bf16_f32 v94, v99, v102
	v_cvt_pk_bf16_f32 v95, v103, v104
	global_store_dwordx4 v[106:107], v[92:95], off
	s_waitcnt vmcnt(18)
	s_nop 1
	v_mov_b64_e32 v[92:93], v[212:213]
	v_mov_b64_e32 v[94:95], v[214:215]
	v_lshlrev_b32_e32 v96, 16, v92
	v_and_b32_e32 v97, 0xffff0000, v92
	v_lshlrev_b32_e32 v98, 16, v93
	v_and_b32_e32 v99, 0xffff0000, v93
	v_lshlrev_b32_e32 v100, 16, v94
	v_and_b32_e32 v101, 0xffff0000, v94
	v_lshlrev_b32_e32 v102, 16, v95
	v_and_b32_e32 v103, 0xffff0000, v95
	s_waitcnt vmcnt(17)
; __device__ __forceinline__ unsigned cvt_pk_bf16(float lo, float hi) { unsigned r; asm volatile("v_cvt_pk_bf16_f32 %0, %1, %2" : "=v"(r) : "v"(lo), "v"(hi)); return r; }
; #define LAS __attribute__((address_space(3)))
; __device__ __forceinline__ float bflo(unsigned w) { return __uint_as_float(w << 16); }
; __device__ __forceinline__ float bfhi(unsigned w) { return __uint_as_float(w & 0xffff0000u); }
;     __device__ __forceinline__ void operator()(const f32x4 (&acc)[2][2][4][2], const Unit& u, int wr, int wc, int fr, int fq, const LAS float*) const {
;         const int row0 = u.pm * 256 + wr * 64 + fr, col0 = u.pn * 256 + wc * 32 + 8 * fq;
; #pragma unroll
;         for (int ai = 0; ai < 2; ++ai)
; #pragma unroll
;             for (int m = 0; m < 4; ++m) { const size_t row = (size_t)(row0 + ai * 128 + m * 16);
; #pragma unroll
;                 for (int bj = 0; bj < 2; ++bj) { const int col = col0 + bj * 128;
;                     const u32x4 g = *(const u32x4*)(G + row * NGATE + MODE * DM + col);
;                     f32x4 v0 = acc[ai][bj][m][0], v1 = acc[ai][bj][m][1];
;                     v0[0] *= bflo(g.x); v0[1] *= bfhi(g.x); v0[2] *= bflo(g.y); v0[3] *= bfhi(g.y); v1[0] *= bflo(g.z); v1[1] *= bfhi(g.z); v1[2] *= bflo(g.w); v1[3] *= bfhi(g.w);
;                     bf16_t* tp = T + row * DM + col;
;                     if (MODE == 1) { const u32x4 t = *(const u32x4*)tp;
;                         v0[0] += bflo(t.x); v0[1] += bfhi(t.x); v0[2] += bflo(t.y); v0[3] += bfhi(t.y); v1[0] += bflo(t.z); v1[1] += bfhi(t.z); v1[2] += bflo(t.w); v1[3] += bfhi(t.w); }
;                     u32x4 w; w.x = cvt_pk_bf16(v0[0], v0[1]); w.y = cvt_pk_bf16(v0[2], v0[3]); w.z = cvt_pk_bf16(v1[0], v1[1]); w.w = cvt_pk_bf16(v1[2], v1[3]);
;                     *(u32x4*)tp = w; } }
	s_nop 1
	v_mov_b64_e32 v[92:93], v[216:217]
	v_mov_b64_e32 v[94:95], v[218:219]
	v_lshlrev_b32_e32 v104, 16, v92
	v_fmac_f32_e32 v104, v88, v96
	v_and_b32_e32 v88, 0xffff0000, v92
	v_fmac_f32_e32 v88, v89, v97
	v_lshlrev_b32_e32 v89, 16, v93
	v_fmac_f32_e32 v89, v90, v98
	v_and_b32_e32 v90, 0xffff0000, v93
	v_fmac_f32_e32 v90, v91, v99
	v_lshlrev_b32_e32 v91, 16, v94
	v_fmac_f32_e32 v91, v84, v100
	v_and_b32_e32 v92, 0xffff0000, v94
	v_lshlrev_b32_e32 v93, 16, v95
	v_and_b32_e32 v94, 0xffff0000, v95
	v_cvt_pk_bf16_f32 v84, v104, v88
	v_fmac_f32_e32 v92, v85, v101
	v_fmac_f32_e32 v93, v86, v102
	v_fmac_f32_e32 v94, v87, v103
	v_cvt_pk_bf16_f32 v85, v89, v90
	v_cvt_pk_bf16_f32 v86, v91, v92
	v_cvt_pk_bf16_f32 v87, v93, v94
	global_store_dwordx4 v[106:107], v[84:87], off offset:256
	v_add_u32_e32 v237, 0x140000, v236
	v_add_u32_e32 v239, 0xa0000, v238
	global_load_dwordx4 v[204:207], v237, s[2:3]
	global_load_dwordx4 v[208:211], v239, s[12:13]
	global_load_dwordx4 v[212:215], v237, s[2:3] offset:256
	global_load_dwordx4 v[216:219], v239, s[12:13] offset:256
	s_nop 1
	v_or_b32_e32 v84, 48, v134
	v_ashrrev_i32_e32 v85, 31, v84
	v_lshlrev_b64 v[86:87], 13, v[84:85]
	v_lshlrev_b64 v[90:91], 12, v[84:85]
	v_lshl_add_u64 v[84:85], s[2:3], 0, v[86:87]
	v_lshl_add_u64 v[86:87], v[84:85], 0, v[132:133]
	v_lshl_add_u64 v[84:85], v[86:87], 0, s[20:21]
	v_add_co_u32_e32 v86, vcc, s76, v86
	s_nop 1
	v_addc_co_u32_e32 v87, vcc, 0, v87, vcc
	s_waitcnt vmcnt(21)
	s_nop 1
	v_mov_b64_e32 v[86:87], v[220:221]
	v_mov_b64_e32 v[88:89], v[222:223]
	v_lshlrev_b32_e32 v92, 16, v86
	v_and_b32_e32 v93, 0xffff0000, v86
	v_lshlrev_b32_e32 v94, 16, v87
	v_and_b32_e32 v95, 0xffff0000, v87
	v_lshl_add_u64 v[86:87], s[12:13], 0, v[90:91]
	v_lshl_add_u64 v[90:91], v[86:87], 0, v[132:133]
	v_lshlrev_b32_e32 v96, 16, v88
	v_and_b32_e32 v97, 0xffff0000, v88
	v_lshlrev_b32_e32 v98, 16, v89
	v_and_b32_e32 v99, 0xffff0000, v89
	s_waitcnt vmcnt(20)
	s_nop 1
	v_mov_b64_e32 v[86:87], v[224:225]
	v_mov_b64_e32 v[88:89], v[226:227]
	v_lshlrev_b32_e32 v100, 16, v86
	v_fmac_f32_e32 v100, v80, v92
	v_and_b32_e32 v80, 0xffff0000, v86
	v_fmac_f32_e32 v80, v81, v93
	v_lshlrev_b32_e32 v81, 16, v87
	v_fmac_f32_e32 v81, v82, v94
	v_and_b32_e32 v82, 0xffff0000, v87
	v_fmac_f32_e32 v82, v83, v95
	v_lshlrev_b32_e32 v83, 16, v88
	v_and_b32_e32 v86, 0xffff0000, v88
	v_lshlrev_b32_e32 v87, 16, v89
	v_and_b32_e32 v88, 0xffff0000, v89
	v_fmac_f32_e32 v83, v76, v96
	v_fmac_f32_e32 v86, v77, v97
	v_fmac_f32_e32 v87, v78, v98
	v_fmac_f32_e32 v88, v79, v99
	v_cvt_pk_bf16_f32 v76, v100, v80
	v_cvt_pk_bf16_f32 v77, v81, v82
	v_cvt_pk_bf16_f32 v78, v83, v86
	v_cvt_pk_bf16_f32 v79, v87, v88
	global_store_dwordx4 v[90:91], v[76:79], off
	s_waitcnt vmcnt(20)
	s_nop 1
	v_mov_b64_e32 v[76:77], v[228:229]
	v_mov_b64_e32 v[78:79], v[230:231]
	v_lshlrev_b32_e32 v80, 16, v76
	v_and_b32_e32 v81, 0xffff0000, v76
	v_lshlrev_b32_e32 v82, 16, v77
	v_and_b32_e32 v83, 0xffff0000, v77
	v_lshlrev_b32_e32 v84, 16, v78
	v_and_b32_e32 v85, 0xffff0000, v78
	v_lshlrev_b32_e32 v86, 16, v79
	v_and_b32_e32 v87, 0xffff0000, v79
	s_waitcnt vmcnt(19)
	s_nop 1
	v_mov_b64_e32 v[76:77], v[232:233]
	v_mov_b64_e32 v[78:79], v[234:235]
	v_lshlrev_b32_e32 v88, 16, v76
	v_fmac_f32_e32 v88, v72, v80
	v_and_b32_e32 v72, 0xffff0000, v76
	v_fmac_f32_e32 v72, v73, v81
	v_lshlrev_b32_e32 v73, 16, v77
	v_fmac_f32_e32 v73, v74, v82
	v_and_b32_e32 v74, 0xffff0000, v77
	v_fmac_f32_e32 v74, v75, v83
	v_lshlrev_b32_e32 v75, 16, v78
	v_fmac_f32_e32 v75, v68, v84
	v_and_b32_e32 v76, 0xffff0000, v78
	v_lshlrev_b32_e32 v77, 16, v79
	v_and_b32_e32 v78, 0xffff0000, v79
	v_cvt_pk_bf16_f32 v68, v88, v72
	v_fmac_f32_e32 v76, v69, v85
	v_fmac_f32_e32 v77, v70, v86
	v_fmac_f32_e32 v78, v71, v87
	v_cvt_pk_bf16_f32 v69, v73, v74
	v_cvt_pk_bf16_f32 v70, v75, v76
	v_cvt_pk_bf16_f32 v71, v77, v78
	global_store_dwordx4 v[90:91], v[68:71], off offset:256
	v_add_u32_e32 v237, 0x160000, v236
	v_add_u32_e32 v239, 0xb0000, v238
	global_load_dwordx4 v[220:223], v237, s[2:3]
	global_load_dwordx4 v[224:227], v239, s[12:13]
	global_load_dwordx4 v[228:231], v237, s[2:3] offset:256
	global_load_dwordx4 v[232:235], v239, s[12:13] offset:256
	s_nop 1
	v_add_u32_e32 v68, 0x80, v134
	v_ashrrev_i32_e32 v69, 31, v68
	v_lshlrev_b64 v[70:71], 13, v[68:69]
	v_lshlrev_b64 v[74:75], 12, v[68:69]
	v_lshl_add_u64 v[68:69], s[2:3], 0, v[70:71]
	v_lshl_add_u64 v[70:71], v[68:69], 0, v[132:133]
	v_lshl_add_u64 v[68:69], v[70:71], 0, s[20:21]
	v_add_co_u32_e32 v70, vcc, s76, v70
	s_nop 1
	v_addc_co_u32_e32 v71, vcc, 0, v71, vcc
	s_waitcnt vmcnt(21)
	s_nop 1
	v_mov_b64_e32 v[70:71], v[172:173]
	v_mov_b64_e32 v[72:73], v[174:175]
	v_lshlrev_b32_e32 v76, 16, v70
	v_and_b32_e32 v77, 0xffff0000, v70
	v_lshlrev_b32_e32 v78, 16, v71
	v_and_b32_e32 v79, 0xffff0000, v71
	v_lshl_add_u64 v[70:71], s[12:13], 0, v[74:75]
	v_lshl_add_u64 v[74:75], v[70:71], 0, v[132:133]
	v_lshlrev_b32_e32 v80, 16, v72
	v_and_b32_e32 v81, 0xffff0000, v72
	v_lshlrev_b32_e32 v82, 16, v73
	v_and_b32_e32 v83, 0xffff0000, v73
	s_waitcnt vmcnt(20)
	s_nop 1
	v_mov_b64_e32 v[70:71], v[176:177]
	v_mov_b64_e32 v[72:73], v[178:179]
	v_lshlrev_b32_e32 v84, 16, v70
	v_fmac_f32_e32 v84, v64, v76
	v_and_b32_e32 v64, 0xffff0000, v70
	v_fmac_f32_e32 v64, v65, v77
	v_lshlrev_b32_e32 v65, 16, v71
	v_fmac_f32_e32 v65, v66, v78
	v_and_b32_e32 v66, 0xffff0000, v71
	v_fmac_f32_e32 v66, v67, v79
	v_lshlrev_b32_e32 v67, 16, v72
	v_and_b32_e32 v70, 0xffff0000, v72
	v_lshlrev_b32_e32 v71, 16, v73
	v_and_b32_e32 v72, 0xffff0000, v73
	v_fmac_f32_e32 v67, v60, v80
	v_fmac_f32_e32 v70, v61, v81
	v_fmac_f32_e32 v71, v62, v82
	v_fmac_f32_e32 v72, v63, v83
	v_cvt_pk_bf16_f32 v60, v84, v64
	v_cvt_pk_bf16_f32 v61, v65, v66
	v_cvt_pk_bf16_f32 v62, v67, v70
	v_cvt_pk_bf16_f32 v63, v71, v72
	global_store_dwordx4 v[74:75], v[60:63], off
	s_waitcnt vmcnt(20)
; __device__ __forceinline__ unsigned cvt_pk_bf16(float lo, float hi) { unsigned r; asm volatile("v_cvt_pk_bf16_f32 %0, %1, %2" : "=v"(r) : "v"(lo), "v"(hi)); return r; }
; #define LAS __attribute__((address_space(3)))
; __device__ __forceinline__ float bflo(unsigned w) { return __uint_as_float(w << 16); }
; __device__ __forceinline__ float bfhi(unsigned w) { return __uint_as_float(w & 0xffff0000u); }
;     __device__ __forceinline__ void operator()(const f32x4 (&acc)[2][2][4][2], const Unit& u, int wr, int wc, int fr, int fq, const LAS float*) const {
;         const int row0 = u.pm * 256 + wr * 64 + fr, col0 = u.pn * 256 + wc * 32 + 8 * fq;
; #pragma unroll
;         for (int ai = 0; ai < 2; ++ai)
; #pragma unroll
;             for (int m = 0; m < 4; ++m) { const size_t row = (size_t)(row0 + ai * 128 + m * 16);
; #pragma unroll
;                 for (int bj = 0; bj < 2; ++bj) { const int col = col0 + bj * 128;
;                     const u32x4 g = *(const u32x4*)(G + row * NGATE + MODE * DM + col);
;                     f32x4 v0 = acc[ai][bj][m][0], v1 = acc[ai][bj][m][1];
;                     v0[0] *= bflo(g.x); v0[1] *= bfhi(g.x); v0[2] *= bflo(g.y); v0[3] *= bfhi(g.y); v1[0] *= bflo(g.z); v1[1] *= bfhi(g.z); v1[2] *= bflo(g.w); v1[3] *= bfhi(g.w);
;                     bf16_t* tp = T + row * DM + col;
;                     if (MODE == 1) { const u32x4 t = *(const u32x4*)tp;
;                         v0[0] += bflo(t.x); v0[1] += bfhi(t.x); v0[2] += bflo(t.y); v0[3] += bfhi(t.y); v1[0] += bflo(t.z); v1[1] += bfhi(t.z); v1[2] += bflo(t.w); v1[3] += bfhi(t.w); }
;                     u32x4 w; w.x = cvt_pk_bf16(v0[0], v0[1]); w.y = cvt_pk_bf16(v0[2], v0[3]); w.z = cvt_pk_bf16(v1[0], v1[1]); w.w = cvt_pk_bf16(v1[2], v1[3]);
;                     *(u32x4*)tp = w; } }
	s_nop 1
	v_mov_b64_e32 v[60:61], v[180:181]
	v_mov_b64_e32 v[62:63], v[182:183]
	v_lshlrev_b32_e32 v64, 16, v60
	v_and_b32_e32 v65, 0xffff0000, v60
	v_lshlrev_b32_e32 v66, 16, v61
	v_and_b32_e32 v67, 0xffff0000, v61
	v_lshlrev_b32_e32 v68, 16, v62
	v_and_b32_e32 v69, 0xffff0000, v62
	v_lshlrev_b32_e32 v70, 16, v63
	v_and_b32_e32 v71, 0xffff0000, v63
	s_waitcnt vmcnt(19)
	s_nop 1
	v_mov_b64_e32 v[60:61], v[184:185]
	v_mov_b64_e32 v[62:63], v[186:187]
	v_lshlrev_b32_e32 v72, 16, v60
	v_fmac_f32_e32 v72, v56, v64
	v_and_b32_e32 v56, 0xffff0000, v60
	v_fmac_f32_e32 v56, v57, v65
	v_lshlrev_b32_e32 v57, 16, v61
	v_fmac_f32_e32 v57, v58, v66
	v_and_b32_e32 v58, 0xffff0000, v61
	v_fmac_f32_e32 v58, v59, v67
	v_lshlrev_b32_e32 v59, 16, v62
	v_fmac_f32_e32 v59, v52, v68
	v_and_b32_e32 v60, 0xffff0000, v62
	v_lshlrev_b32_e32 v61, 16, v63
	v_and_b32_e32 v62, 0xffff0000, v63
	v_cvt_pk_bf16_f32 v52, v72, v56
	v_fmac_f32_e32 v60, v53, v69
	v_fmac_f32_e32 v61, v54, v70
	v_fmac_f32_e32 v62, v55, v71
	v_cvt_pk_bf16_f32 v53, v57, v58
	v_cvt_pk_bf16_f32 v54, v59, v60
	v_cvt_pk_bf16_f32 v55, v61, v62
	global_store_dwordx4 v[74:75], v[52:55], off offset:256
	s_nop 1
	v_add_u32_e32 v52, 0x90, v134
	v_ashrrev_i32_e32 v53, 31, v52
	v_lshlrev_b64 v[54:55], 13, v[52:53]
	v_lshlrev_b64 v[58:59], 12, v[52:53]
	v_lshl_add_u64 v[52:53], s[2:3], 0, v[54:55]
	v_lshl_add_u64 v[54:55], v[52:53], 0, v[132:133]
	v_lshl_add_u64 v[52:53], v[54:55], 0, s[20:21]
	v_add_co_u32_e32 v54, vcc, s76, v54
	s_nop 1
	v_addc_co_u32_e32 v55, vcc, 0, v55, vcc
	s_waitcnt vmcnt(17)
	s_nop 1
	v_mov_b64_e32 v[54:55], v[188:189]
	v_mov_b64_e32 v[56:57], v[190:191]
	v_lshlrev_b32_e32 v60, 16, v54
	v_and_b32_e32 v61, 0xffff0000, v54
	v_lshlrev_b32_e32 v62, 16, v55
	v_and_b32_e32 v63, 0xffff0000, v55
	v_lshl_add_u64 v[54:55], s[12:13], 0, v[58:59]
	v_lshl_add_u64 v[58:59], v[54:55], 0, v[132:133]
	v_lshlrev_b32_e32 v64, 16, v56
	v_and_b32_e32 v65, 0xffff0000, v56
	v_lshlrev_b32_e32 v66, 16, v57
	v_and_b32_e32 v67, 0xffff0000, v57
	s_waitcnt vmcnt(16)
	s_nop 1
	v_mov_b64_e32 v[54:55], v[192:193]
	v_mov_b64_e32 v[56:57], v[194:195]
	v_lshlrev_b32_e32 v68, 16, v54
	v_fmac_f32_e32 v68, v48, v60
	v_and_b32_e32 v48, 0xffff0000, v54
	v_fmac_f32_e32 v48, v49, v61
	v_lshlrev_b32_e32 v49, 16, v55
	v_fmac_f32_e32 v49, v50, v62
	v_and_b32_e32 v50, 0xffff0000, v55
	v_fmac_f32_e32 v50, v51, v63
	v_lshlrev_b32_e32 v51, 16, v56
	v_and_b32_e32 v54, 0xffff0000, v56
	v_lshlrev_b32_e32 v55, 16, v57
	v_and_b32_e32 v56, 0xffff0000, v57
	v_fmac_f32_e32 v51, v44, v64
	v_fmac_f32_e32 v54, v45, v65
	v_fmac_f32_e32 v55, v46, v66
	v_fmac_f32_e32 v56, v47, v67
	v_cvt_pk_bf16_f32 v44, v68, v48
	v_cvt_pk_bf16_f32 v45, v49, v50
	v_cvt_pk_bf16_f32 v46, v51, v54
	v_cvt_pk_bf16_f32 v47, v55, v56
	global_store_dwordx4 v[58:59], v[44:47], off
	s_waitcnt vmcnt(16)
	s_nop 1
	v_mov_b64_e32 v[44:45], v[196:197]
	v_mov_b64_e32 v[46:47], v[198:199]
	v_lshlrev_b32_e32 v48, 16, v44
	v_and_b32_e32 v49, 0xffff0000, v44
	v_lshlrev_b32_e32 v50, 16, v45
	v_and_b32_e32 v51, 0xffff0000, v45
	v_lshlrev_b32_e32 v52, 16, v46
	v_and_b32_e32 v53, 0xffff0000, v46
	v_lshlrev_b32_e32 v54, 16, v47
	v_and_b32_e32 v55, 0xffff0000, v47
	s_waitcnt vmcnt(15)
	s_nop 1
	v_mov_b64_e32 v[44:45], v[200:201]
	v_mov_b64_e32 v[46:47], v[202:203]
	v_lshlrev_b32_e32 v56, 16, v44
	v_fmac_f32_e32 v56, v40, v48
	v_and_b32_e32 v40, 0xffff0000, v44
	v_fmac_f32_e32 v40, v41, v49
	v_lshlrev_b32_e32 v41, 16, v45
	v_fmac_f32_e32 v41, v42, v50
	v_and_b32_e32 v42, 0xffff0000, v45
	v_fmac_f32_e32 v42, v43, v51
	v_lshlrev_b32_e32 v43, 16, v46
	v_fmac_f32_e32 v43, v36, v52
	v_and_b32_e32 v44, 0xffff0000, v46
	v_lshlrev_b32_e32 v45, 16, v47
	v_and_b32_e32 v46, 0xffff0000, v47
	v_cvt_pk_bf16_f32 v36, v56, v40
	v_fmac_f32_e32 v44, v37, v53
	v_fmac_f32_e32 v45, v38, v54
	v_fmac_f32_e32 v46, v39, v55
	v_cvt_pk_bf16_f32 v37, v41, v42
	v_cvt_pk_bf16_f32 v38, v43, v44
	v_cvt_pk_bf16_f32 v39, v45, v46
	global_store_dwordx4 v[58:59], v[36:39], off offset:256
	s_nop 1
	v_add_u32_e32 v36, 0xa0, v134
	v_ashrrev_i32_e32 v37, 31, v36
	v_lshlrev_b64 v[38:39], 13, v[36:37]
	v_lshlrev_b64 v[42:43], 12, v[36:37]
	v_lshl_add_u64 v[36:37], s[2:3], 0, v[38:39]
	v_lshl_add_u64 v[38:39], v[36:37], 0, v[132:133]
	v_lshl_add_u64 v[36:37], v[38:39], 0, s[20:21]
	v_add_co_u32_e32 v38, vcc, s76, v38
	s_nop 1
	v_addc_co_u32_e32 v39, vcc, 0, v39, vcc
	s_waitcnt vmcnt(13)
	s_nop 1
	v_mov_b64_e32 v[38:39], v[204:205]
	v_mov_b64_e32 v[40:41], v[206:207]
	v_lshlrev_b32_e32 v44, 16, v38
	v_and_b32_e32 v45, 0xffff0000, v38
	v_lshlrev_b32_e32 v46, 16, v39
	v_and_b32_e32 v47, 0xffff0000, v39
	v_lshl_add_u64 v[38:39], s[12:13], 0, v[42:43]
	v_lshl_add_u64 v[42:43], v[38:39], 0, v[132:133]
	v_lshlrev_b32_e32 v48, 16, v40
	v_and_b32_e32 v49, 0xffff0000, v40
	v_lshlrev_b32_e32 v50, 16, v41
	v_and_b32_e32 v51, 0xffff0000, v41
	s_waitcnt vmcnt(12)
; __device__ __forceinline__ unsigned cvt_pk_bf16(float lo, float hi) { unsigned r; asm volatile("v_cvt_pk_bf16_f32 %0, %1, %2" : "=v"(r) : "v"(lo), "v"(hi)); return r; }
; #define LAS __attribute__((address_space(3)))
; __device__ __forceinline__ float bflo(unsigned w) { return __uint_as_float(w << 16); }
; __device__ __forceinline__ float bfhi(unsigned w) { return __uint_as_float(w & 0xffff0000u); }
;     __device__ __forceinline__ void operator()(const f32x4 (&acc)[2][2][4][2], const Unit& u, int wr, int wc, int fr, int fq, const LAS float*) const {
;         const int row0 = u.pm * 256 + wr * 64 + fr, col0 = u.pn * 256 + wc * 32 + 8 * fq;
; #pragma unroll
;         for (int ai = 0; ai < 2; ++ai)
; #pragma unroll
;             for (int m = 0; m < 4; ++m) { const size_t row = (size_t)(row0 + ai * 128 + m * 16);
; #pragma unroll
;                 for (int bj = 0; bj < 2; ++bj) { const int col = col0 + bj * 128;
;                     const u32x4 g = *(const u32x4*)(G + row * NGATE + MODE * DM + col);
;                     f32x4 v0 = acc[ai][bj][m][0], v1 = acc[ai][bj][m][1];
;                     v0[0] *= bflo(g.x); v0[1] *= bfhi(g.x); v0[2] *= bflo(g.y); v0[3] *= bfhi(g.y); v1[0] *= bflo(g.z); v1[1] *= bfhi(g.z); v1[2] *= bflo(g.w); v1[3] *= bfhi(g.w);
;                     bf16_t* tp = T + row * DM + col;
;                     if (MODE == 1) { const u32x4 t = *(const u32x4*)tp;
;                         v0[0] += bflo(t.x); v0[1] += bfhi(t.x); v0[2] += bflo(t.y); v0[3] += bfhi(t.y); v1[0] += bflo(t.z); v1[1] += bfhi(t.z); v1[2] += bflo(t.w); v1[3] += bfhi(t.w); }
;                     u32x4 w; w.x = cvt_pk_bf16(v0[0], v0[1]); w.y = cvt_pk_bf16(v0[2], v0[3]); w.z = cvt_pk_bf16(v1[0], v1[1]); w.w = cvt_pk_bf16(v1[2], v1[3]);
;                     *(u32x4*)tp = w; } }
	s_nop 1
	v_mov_b64_e32 v[38:39], v[208:209]
	v_mov_b64_e32 v[40:41], v[210:211]
	v_lshlrev_b32_e32 v52, 16, v38
	v_fmac_f32_e32 v52, v32, v44
	v_and_b32_e32 v32, 0xffff0000, v38
	v_fmac_f32_e32 v32, v33, v45
	v_lshlrev_b32_e32 v33, 16, v39
	v_fmac_f32_e32 v33, v34, v46
	v_and_b32_e32 v34, 0xffff0000, v39
	v_fmac_f32_e32 v34, v35, v47
	v_lshlrev_b32_e32 v35, 16, v40
	v_and_b32_e32 v38, 0xffff0000, v40
	v_lshlrev_b32_e32 v39, 16, v41
	v_and_b32_e32 v40, 0xffff0000, v41
	v_fmac_f32_e32 v35, v28, v48
	v_fmac_f32_e32 v38, v29, v49
	v_fmac_f32_e32 v39, v30, v50
	v_fmac_f32_e32 v40, v31, v51
	v_cvt_pk_bf16_f32 v28, v52, v32
	v_cvt_pk_bf16_f32 v29, v33, v34
	v_cvt_pk_bf16_f32 v30, v35, v38
	v_cvt_pk_bf16_f32 v31, v39, v40
	global_store_dwordx4 v[42:43], v[28:31], off
	s_waitcnt vmcnt(12)
	s_nop 1
	v_mov_b64_e32 v[28:29], v[212:213]
	v_mov_b64_e32 v[30:31], v[214:215]
	v_lshlrev_b32_e32 v32, 16, v28
	v_and_b32_e32 v33, 0xffff0000, v28
	v_lshlrev_b32_e32 v34, 16, v29
	v_and_b32_e32 v35, 0xffff0000, v29
	v_lshlrev_b32_e32 v36, 16, v30
	v_and_b32_e32 v37, 0xffff0000, v30
	v_lshlrev_b32_e32 v38, 16, v31
	v_and_b32_e32 v39, 0xffff0000, v31
	s_waitcnt vmcnt(11)
	s_nop 1
	v_mov_b64_e32 v[28:29], v[216:217]
	v_mov_b64_e32 v[30:31], v[218:219]
	v_lshlrev_b32_e32 v40, 16, v28
	v_fmac_f32_e32 v40, v24, v32
	v_and_b32_e32 v24, 0xffff0000, v28
	v_fmac_f32_e32 v24, v25, v33
	v_lshlrev_b32_e32 v25, 16, v29
	v_fmac_f32_e32 v25, v26, v34
	v_and_b32_e32 v26, 0xffff0000, v29
	v_fmac_f32_e32 v26, v27, v35
	v_lshlrev_b32_e32 v27, 16, v30
	v_fmac_f32_e32 v27, v20, v36
	v_and_b32_e32 v28, 0xffff0000, v30
	v_lshlrev_b32_e32 v29, 16, v31
	v_and_b32_e32 v30, 0xffff0000, v31
	v_cvt_pk_bf16_f32 v20, v40, v24
	v_fmac_f32_e32 v28, v21, v37
	v_fmac_f32_e32 v29, v22, v38
	v_fmac_f32_e32 v30, v23, v39
	v_cvt_pk_bf16_f32 v21, v25, v26
	v_cvt_pk_bf16_f32 v22, v27, v28
	v_cvt_pk_bf16_f32 v23, v29, v30
	global_store_dwordx4 v[42:43], v[20:23], off offset:256
	s_nop 1
	v_add_u32_e32 v20, 0xb0, v134
	v_ashrrev_i32_e32 v21, 31, v20
	v_lshlrev_b64 v[22:23], 13, v[20:21]
	v_lshlrev_b64 v[26:27], 12, v[20:21]
	v_lshl_add_u64 v[20:21], s[2:3], 0, v[22:23]
	v_lshl_add_u64 v[22:23], v[20:21], 0, v[132:133]
	v_lshl_add_u64 v[20:21], v[22:23], 0, s[20:21]
	v_add_co_u32_e32 v22, vcc, s76, v22
	s_mov_b64 s[20:21], s[16:17]
	s_nop 0
	v_addc_co_u32_e32 v23, vcc, 0, v23, vcc
	s_andn2_b64 vcc, exec, s[6:7]
	s_waitcnt vmcnt(9)
	s_nop 1
	v_mov_b64_e32 v[22:23], v[220:221]
	v_mov_b64_e32 v[24:25], v[222:223]
	v_lshlrev_b32_e32 v28, 16, v22
	v_and_b32_e32 v29, 0xffff0000, v22
	v_lshlrev_b32_e32 v30, 16, v23
	v_and_b32_e32 v31, 0xffff0000, v23
	v_lshl_add_u64 v[22:23], s[12:13], 0, v[26:27]
	v_lshl_add_u64 v[26:27], v[22:23], 0, v[132:133]
	v_lshlrev_b32_e32 v32, 16, v24
	v_and_b32_e32 v33, 0xffff0000, v24
	v_lshlrev_b32_e32 v34, 16, v25
	v_and_b32_e32 v35, 0xffff0000, v25
	s_waitcnt vmcnt(8)
	s_nop 1
	v_mov_b64_e32 v[22:23], v[224:225]
	v_mov_b64_e32 v[24:25], v[226:227]
	v_lshlrev_b32_e32 v36, 16, v22
	v_fmac_f32_e32 v36, v16, v28
	v_and_b32_e32 v16, 0xffff0000, v22
	v_fmac_f32_e32 v16, v17, v29
	v_lshlrev_b32_e32 v17, 16, v23
	v_fmac_f32_e32 v17, v18, v30
	v_and_b32_e32 v18, 0xffff0000, v23
	v_fmac_f32_e32 v18, v19, v31
	v_lshlrev_b32_e32 v19, 16, v24
	v_and_b32_e32 v22, 0xffff0000, v24
	v_lshlrev_b32_e32 v23, 16, v25
	v_and_b32_e32 v24, 0xffff0000, v25
	v_fmac_f32_e32 v19, v12, v32
	v_fmac_f32_e32 v22, v13, v33
	v_fmac_f32_e32 v23, v14, v34
	v_fmac_f32_e32 v24, v15, v35
	v_cvt_pk_bf16_f32 v12, v36, v16
	v_cvt_pk_bf16_f32 v13, v17, v18
	v_cvt_pk_bf16_f32 v14, v19, v22
	v_cvt_pk_bf16_f32 v15, v23, v24
	global_store_dwordx4 v[26:27], v[12:15], off
	s_waitcnt vmcnt(8)
	s_nop 1
	v_mov_b64_e32 v[12:13], v[228:229]
	v_mov_b64_e32 v[14:15], v[230:231]
	v_lshlrev_b32_e32 v16, 16, v12
	v_and_b32_e32 v17, 0xffff0000, v12
	v_lshlrev_b32_e32 v18, 16, v13
	v_and_b32_e32 v19, 0xffff0000, v13
	v_lshlrev_b32_e32 v20, 16, v14
	v_and_b32_e32 v21, 0xffff0000, v14
	v_lshlrev_b32_e32 v22, 16, v15
	v_and_b32_e32 v23, 0xffff0000, v15
	s_waitcnt vmcnt(7)
	s_nop 1
	v_mov_b64_e32 v[12:13], v[232:233]
	v_mov_b64_e32 v[14:15], v[234:235]
	v_lshlrev_b32_e32 v24, 16, v12
	v_fmac_f32_e32 v24, v4, v16
	v_and_b32_e32 v4, 0xffff0000, v12
	v_fmac_f32_e32 v4, v5, v17
	v_lshlrev_b32_e32 v5, 16, v13
	v_fmac_f32_e32 v5, v6, v18
	v_and_b32_e32 v6, 0xffff0000, v13
	v_fmac_f32_e32 v6, v7, v19
	v_lshlrev_b32_e32 v7, 16, v14
	v_fmac_f32_e32 v7, v8, v20
	v_and_b32_e32 v8, 0xffff0000, v14
	v_fmac_f32_e32 v8, v9, v21
	v_lshlrev_b32_e32 v9, 16, v15
	v_fmac_f32_e32 v9, v10, v22
	v_and_b32_e32 v10, 0xffff0000, v15
	v_fmac_f32_e32 v10, v11, v23
	v_cvt_pk_bf16_f32 v4, v24, v4
	v_cvt_pk_bf16_f32 v5, v5, v6
	v_cvt_pk_bf16_f32 v6, v7, v8
	v_cvt_pk_bf16_f32 v7, v9, v10
	global_store_dwordx4 v[26:27], v[4:7], off offset:256
	s_cbranch_vccnz .LBB0_164
	s_waitcnt vmcnt(0) lgkmcnt(0)
	s_barrier

; template <class Epi, class Sched>
; __device__ __forceinline__ void gemm_simple(PG8_LAS unsigned char* lds, const Gemm g, const Sched& S, const Epi& E, int wave_s) {
;     ...
;         for (; t < nt; t += 2) {
;             const bool last = (t == nt - 2);
;             PG8_TILE(0, cA + (size_t)(t + 1) * kstep, cB + (size_t)(t + 1) * kstep, true);
;             const char* a2 = last ? nA : cA + (size_t)(t + 2) * kstep; const char* b2 = last ? nB : cB + (size_t)(t + 2) * kstep;
;             PG8_TILE(1, a2, b2, (!last || has_next));
.LBB0_195:
	s_waitcnt vmcnt(2) lgkmcnt(0)
	s_barrier
	ds_read_b128 v[146:149], v132
	ds_read_b128 v[174:177], v152
	ds_read_b128 v[158:161], v132 offset:2048
	ds_read_b128 v[182:185], v152 offset:2048
	ds_read_b128 v[190:193], v152 offset:4096
	s_add_u32 s58, s18, s57
	s_addc_u32 s59, s19, 0
	s_add_u32 s24, s58, 0x80
	s_addc_u32 s25, s59, 0
	s_mov_b32 m0, s43
	s_nop 0
	global_load_lds_dwordx4 v137, s[24:25]
	s_mov_b32 m0, s47
	s_nop 0
	global_load_lds_dwordx4 v139, s[24:25]
	s_waitcnt lgkmcnt(3)
	v_mfma_f32_16x16x32_bf16 v[128:131], v[146:149], v[174:177], v[128:131]
	s_waitcnt lgkmcnt(2)
	v_mfma_f32_16x16x32_bf16 v[124:127], v[158:161], v[174:177], v[124:127]
	ds_read_b128 v[198:201], v152 offset:6144
	s_waitcnt lgkmcnt(2)
	v_mfma_f32_16x16x32_bf16 v[112:115], v[146:149], v[182:185], v[112:115]
	v_mfma_f32_16x16x32_bf16 v[108:111], v[158:161], v[182:185], v[108:111]
	ds_read_b128 v[154:157], v132 offset:1024
	ds_read_b128 v[178:181], v152 offset:1024
	s_waitcnt lgkmcnt(3)
	v_mfma_f32_16x16x32_bf16 v[96:99], v[146:149], v[190:193], v[96:99]
	ds_read_b128 v[170:173], v132 offset:3072
	v_mfma_f32_16x16x32_bf16 v[92:95], v[158:161], v[190:193], v[92:95]
	ds_read_b128 v[186:189], v152 offset:3072
	s_waitcnt lgkmcnt(4)
	v_mfma_f32_16x16x32_bf16 v[80:83], v[146:149], v[198:201], v[80:83]
	v_mfma_f32_16x16x32_bf16 v[76:79], v[158:161], v[198:201], v[76:79]
	ds_read_b128 v[194:197], v152 offset:5120
	s_waitcnt lgkmcnt(3)
	v_mfma_f32_16x16x32_bf16 v[128:131], v[154:157], v[178:181], v[128:131]
	s_waitcnt lgkmcnt(2)
	v_mfma_f32_16x16x32_bf16 v[124:127], v[170:173], v[178:181], v[124:127]
	ds_read_b128 v[202:205], v152 offset:7168
	s_waitcnt lgkmcnt(2)
	v_mfma_f32_16x16x32_bf16 v[112:115], v[154:157], v[186:189], v[112:115]
	v_mfma_f32_16x16x32_bf16 v[108:111], v[170:173], v[186:189], v[108:111]
	ds_read_b128 v[206:209], v133
	s_waitcnt lgkmcnt(2)
	v_mfma_f32_16x16x32_bf16 v[96:99], v[154:157], v[194:197], v[96:99]
	ds_read_b128 v[214:217], v133 offset:2048
	v_mfma_f32_16x16x32_bf16 v[92:95], v[170:173], v[194:197], v[92:95]
	s_waitcnt lgkmcnt(2)
	v_mfma_f32_16x16x32_bf16 v[80:83], v[154:157], v[202:205], v[80:83]
	v_mfma_f32_16x16x32_bf16 v[76:79], v[170:173], v[202:205], v[76:79]
	s_add_u32 s60, s20, s57
	s_addc_u32 s61, s21, 0
	s_add_u32 s24, s60, 0x80
	s_addc_u32 s25, s61, 0
	s_mov_b32 m0, s44
	s_nop 0
	global_load_lds_dwordx4 v136, s[24:25]
	s_mov_b32 m0, s48
	s_nop 0
	global_load_lds_dwordx4 v138, s[24:25]
	s_waitcnt lgkmcnt(1)
	v_mfma_f32_16x16x32_bf16 v[120:123], v[206:209], v[174:177], v[120:123]
	s_waitcnt lgkmcnt(0)
	v_mfma_f32_16x16x32_bf16 v[116:119], v[214:217], v[174:177], v[116:119]
	v_mfma_f32_16x16x32_bf16 v[104:107], v[206:209], v[182:185], v[104:107]
	v_mfma_f32_16x16x32_bf16 v[100:103], v[214:217], v[182:185], v[100:103]
	ds_read_b128 v[210:213], v133 offset:1024
	v_mfma_f32_16x16x32_bf16 v[88:91], v[206:209], v[190:193], v[88:91]
	ds_read_b128 v[218:221], v133 offset:3072
	v_mfma_f32_16x16x32_bf16 v[84:87], v[214:217], v[190:193], v[84:87]
	v_mfma_f32_16x16x32_bf16 v[72:75], v[206:209], v[198:201], v[72:75]
	v_mfma_f32_16x16x32_bf16 v[68:71], v[214:217], v[198:201], v[68:71]
	s_waitcnt lgkmcnt(1)
	v_mfma_f32_16x16x32_bf16 v[120:123], v[210:213], v[178:181], v[120:123]
	s_waitcnt lgkmcnt(0)
	v_mfma_f32_16x16x32_bf16 v[116:119], v[218:221], v[178:181], v[116:119]
	v_mfma_f32_16x16x32_bf16 v[104:107], v[210:213], v[186:189], v[104:107]
	v_mfma_f32_16x16x32_bf16 v[100:103], v[218:221], v[186:189], v[100:103]
	v_mfma_f32_16x16x32_bf16 v[88:91], v[210:213], v[194:197], v[88:91]
	v_mfma_f32_16x16x32_bf16 v[84:87], v[218:221], v[194:197], v[84:87]
	v_mfma_f32_16x16x32_bf16 v[72:75], v[210:213], v[202:205], v[72:75]
	v_mfma_f32_16x16x32_bf16 v[68:71], v[218:221], v[202:205], v[68:71]
	s_waitcnt vmcnt(4) lgkmcnt(0)
	s_barrier
	ds_read_b128 v[174:177], v152 offset:16384
	ds_read_b128 v[182:185], v152 offset:18432
	ds_read_b128 v[190:193], v152 offset:20480
	s_add_u32 s24, s58, 0x20080
	s_addc_u32 s25, s59, 0
	s_mov_b32 m0, s45
	s_nop 0
	global_load_lds_dwordx4 v137, s[24:25]
	s_mov_b32 m0, s49
	s_nop 0
	global_load_lds_dwordx4 v139, s[24:25]
	s_waitcnt lgkmcnt(2)
	v_mfma_f32_16x16x32_bf16 v[64:67], v[146:149], v[174:177], v[64:67]
	v_mfma_f32_16x16x32_bf16 v[60:63], v[158:161], v[174:177], v[60:63]
	ds_read_b128 v[198:201], v152 offset:22528
	s_waitcnt lgkmcnt(2)
	v_mfma_f32_16x16x32_bf16 v[48:51], v[146:149], v[182:185], v[48:51]
	v_mfma_f32_16x16x32_bf16 v[44:47], v[158:161], v[182:185], v[44:47]
	ds_read_b128 v[178:181], v152 offset:17408
	s_waitcnt lgkmcnt(2)
	v_mfma_f32_16x16x32_bf16 v[32:35], v[146:149], v[190:193], v[32:35]
	v_mfma_f32_16x16x32_bf16 v[28:31], v[158:161], v[190:193], v[28:31]
	ds_read_b128 v[186:189], v152 offset:19456
	s_waitcnt lgkmcnt(2)
	v_mfma_f32_16x16x32_bf16 v[16:19], v[146:149], v[198:201], v[16:19]
	v_mfma_f32_16x16x32_bf16 v[12:15], v[158:161], v[198:201], v[12:15]
	ds_read_b128 v[194:197], v152 offset:21504
	s_waitcnt lgkmcnt(2)
	v_mfma_f32_16x16x32_bf16 v[64:67], v[154:157], v[178:181], v[64:67]
	v_mfma_f32_16x16x32_bf16 v[60:63], v[170:173], v[178:181], v[60:63]
	ds_read_b128 v[202:205], v152 offset:23552
	s_waitcnt lgkmcnt(2)
	v_mfma_f32_16x16x32_bf16 v[48:51], v[154:157], v[186:189], v[48:51]
	v_mfma_f32_16x16x32_bf16 v[44:47], v[170:173], v[186:189], v[44:47]
	s_waitcnt lgkmcnt(1)
	v_mfma_f32_16x16x32_bf16 v[32:35], v[154:157], v[194:197], v[32:35]
	v_mfma_f32_16x16x32_bf16 v[28:31], v[170:173], v[194:197], v[28:31]
	s_waitcnt lgkmcnt(0)
	v_mfma_f32_16x16x32_bf16 v[16:19], v[154:157], v[202:205], v[16:19]
	v_mfma_f32_16x16x32_bf16 v[12:15], v[170:173], v[202:205], v[12:15]
	s_add_u32 s24, s60, 0x20080
	s_addc_u32 s25, s61, 0
	s_mov_b32 m0, s46
	s_nop 0
	global_load_lds_dwordx4 v136, s[24:25]
	s_mov_b32 m0, s50
	s_nop 0
	global_load_lds_dwordx4 v138, s[24:25]
	v_mfma_f32_16x16x32_bf16 v[56:59], v[206:209], v[174:177], v[56:59]
	s_add_u32 s24, s60, 0x100
	s_addc_u32 s25, s61, 0
	s_add_u32 s58, s58, 0x100
	v_mfma_f32_16x16x32_bf16 v[52:55], v[214:217], v[174:177], v[52:55]
	s_addc_u32 s59, s59, 0
	v_mfma_f32_16x16x32_bf16 v[40:43], v[206:209], v[182:185], v[40:43]
	v_mfma_f32_16x16x32_bf16 v[36:39], v[214:217], v[182:185], v[36:39]
	v_mfma_f32_16x16x32_bf16 v[24:27], v[206:209], v[190:193], v[24:27]
	v_mfma_f32_16x16x32_bf16 v[20:23], v[214:217], v[190:193], v[20:23]
	v_mfma_f32_16x16x32_bf16 v[4:7], v[206:209], v[198:201], v[4:7]
	v_mfma_f32_16x16x32_bf16 v[8:11], v[214:217], v[198:201], v[8:11]
	v_mfma_f32_16x16x32_bf16 v[56:59], v[210:213], v[178:181], v[56:59]
	v_mfma_f32_16x16x32_bf16 v[52:55], v[218:221], v[178:181], v[52:55]
	v_mfma_f32_16x16x32_bf16 v[40:43], v[210:213], v[186:189], v[40:43]
	v_mfma_f32_16x16x32_bf16 v[36:39], v[218:221], v[186:189], v[36:39]
	v_mfma_f32_16x16x32_bf16 v[24:27], v[210:213], v[194:197], v[24:27]
	v_mfma_f32_16x16x32_bf16 v[20:23], v[218:221], v[194:197], v[20:23]
	v_mfma_f32_16x16x32_bf16 v[4:7], v[210:213], v[202:205], v[4:7]
	v_mfma_f32_16x16x32_bf16 v[8:11], v[218:221], v[202:205], v[8:11]
	s_waitcnt vmcnt(2) lgkmcnt(0)
	s_barrier
; template <class Epi, class Sched>
; __device__ __forceinline__ void gemm_simple(PG8_LAS unsigned char* lds, const Gemm g, const Sched& S, const Epi& E, int wave_s) {
;     ...
;         for (; t < nt; t += 2) {
;             const bool last = (t == nt - 2);
;             PG8_TILE(0, cA + (size_t)(t + 1) * kstep, cB + (size_t)(t + 1) * kstep, true);
;             const char* a2 = last ? nA : cA + (size_t)(t + 2) * kstep; const char* b2 = last ? nB : cB + (size_t)(t + 2) * kstep;
;             PG8_TILE(1, a2, b2, (!last || has_next));
	ds_read_b128 v[146:149], v134
	ds_read_b128 v[174:177], v152 offset:32768
	ds_read_b128 v[158:161], v134 offset:2048
	ds_read_b128 v[182:185], v152 offset:34816
	ds_read_b128 v[190:193], v152 offset:36864
	s_cmp_eq_u32 s57, s22
	s_cselect_b32 s25, s9, s25
	s_cselect_b32 s24, s54, s24
	s_cselect_b32 s59, s5, s59
	s_cselect_b32 s58, s55, s58
	s_mov_b32 m0, s36
	s_nop 0
	global_load_lds_dwordx4 v137, s[58:59]
	s_mov_b32 m0, s37
	s_nop 0
	global_load_lds_dwordx4 v139, s[58:59]
	s_waitcnt lgkmcnt(3)
	v_mfma_f32_16x16x32_bf16 v[128:131], v[146:149], v[174:177], v[128:131]
	s_waitcnt lgkmcnt(2)
	v_mfma_f32_16x16x32_bf16 v[124:127], v[158:161], v[174:177], v[124:127]
	ds_read_b128 v[198:201], v152 offset:38912
	s_waitcnt lgkmcnt(2)
	v_mfma_f32_16x16x32_bf16 v[112:115], v[146:149], v[182:185], v[112:115]
	v_mfma_f32_16x16x32_bf16 v[108:111], v[158:161], v[182:185], v[108:111]
	ds_read_b128 v[154:157], v134 offset:1024
	ds_read_b128 v[178:181], v152 offset:33792
	s_waitcnt lgkmcnt(3)
	v_mfma_f32_16x16x32_bf16 v[96:99], v[146:149], v[190:193], v[96:99]
	ds_read_b128 v[170:173], v134 offset:3072
	v_mfma_f32_16x16x32_bf16 v[92:95], v[158:161], v[190:193], v[92:95]
	ds_read_b128 v[186:189], v152 offset:35840
	s_waitcnt lgkmcnt(4)
	v_mfma_f32_16x16x32_bf16 v[80:83], v[146:149], v[198:201], v[80:83]
	v_mfma_f32_16x16x32_bf16 v[76:79], v[158:161], v[198:201], v[76:79]
	ds_read_b128 v[194:197], v152 offset:37888
	s_waitcnt lgkmcnt(3)
	v_mfma_f32_16x16x32_bf16 v[128:131], v[154:157], v[178:181], v[128:131]
	s_waitcnt lgkmcnt(2)
	v_mfma_f32_16x16x32_bf16 v[124:127], v[170:173], v[178:181], v[124:127]
	ds_read_b128 v[202:205], v152 offset:39936
	s_waitcnt lgkmcnt(2)
	v_mfma_f32_16x16x32_bf16 v[112:115], v[154:157], v[186:189], v[112:115]
	v_mfma_f32_16x16x32_bf16 v[108:111], v[170:173], v[186:189], v[108:111]
	ds_read_b128 v[206:209], v135
	s_waitcnt lgkmcnt(2)
	v_mfma_f32_16x16x32_bf16 v[96:99], v[154:157], v[194:197], v[96:99]
	ds_read_b128 v[214:217], v135 offset:2048
	v_mfma_f32_16x16x32_bf16 v[92:95], v[170:173], v[194:197], v[92:95]
	s_waitcnt lgkmcnt(2)
	v_mfma_f32_16x16x32_bf16 v[80:83], v[154:157], v[202:205], v[80:83]
	v_mfma_f32_16x16x32_bf16 v[76:79], v[170:173], v[202:205], v[76:79]
	s_mov_b32 m0, s17
	s_nop 0
	global_load_lds_dwordx4 v136, s[24:25]
	s_mov_b32 m0, s38
	s_nop 0
	global_load_lds_dwordx4 v138, s[24:25]
	s_waitcnt lgkmcnt(1)
	v_mfma_f32_16x16x32_bf16 v[120:123], v[206:209], v[174:177], v[120:123]
	s_waitcnt lgkmcnt(0)
	v_mfma_f32_16x16x32_bf16 v[116:119], v[214:217], v[174:177], v[116:119]
	v_mfma_f32_16x16x32_bf16 v[104:107], v[206:209], v[182:185], v[104:107]
	v_mfma_f32_16x16x32_bf16 v[100:103], v[214:217], v[182:185], v[100:103]
	ds_read_b128 v[210:213], v135 offset:1024
	v_mfma_f32_16x16x32_bf16 v[88:91], v[206:209], v[190:193], v[88:91]
	ds_read_b128 v[218:221], v135 offset:3072
	v_mfma_f32_16x16x32_bf16 v[84:87], v[214:217], v[190:193], v[84:87]
	v_mfma_f32_16x16x32_bf16 v[72:75], v[206:209], v[198:201], v[72:75]
	v_mfma_f32_16x16x32_bf16 v[68:71], v[214:217], v[198:201], v[68:71]
	s_waitcnt lgkmcnt(1)
	v_mfma_f32_16x16x32_bf16 v[120:123], v[210:213], v[178:181], v[120:123]
	s_waitcnt lgkmcnt(0)
	v_mfma_f32_16x16x32_bf16 v[116:119], v[218:221], v[178:181], v[116:119]
	v_mfma_f32_16x16x32_bf16 v[104:107], v[210:213], v[186:189], v[104:107]
	v_mfma_f32_16x16x32_bf16 v[100:103], v[218:221], v[186:189], v[100:103]
	v_mfma_f32_16x16x32_bf16 v[88:91], v[210:213], v[194:197], v[88:91]
	v_mfma_f32_16x16x32_bf16 v[84:87], v[218:221], v[194:197], v[84:87]
	v_mfma_f32_16x16x32_bf16 v[72:75], v[210:213], v[202:205], v[72:75]
	v_mfma_f32_16x16x32_bf16 v[68:71], v[218:221], v[202:205], v[68:71]
	s_waitcnt vmcnt(4) lgkmcnt(0)
	s_barrier
	ds_read_b128 v[174:177], v152 offset:49152
	ds_read_b128 v[182:185], v152 offset:51200
	ds_read_b128 v[190:193], v152 offset:53248
	s_add_u32 s58, s58, 0x20000
	s_addc_u32 s59, s59, 0
	s_mov_b32 m0, s39
	s_nop 0
	global_load_lds_dwordx4 v137, s[58:59]
	s_mov_b32 m0, s40
	s_nop 0
	global_load_lds_dwordx4 v139, s[58:59]
	s_waitcnt lgkmcnt(2)
	v_mfma_f32_16x16x32_bf16 v[64:67], v[146:149], v[174:177], v[64:67]
	v_mfma_f32_16x16x32_bf16 v[60:63], v[158:161], v[174:177], v[60:63]
	ds_read_b128 v[198:201], v152 offset:55296
	s_waitcnt lgkmcnt(2)
	v_mfma_f32_16x16x32_bf16 v[48:51], v[146:149], v[182:185], v[48:51]
	v_mfma_f32_16x16x32_bf16 v[44:47], v[158:161], v[182:185], v[44:47]
	ds_read_b128 v[178:181], v152 offset:50176
	s_waitcnt lgkmcnt(2)
	v_mfma_f32_16x16x32_bf16 v[32:35], v[146:149], v[190:193], v[32:35]
	v_mfma_f32_16x16x32_bf16 v[28:31], v[158:161], v[190:193], v[28:31]
	ds_read_b128 v[186:189], v152 offset:52224
	s_waitcnt lgkmcnt(2)
	v_mfma_f32_16x16x32_bf16 v[16:19], v[146:149], v[198:201], v[16:19]
	v_mfma_f32_16x16x32_bf16 v[12:15], v[158:161], v[198:201], v[12:15]
	ds_read_b128 v[194:197], v152 offset:54272
	s_waitcnt lgkmcnt(2)
	v_mfma_f32_16x16x32_bf16 v[64:67], v[154:157], v[178:181], v[64:67]
	v_mfma_f32_16x16x32_bf16 v[60:63], v[170:173], v[178:181], v[60:63]
	ds_read_b128 v[202:205], v152 offset:56320
	s_waitcnt lgkmcnt(2)
	v_mfma_f32_16x16x32_bf16 v[48:51], v[154:157], v[186:189], v[48:51]
	v_mfma_f32_16x16x32_bf16 v[44:47], v[170:173], v[186:189], v[44:47]
	s_waitcnt lgkmcnt(1)
	v_mfma_f32_16x16x32_bf16 v[32:35], v[154:157], v[194:197], v[32:35]
	v_mfma_f32_16x16x32_bf16 v[28:31], v[170:173], v[194:197], v[28:31]
	s_waitcnt lgkmcnt(0)
	v_mfma_f32_16x16x32_bf16 v[16:19], v[154:157], v[202:205], v[16:19]
	v_mfma_f32_16x16x32_bf16 v[12:15], v[170:173], v[202:205], v[12:15]
	s_add_u32 s24, s24, 0x20000
	s_addc_u32 s25, s25, 0
	s_mov_b32 m0, s41
	s_nop 0
	global_load_lds_dwordx4 v136, s[24:25]
	s_mov_b32 m0, s42
	s_nop 0
	global_load_lds_dwordx4 v138, s[24:25]
	v_mfma_f32_16x16x32_bf16 v[56:59], v[206:209], v[174:177], v[56:59]
	s_add_i32 s56, s56, 2
	s_add_u32 s22, s22, 0xffffff00
	s_addc_u32 s23, s23, -1
	v_mfma_f32_16x16x32_bf16 v[52:55], v[214:217], v[174:177], v[52:55]
	s_add_u32 s18, s18, 0x100
	s_addc_u32 s19, s19, 0
	s_add_u32 s20, s20, 0x100
	v_mfma_f32_16x16x32_bf16 v[40:43], v[206:209], v[182:185], v[40:43]
	s_addc_u32 s21, s21, 0
	s_cmp_lt_u32 s56, 6
	v_mfma_f32_16x16x32_bf16 v[36:39], v[214:217], v[182:185], v[36:39]
	v_mfma_f32_16x16x32_bf16 v[24:27], v[206:209], v[190:193], v[24:27]
	v_mfma_f32_16x16x32_bf16 v[20:23], v[214:217], v[190:193], v[20:23]
	v_mfma_f32_16x16x32_bf16 v[4:7], v[206:209], v[198:201], v[4:7]
	v_mfma_f32_16x16x32_bf16 v[8:11], v[214:217], v[198:201], v[8:11]
	v_mfma_f32_16x16x32_bf16 v[56:59], v[210:213], v[178:181], v[56:59]
	v_mfma_f32_16x16x32_bf16 v[52:55], v[218:221], v[178:181], v[52:55]
	v_mfma_f32_16x16x32_bf16 v[40:43], v[210:213], v[186:189], v[40:43]
	v_mfma_f32_16x16x32_bf16 v[36:39], v[218:221], v[186:189], v[36:39]
	v_mfma_f32_16x16x32_bf16 v[24:27], v[210:213], v[194:197], v[24:27]
	v_mfma_f32_16x16x32_bf16 v[20:23], v[218:221], v[194:197], v[20:23]
	v_mfma_f32_16x16x32_bf16 v[4:7], v[210:213], v[202:205], v[4:7]
	v_mfma_f32_16x16x32_bf16 v[8:11], v[218:221], v[202:205], v[8:11]
	s_cbranch_scc1 .LBB0_195
; __device__ __forceinline__ unsigned cvt_pk_bf16(float lo, float hi) { unsigned r; asm volatile("v_cvt_pk_bf16_f32 %0, %1, %2" : "=v"(r) : "v"(lo), "v"(hi)); return r; }
; #define LAS __attribute__((address_space(3)))
; __device__ __forceinline__ float bflo(unsigned w) { return __uint_as_float(w << 16); }
; __device__ __forceinline__ float bfhi(unsigned w) { return __uint_as_float(w & 0xffff0000u); }
;     __device__ __forceinline__ void operator()(const f32x4 (&acc)[2][2][4][2], const Unit& u, int wr, int wc, int fr, int fq, const LAS float*) const {
;         const int row0 = u.pm * 256 + wr * 64 + fr, col0 = u.pn * 256 + wc * 32 + 8 * fq;
; #pragma unroll
;         for (int ai = 0; ai < 2; ++ai)
; #pragma unroll
;             for (int m = 0; m < 4; ++m) { const size_t row = (size_t)(row0 + ai * 128 + m * 16);
; #pragma unroll
;                 for (int bj = 0; bj < 2; ++bj) { const int col = col0 + bj * 128;
;                     const u32x4 g = *(const u32x4*)(G + row * NGATE + MODE * DM + col);
;                     f32x4 v0 = acc[ai][bj][m][0], v1 = acc[ai][bj][m][1];
;                     v0[0] *= bflo(g.x); v0[1] *= bfhi(g.x); v0[2] *= bflo(g.y); v0[3] *= bfhi(g.y); v1[0] *= bflo(g.z); v1[1] *= bfhi(g.z); v1[2] *= bflo(g.w); v1[3] *= bfhi(g.w);
;                     bf16_t* tp = T + row * DM + col;
;                     if (MODE == 1) { const u32x4 t = *(const u32x4*)tp;
;                         v0[0] += bflo(t.x); v0[1] += bfhi(t.x); v0[2] += bflo(t.y); v0[3] += bfhi(t.y); v1[0] += bflo(t.z); v1[1] += bfhi(t.z); v1[2] += bflo(t.w); v1[3] += bfhi(t.w); }
;                     u32x4 w; w.x = cvt_pk_bf16(v0[0], v0[1]); w.y = cvt_pk_bf16(v0[2], v0[3]); w.z = cvt_pk_bf16(v1[0], v1[1]); w.w = cvt_pk_bf16(v1[2], v1[3]);
;                     *(u32x4*)tp = w; } }
	v_mov_b32_e32 v132, v141
	s_lshl_b32 s5, s16, 8
	v_mbcnt_lo_u32_b32 v132, -1, v132
	v_mbcnt_hi_u32_b32 v132, -1, v132
	s_add_i32 s5, s5, s29
	v_and_or_b32 v134, v132, 15, s5
	s_lshl_b32 s5, s53, 8
	v_ashrrev_i32_e32 v132, 1, v132
	s_or_b32 s5, s5, s35
	v_and_b32_e32 v132, -8, v132
	v_add_u32_e32 v132, s5, v132
	v_ashrrev_i32_e32 v135, 31, v134
	v_lshlrev_b64 v[142:143], 13, v[134:135]
	v_ashrrev_i32_e32 v133, 31, v132
	v_lshl_add_u64 v[142:143], s[2:3], 0, v[142:143]
	v_lshlrev_b64 v[132:133], 1, v[132:133]
	v_lshl_add_u64 v[142:143], v[142:143], 0, v[132:133]
	v_lshlrev_b32_e32 v236, 13, v134
	v_add_u32_e32 v236, v236, v132
	global_load_dwordx4 v[172:175], v236, s[2:3]
	global_load_dwordx4 v[176:179], v236, s[2:3] offset:256
	v_add_u32_e32 v237, 0x20000, v236
	global_load_dwordx4 v[180:183], v237, s[2:3]
	global_load_dwordx4 v[184:187], v237, s[2:3] offset:256
	v_add_u32_e32 v237, 0x40000, v236
	global_load_dwordx4 v[188:191], v237, s[2:3]
	global_load_dwordx4 v[192:195], v237, s[2:3] offset:256
	v_add_u32_e32 v237, 0x60000, v236
	global_load_dwordx4 v[196:199], v237, s[2:3]
	global_load_dwordx4 v[200:203], v237, s[2:3] offset:256
	v_add_u32_e32 v237, 0x100000, v236
	global_load_dwordx4 v[204:207], v237, s[2:3]
	global_load_dwordx4 v[208:211], v237, s[2:3] offset:256
	v_add_u32_e32 v237, 0x120000, v236
	global_load_dwordx4 v[212:215], v237, s[2:3]
	global_load_dwordx4 v[216:219], v237, s[2:3] offset:256
	v_add_u32_e32 v237, 0x140000, v236
	global_load_dwordx4 v[220:223], v237, s[2:3]
	global_load_dwordx4 v[224:227], v237, s[2:3] offset:256
	v_add_u32_e32 v237, 0x160000, v236
	global_load_dwordx4 v[228:231], v237, s[2:3]
	global_load_dwordx4 v[232:235], v237, s[2:3] offset:256
	v_lshlrev_b64 v[144:145], 12, v[134:135]
	s_andn2_b64 vcc, exec, s[6:7]
	s_mov_b32 s53, s4
	s_mov_b32 s16, s8
	s_mov_b64 s[18:19], s[14:15]
	s_mov_b64 s[20:21], s[10:11]
	s_mov_b32 s9, s52
	s_waitcnt vmcnt(15)
	s_nop 1
	v_mov_b64_e32 v[146:147], v[172:173]
	v_mov_b64_e32 v[148:149], v[174:175]
	v_lshlrev_b32_e32 v135, 16, v146
	v_mul_f32_e32 v135, v128, v135
	v_and_b32_e32 v128, 0xffff0000, v146
	v_mul_f32_e32 v146, v129, v128
	v_lshlrev_b32_e32 v128, 16, v147
	v_mul_f32_e32 v130, v130, v128
	v_and_b32_e32 v128, 0xffff0000, v147
	v_mul_f32_e32 v131, v131, v128
	v_lshlrev_b32_e32 v128, 16, v148
	v_mul_f32_e32 v147, v124, v128
	v_and_b32_e32 v124, 0xffff0000, v148
	v_mul_f32_e32 v148, v125, v124
	v_lshlrev_b32_e32 v124, 16, v149
	v_mul_f32_e32 v153, v126, v124
	v_and_b32_e32 v124, 0xffff0000, v149
	v_mul_f32_e32 v127, v127, v124
	v_lshl_add_u64 v[124:125], s[12:13], 0, v[144:145]
	v_lshl_add_u64 v[128:129], v[124:125], 0, v[132:133]
	v_cvt_pk_bf16_f32 v124, v135, v146
	v_cvt_pk_bf16_f32 v125, v130, v131
	v_cvt_pk_bf16_f32 v126, v147, v148
	v_cvt_pk_bf16_f32 v127, v153, v127
	global_store_dwordx4 v[128:129], v[124:127], off
	s_waitcnt vmcnt(15)
	s_nop 1
	v_mov_b64_e32 v[124:125], v[176:177]
	v_mov_b64_e32 v[126:127], v[178:179]
	v_lshlrev_b32_e32 v130, 16, v124
	v_and_b32_e32 v124, 0xffff0000, v124
	v_mul_f32_e32 v121, v121, v124
	v_lshlrev_b32_e32 v124, 16, v125
	v_mul_f32_e32 v122, v122, v124
	v_and_b32_e32 v124, 0xffff0000, v125
	v_mul_f32_e32 v123, v123, v124
	v_lshlrev_b32_e32 v124, 16, v126
	v_mul_f32_e32 v124, v116, v124
	v_and_b32_e32 v116, 0xffff0000, v126
	v_mul_f32_e32 v125, v117, v116
	v_lshlrev_b32_e32 v116, 16, v127
	v_mul_f32_e32 v126, v118, v116
	v_and_b32_e32 v116, 0xffff0000, v127
	v_mul_f32_e32 v120, v120, v130
	v_mul_f32_e32 v119, v119, v116
	v_cvt_pk_bf16_f32 v116, v120, v121
	v_cvt_pk_bf16_f32 v117, v122, v123
	v_cvt_pk_bf16_f32 v118, v124, v125
	v_cvt_pk_bf16_f32 v119, v126, v119
	global_store_dwordx4 v[128:129], v[116:119], off offset:256
	s_nop 1
	v_or_b32_e32 v116, 16, v134
	v_ashrrev_i32_e32 v117, 31, v116
	v_lshlrev_b64 v[118:119], 13, v[116:117]
	v_lshlrev_b64 v[120:121], 12, v[116:117]
	v_lshl_add_u64 v[116:117], s[2:3], 0, v[118:119]
	v_lshl_add_u64 v[122:123], v[116:117], 0, v[132:133]
	s_waitcnt vmcnt(15)
	s_nop 1
	v_mov_b64_e32 v[116:117], v[180:181]
	v_mov_b64_e32 v[118:119], v[182:183]
	v_lshlrev_b32_e32 v124, 16, v116
	v_mul_f32_e32 v124, v112, v124
	v_and_b32_e32 v112, 0xffff0000, v116
	v_mul_f32_e32 v116, v113, v112
	v_lshlrev_b32_e32 v112, 16, v117
	v_mul_f32_e32 v114, v114, v112
	v_and_b32_e32 v112, 0xffff0000, v117
	v_mul_f32_e32 v115, v115, v112
	v_lshlrev_b32_e32 v112, 16, v118
	v_mul_f32_e32 v117, v108, v112
	v_and_b32_e32 v108, 0xffff0000, v118
	v_mul_f32_e32 v118, v109, v108
	v_lshlrev_b32_e32 v108, 16, v119
	v_mul_f32_e32 v125, v110, v108
	v_and_b32_e32 v108, 0xffff0000, v119
	v_mul_f32_e32 v111, v111, v108
	v_lshl_add_u64 v[108:109], s[12:13], 0, v[120:121]
	v_lshl_add_u64 v[112:113], v[108:109], 0, v[132:133]
	v_cvt_pk_bf16_f32 v108, v124, v116
	v_cvt_pk_bf16_f32 v109, v114, v115
	v_cvt_pk_bf16_f32 v110, v117, v118
	v_cvt_pk_bf16_f32 v111, v125, v111
	global_store_dwordx4 v[112:113], v[108:111], off
	s_waitcnt vmcnt(15)
	s_nop 1
	v_mov_b64_e32 v[108:109], v[184:185]
	v_mov_b64_e32 v[110:111], v[186:187]
	v_lshlrev_b32_e32 v114, 16, v108
	v_and_b32_e32 v108, 0xffff0000, v108
	v_mul_f32_e32 v105, v105, v108
	v_lshlrev_b32_e32 v108, 16, v109
	v_mul_f32_e32 v106, v106, v108
	v_and_b32_e32 v108, 0xffff0000, v109
	v_mul_f32_e32 v107, v107, v108
	v_lshlrev_b32_e32 v108, 16, v110
	v_mul_f32_e32 v108, v100, v108
	v_and_b32_e32 v100, 0xffff0000, v110
	v_mul_f32_e32 v109, v101, v100
	v_lshlrev_b32_e32 v100, 16, v111
	v_mul_f32_e32 v110, v102, v100
	v_and_b32_e32 v100, 0xffff0000, v111
	v_mul_f32_e32 v104, v104, v114
	v_mul_f32_e32 v103, v103, v100
	v_cvt_pk_bf16_f32 v100, v104, v105
	v_cvt_pk_bf16_f32 v101, v106, v107
	v_cvt_pk_bf16_f32 v102, v108, v109
	v_cvt_pk_bf16_f32 v103, v110, v103
	global_store_dwordx4 v[112:113], v[100:103], off offset:256
	s_nop 1
	v_or_b32_e32 v100, 32, v134
	v_ashrrev_i32_e32 v101, 31, v100
	v_lshlrev_b64 v[102:103], 13, v[100:101]
	v_lshlrev_b64 v[104:105], 12, v[100:101]
	v_lshl_add_u64 v[100:101], s[2:3], 0, v[102:103]
	v_lshl_add_u64 v[106:107], v[100:101], 0, v[132:133]
	s_waitcnt vmcnt(15)
; __device__ __forceinline__ unsigned cvt_pk_bf16(float lo, float hi) { unsigned r; asm volatile("v_cvt_pk_bf16_f32 %0, %1, %2" : "=v"(r) : "v"(lo), "v"(hi)); return r; }
; #define LAS __attribute__((address_space(3)))
; __device__ __forceinline__ float bflo(unsigned w) { return __uint_as_float(w << 16); }
; __device__ __forceinline__ float bfhi(unsigned w) { return __uint_as_float(w & 0xffff0000u); }
;     __device__ __forceinline__ void operator()(const f32x4 (&acc)[2][2][4][2], const Unit& u, int wr, int wc, int fr, int fq, const LAS float*) const {
;         const int row0 = u.pm * 256 + wr * 64 + fr, col0 = u.pn * 256 + wc * 32 + 8 * fq;
; #pragma unroll
;         for (int ai = 0; ai < 2; ++ai)
; #pragma unroll
;             for (int m = 0; m < 4; ++m) { const size_t row = (size_t)(row0 + ai * 128 + m * 16);
; #pragma unroll
;                 for (int bj = 0; bj < 2; ++bj) { const int col = col0 + bj * 128;
;                     const u32x4 g = *(const u32x4*)(G + row * NGATE + MODE * DM + col);
;                     f32x4 v0 = acc[ai][bj][m][0], v1 = acc[ai][bj][m][1];
;                     v0[0] *= bflo(g.x); v0[1] *= bfhi(g.x); v0[2] *= bflo(g.y); v0[3] *= bfhi(g.y); v1[0] *= bflo(g.z); v1[1] *= bfhi(g.z); v1[2] *= bflo(g.w); v1[3] *= bfhi(g.w);
;                     bf16_t* tp = T + row * DM + col;
;                     if (MODE == 1) { const u32x4 t = *(const u32x4*)tp;
;                         v0[0] += bflo(t.x); v0[1] += bfhi(t.x); v0[2] += bflo(t.y); v0[3] += bfhi(t.y); v1[0] += bflo(t.z); v1[1] += bfhi(t.z); v1[2] += bflo(t.w); v1[3] += bfhi(t.w); }
;                     u32x4 w; w.x = cvt_pk_bf16(v0[0], v0[1]); w.y = cvt_pk_bf16(v0[2], v0[3]); w.z = cvt_pk_bf16(v1[0], v1[1]); w.w = cvt_pk_bf16(v1[2], v1[3]);
;                     *(u32x4*)tp = w; } }
	s_nop 1
	v_mov_b64_e32 v[100:101], v[188:189]
	v_mov_b64_e32 v[102:103], v[190:191]
	v_lshlrev_b32_e32 v108, 16, v100
	v_mul_f32_e32 v108, v96, v108
	v_and_b32_e32 v96, 0xffff0000, v100
	v_mul_f32_e32 v100, v97, v96
	v_lshlrev_b32_e32 v96, 16, v101
	v_mul_f32_e32 v98, v98, v96
	v_and_b32_e32 v96, 0xffff0000, v101
	v_mul_f32_e32 v99, v99, v96
	v_lshlrev_b32_e32 v96, 16, v102
	v_mul_f32_e32 v101, v92, v96
	v_and_b32_e32 v92, 0xffff0000, v102
	v_mul_f32_e32 v102, v93, v92
	v_lshlrev_b32_e32 v92, 16, v103
	v_mul_f32_e32 v109, v94, v92
	v_and_b32_e32 v92, 0xffff0000, v103
	v_mul_f32_e32 v95, v95, v92
	v_lshl_add_u64 v[92:93], s[12:13], 0, v[104:105]
	v_lshl_add_u64 v[96:97], v[92:93], 0, v[132:133]
	v_cvt_pk_bf16_f32 v92, v108, v100
	v_cvt_pk_bf16_f32 v93, v98, v99
	v_cvt_pk_bf16_f32 v94, v101, v102
	v_cvt_pk_bf16_f32 v95, v109, v95
	global_store_dwordx4 v[96:97], v[92:95], off
	s_waitcnt vmcnt(15)
	s_nop 1
	v_mov_b64_e32 v[92:93], v[192:193]
	v_mov_b64_e32 v[94:95], v[194:195]
	v_lshlrev_b32_e32 v98, 16, v92
	v_and_b32_e32 v92, 0xffff0000, v92
	v_mul_f32_e32 v89, v89, v92
	v_lshlrev_b32_e32 v92, 16, v93
	v_mul_f32_e32 v90, v90, v92
	v_and_b32_e32 v92, 0xffff0000, v93
	v_mul_f32_e32 v91, v91, v92
	v_lshlrev_b32_e32 v92, 16, v94
	v_mul_f32_e32 v92, v84, v92
	v_and_b32_e32 v84, 0xffff0000, v94
	v_mul_f32_e32 v93, v85, v84
	v_lshlrev_b32_e32 v84, 16, v95
	v_mul_f32_e32 v94, v86, v84
	v_and_b32_e32 v84, 0xffff0000, v95
	v_mul_f32_e32 v88, v88, v98
	v_mul_f32_e32 v87, v87, v84
	v_cvt_pk_bf16_f32 v84, v88, v89
	v_cvt_pk_bf16_f32 v85, v90, v91
	v_cvt_pk_bf16_f32 v86, v92, v93
	v_cvt_pk_bf16_f32 v87, v94, v87
	global_store_dwordx4 v[96:97], v[84:87], off offset:256
	s_nop 1
	v_or_b32_e32 v84, 48, v134
	v_ashrrev_i32_e32 v85, 31, v84
	v_lshlrev_b64 v[86:87], 13, v[84:85]
	v_lshlrev_b64 v[88:89], 12, v[84:85]
	v_lshl_add_u64 v[84:85], s[2:3], 0, v[86:87]
	v_lshl_add_u64 v[90:91], v[84:85], 0, v[132:133]
	s_waitcnt vmcnt(15)
	s_nop 1
	v_mov_b64_e32 v[84:85], v[196:197]
	v_mov_b64_e32 v[86:87], v[198:199]
	v_lshlrev_b32_e32 v92, 16, v84
	v_mul_f32_e32 v92, v80, v92
	v_and_b32_e32 v80, 0xffff0000, v84
	v_mul_f32_e32 v84, v81, v80
	v_lshlrev_b32_e32 v80, 16, v85
	v_mul_f32_e32 v82, v82, v80
	v_and_b32_e32 v80, 0xffff0000, v85
	v_mul_f32_e32 v83, v83, v80
	v_lshlrev_b32_e32 v80, 16, v86
	v_mul_f32_e32 v85, v76, v80
	v_and_b32_e32 v76, 0xffff0000, v86
	v_mul_f32_e32 v86, v77, v76
	v_lshlrev_b32_e32 v76, 16, v87
	v_mul_f32_e32 v93, v78, v76
	v_and_b32_e32 v76, 0xffff0000, v87
	v_mul_f32_e32 v79, v79, v76
	v_lshl_add_u64 v[76:77], s[12:13], 0, v[88:89]
	v_lshl_add_u64 v[80:81], v[76:77], 0, v[132:133]
	v_cvt_pk_bf16_f32 v76, v92, v84
	v_cvt_pk_bf16_f32 v77, v82, v83
	v_cvt_pk_bf16_f32 v78, v85, v86
	v_cvt_pk_bf16_f32 v79, v93, v79
	global_store_dwordx4 v[80:81], v[76:79], off
	s_waitcnt vmcnt(15)
	s_nop 1
	v_mov_b64_e32 v[76:77], v[200:201]
	v_mov_b64_e32 v[78:79], v[202:203]
	v_lshlrev_b32_e32 v82, 16, v76
	v_and_b32_e32 v76, 0xffff0000, v76
	v_mul_f32_e32 v73, v73, v76
	v_lshlrev_b32_e32 v76, 16, v77
	v_mul_f32_e32 v74, v74, v76
	v_and_b32_e32 v76, 0xffff0000, v77
	v_mul_f32_e32 v75, v75, v76
	v_lshlrev_b32_e32 v76, 16, v78
	v_mul_f32_e32 v76, v68, v76
	v_and_b32_e32 v68, 0xffff0000, v78
	v_mul_f32_e32 v77, v69, v68
	v_lshlrev_b32_e32 v68, 16, v79
	v_mul_f32_e32 v78, v70, v68
	v_and_b32_e32 v68, 0xffff0000, v79
	v_mul_f32_e32 v72, v72, v82
	v_mul_f32_e32 v71, v71, v68
	v_cvt_pk_bf16_f32 v68, v72, v73
	v_cvt_pk_bf16_f32 v69, v74, v75
	v_cvt_pk_bf16_f32 v70, v76, v77
	v_cvt_pk_bf16_f32 v71, v78, v71
	global_store_dwordx4 v[80:81], v[68:71], off offset:256
	s_nop 1
	v_add_u32_e32 v68, 0x80, v134
	v_ashrrev_i32_e32 v69, 31, v68
	v_lshlrev_b64 v[70:71], 13, v[68:69]
	v_lshlrev_b64 v[72:73], 12, v[68:69]
	v_lshl_add_u64 v[68:69], s[2:3], 0, v[70:71]
	v_lshl_add_u64 v[74:75], v[68:69], 0, v[132:133]
	s_waitcnt vmcnt(15)
	s_nop 1
	v_mov_b64_e32 v[68:69], v[204:205]
	v_mov_b64_e32 v[70:71], v[206:207]
	v_lshlrev_b32_e32 v76, 16, v68
	v_mul_f32_e32 v76, v64, v76
	v_and_b32_e32 v64, 0xffff0000, v68
	v_mul_f32_e32 v68, v65, v64
	v_lshlrev_b32_e32 v64, 16, v69
	v_mul_f32_e32 v66, v66, v64
	v_and_b32_e32 v64, 0xffff0000, v69
	v_mul_f32_e32 v67, v67, v64
	v_lshlrev_b32_e32 v64, 16, v70
	v_mul_f32_e32 v69, v60, v64
	v_and_b32_e32 v60, 0xffff0000, v70
	v_mul_f32_e32 v70, v61, v60
	v_lshlrev_b32_e32 v60, 16, v71
	v_mul_f32_e32 v77, v62, v60
	v_and_b32_e32 v60, 0xffff0000, v71
	v_mul_f32_e32 v63, v63, v60
	v_lshl_add_u64 v[60:61], s[12:13], 0, v[72:73]
	v_lshl_add_u64 v[64:65], v[60:61], 0, v[132:133]
	v_cvt_pk_bf16_f32 v60, v76, v68
	v_cvt_pk_bf16_f32 v61, v66, v67
	v_cvt_pk_bf16_f32 v62, v69, v70
	v_cvt_pk_bf16_f32 v63, v77, v63
	global_store_dwordx4 v[64:65], v[60:63], off
	s_waitcnt vmcnt(15)
	s_nop 1
	v_mov_b64_e32 v[60:61], v[208:209]
	v_mov_b64_e32 v[62:63], v[210:211]
	v_lshlrev_b32_e32 v66, 16, v60
	v_and_b32_e32 v60, 0xffff0000, v60
	v_mul_f32_e32 v57, v57, v60
	v_lshlrev_b32_e32 v60, 16, v61
	v_mul_f32_e32 v58, v58, v60
	v_and_b32_e32 v60, 0xffff0000, v61
	v_mul_f32_e32 v59, v59, v60
	v_lshlrev_b32_e32 v60, 16, v62
	v_mul_f32_e32 v60, v52, v60
	v_and_b32_e32 v52, 0xffff0000, v62
	v_mul_f32_e32 v61, v53, v52
	v_lshlrev_b32_e32 v52, 16, v63
	v_mul_f32_e32 v62, v54, v52
	v_and_b32_e32 v52, 0xffff0000, v63
	v_mul_f32_e32 v56, v56, v66
	v_mul_f32_e32 v55, v55, v52
	v_cvt_pk_bf16_f32 v52, v56, v57
	v_cvt_pk_bf16_f32 v53, v58, v59
	v_cvt_pk_bf16_f32 v54, v60, v61
	v_cvt_pk_bf16_f32 v55, v62, v55
	global_store_dwordx4 v[64:65], v[52:55], off offset:256
	s_nop 1
	v_add_u32_e32 v52, 0x90, v134
	v_ashrrev_i32_e32 v53, 31, v52
	v_lshlrev_b64 v[54:55], 13, v[52:53]
	v_lshlrev_b64 v[56:57], 12, v[52:53]
	v_lshl_add_u64 v[52:53], s[2:3], 0, v[54:55]
	v_lshl_add_u64 v[58:59], v[52:53], 0, v[132:133]
	s_waitcnt vmcnt(15)
; __device__ __forceinline__ unsigned cvt_pk_bf16(float lo, float hi) { unsigned r; asm volatile("v_cvt_pk_bf16_f32 %0, %1, %2" : "=v"(r) : "v"(lo), "v"(hi)); return r; }
; #define LAS __attribute__((address_space(3)))
; __device__ __forceinline__ float bflo(unsigned w) { return __uint_as_float(w << 16); }
; __device__ __forceinline__ float bfhi(unsigned w) { return __uint_as_float(w & 0xffff0000u); }
;     __device__ __forceinline__ void operator()(const f32x4 (&acc)[2][2][4][2], const Unit& u, int wr, int wc, int fr, int fq, const LAS float*) const {
;         const int row0 = u.pm * 256 + wr * 64 + fr, col0 = u.pn * 256 + wc * 32 + 8 * fq;
; #pragma unroll
;         for (int ai = 0; ai < 2; ++ai)
; #pragma unroll
;             for (int m = 0; m < 4; ++m) { const size_t row = (size_t)(row0 + ai * 128 + m * 16);
; #pragma unroll
;                 for (int bj = 0; bj < 2; ++bj) { const int col = col0 + bj * 128;
;                     const u32x4 g = *(const u32x4*)(G + row * NGATE + MODE * DM + col);
;                     f32x4 v0 = acc[ai][bj][m][0], v1 = acc[ai][bj][m][1];
;                     v0[0] *= bflo(g.x); v0[1] *= bfhi(g.x); v0[2] *= bflo(g.y); v0[3] *= bfhi(g.y); v1[0] *= bflo(g.z); v1[1] *= bfhi(g.z); v1[2] *= bflo(g.w); v1[3] *= bfhi(g.w);
;                     bf16_t* tp = T + row * DM + col;
;                     if (MODE == 1) { const u32x4 t = *(const u32x4*)tp;
;                         v0[0] += bflo(t.x); v0[1] += bfhi(t.x); v0[2] += bflo(t.y); v0[3] += bfhi(t.y); v1[0] += bflo(t.z); v1[1] += bfhi(t.z); v1[2] += bflo(t.w); v1[3] += bfhi(t.w); }
;                     u32x4 w; w.x = cvt_pk_bf16(v0[0], v0[1]); w.y = cvt_pk_bf16(v0[2], v0[3]); w.z = cvt_pk_bf16(v1[0], v1[1]); w.w = cvt_pk_bf16(v1[2], v1[3]);
;                     *(u32x4*)tp = w; } }
	s_nop 1
	v_mov_b64_e32 v[52:53], v[212:213]
	v_mov_b64_e32 v[54:55], v[214:215]
	v_lshlrev_b32_e32 v60, 16, v52
	v_mul_f32_e32 v60, v48, v60
	v_and_b32_e32 v48, 0xffff0000, v52
	v_mul_f32_e32 v52, v49, v48
	v_lshlrev_b32_e32 v48, 16, v53
	v_mul_f32_e32 v50, v50, v48
	v_and_b32_e32 v48, 0xffff0000, v53
	v_mul_f32_e32 v51, v51, v48
	v_lshlrev_b32_e32 v48, 16, v54
	v_mul_f32_e32 v53, v44, v48
	v_and_b32_e32 v44, 0xffff0000, v54
	v_mul_f32_e32 v54, v45, v44
	v_lshlrev_b32_e32 v44, 16, v55
	v_mul_f32_e32 v61, v46, v44
	v_and_b32_e32 v44, 0xffff0000, v55
	v_mul_f32_e32 v47, v47, v44
	v_lshl_add_u64 v[44:45], s[12:13], 0, v[56:57]
	v_lshl_add_u64 v[48:49], v[44:45], 0, v[132:133]
	v_cvt_pk_bf16_f32 v44, v60, v52
	v_cvt_pk_bf16_f32 v45, v50, v51
	v_cvt_pk_bf16_f32 v46, v53, v54
	v_cvt_pk_bf16_f32 v47, v61, v47
	global_store_dwordx4 v[48:49], v[44:47], off
	s_waitcnt vmcnt(15)
	s_nop 1
	v_mov_b64_e32 v[44:45], v[216:217]
	v_mov_b64_e32 v[46:47], v[218:219]
	v_lshlrev_b32_e32 v50, 16, v44
	v_and_b32_e32 v44, 0xffff0000, v44
	v_mul_f32_e32 v41, v41, v44
	v_lshlrev_b32_e32 v44, 16, v45
	v_mul_f32_e32 v42, v42, v44
	v_and_b32_e32 v44, 0xffff0000, v45
	v_mul_f32_e32 v43, v43, v44
	v_lshlrev_b32_e32 v44, 16, v46
	v_mul_f32_e32 v44, v36, v44
	v_and_b32_e32 v36, 0xffff0000, v46
	v_mul_f32_e32 v45, v37, v36
	v_lshlrev_b32_e32 v36, 16, v47
	v_mul_f32_e32 v46, v38, v36
	v_and_b32_e32 v36, 0xffff0000, v47
	v_mul_f32_e32 v40, v40, v50
	v_mul_f32_e32 v39, v39, v36
	v_cvt_pk_bf16_f32 v36, v40, v41
	v_cvt_pk_bf16_f32 v37, v42, v43
	v_cvt_pk_bf16_f32 v38, v44, v45
	v_cvt_pk_bf16_f32 v39, v46, v39
	global_store_dwordx4 v[48:49], v[36:39], off offset:256
	s_nop 1
	v_add_u32_e32 v36, 0xa0, v134
	v_ashrrev_i32_e32 v37, 31, v36
	v_lshlrev_b64 v[38:39], 13, v[36:37]
	v_lshlrev_b64 v[40:41], 12, v[36:37]
	v_lshl_add_u64 v[36:37], s[2:3], 0, v[38:39]
	v_lshl_add_u64 v[42:43], v[36:37], 0, v[132:133]
	s_waitcnt vmcnt(15)
	s_nop 1
	v_mov_b64_e32 v[36:37], v[220:221]
	v_mov_b64_e32 v[38:39], v[222:223]
	v_lshlrev_b32_e32 v44, 16, v36
	v_mul_f32_e32 v44, v32, v44
	v_and_b32_e32 v32, 0xffff0000, v36
	v_mul_f32_e32 v36, v33, v32
	v_lshlrev_b32_e32 v32, 16, v37
	v_mul_f32_e32 v34, v34, v32
	v_and_b32_e32 v32, 0xffff0000, v37
	v_mul_f32_e32 v35, v35, v32
	v_lshlrev_b32_e32 v32, 16, v38
	v_mul_f32_e32 v37, v28, v32
	v_and_b32_e32 v28, 0xffff0000, v38
	v_mul_f32_e32 v38, v29, v28
	v_lshlrev_b32_e32 v28, 16, v39
	v_mul_f32_e32 v45, v30, v28
	v_and_b32_e32 v28, 0xffff0000, v39
	v_mul_f32_e32 v31, v31, v28
	v_lshl_add_u64 v[28:29], s[12:13], 0, v[40:41]
	v_lshl_add_u64 v[32:33], v[28:29], 0, v[132:133]
	v_cvt_pk_bf16_f32 v28, v44, v36
	v_cvt_pk_bf16_f32 v29, v34, v35
	v_cvt_pk_bf16_f32 v30, v37, v38
	v_cvt_pk_bf16_f32 v31, v45, v31
	global_store_dwordx4 v[32:33], v[28:31], off
	s_waitcnt vmcnt(15)
	s_nop 1
	v_mov_b64_e32 v[28:29], v[224:225]
	v_mov_b64_e32 v[30:31], v[226:227]
	v_lshlrev_b32_e32 v34, 16, v28
	v_and_b32_e32 v28, 0xffff0000, v28
	v_mul_f32_e32 v25, v25, v28
	v_lshlrev_b32_e32 v28, 16, v29
	v_mul_f32_e32 v26, v26, v28
	v_and_b32_e32 v28, 0xffff0000, v29
	v_mul_f32_e32 v27, v27, v28
	v_lshlrev_b32_e32 v28, 16, v30
	v_mul_f32_e32 v28, v20, v28
	v_and_b32_e32 v20, 0xffff0000, v30
	v_mul_f32_e32 v29, v21, v20
	v_lshlrev_b32_e32 v20, 16, v31
	v_mul_f32_e32 v30, v22, v20
	v_and_b32_e32 v20, 0xffff0000, v31
	v_mul_f32_e32 v24, v24, v34
	v_mul_f32_e32 v23, v23, v20
	v_cvt_pk_bf16_f32 v20, v24, v25
	v_cvt_pk_bf16_f32 v21, v26, v27
	v_cvt_pk_bf16_f32 v22, v28, v29
	v_cvt_pk_bf16_f32 v23, v30, v23
	global_store_dwordx4 v[32:33], v[20:23], off offset:256
	s_nop 1
	v_add_u32_e32 v20, 0xb0, v134
	v_ashrrev_i32_e32 v21, 31, v20
	v_lshlrev_b64 v[22:23], 13, v[20:21]
	v_lshlrev_b64 v[24:25], 12, v[20:21]
	v_lshl_add_u64 v[20:21], s[2:3], 0, v[22:23]
	v_lshl_add_u64 v[26:27], v[20:21], 0, v[132:133]
	s_waitcnt vmcnt(15)
	s_nop 1
	v_mov_b64_e32 v[20:21], v[228:229]
	v_mov_b64_e32 v[22:23], v[230:231]
	v_lshlrev_b32_e32 v28, 16, v20
	v_mul_f32_e32 v28, v16, v28
	v_and_b32_e32 v16, 0xffff0000, v20
	v_mul_f32_e32 v20, v17, v16
	v_lshlrev_b32_e32 v16, 16, v21
	v_mul_f32_e32 v18, v18, v16
	v_and_b32_e32 v16, 0xffff0000, v21
	v_mul_f32_e32 v19, v19, v16
	v_lshlrev_b32_e32 v16, 16, v22
	v_mul_f32_e32 v21, v12, v16
	v_and_b32_e32 v12, 0xffff0000, v22
	v_mul_f32_e32 v22, v13, v12
	v_lshlrev_b32_e32 v12, 16, v23
	v_mul_f32_e32 v29, v14, v12
	v_and_b32_e32 v12, 0xffff0000, v23
	v_mul_f32_e32 v15, v15, v12
	v_lshl_add_u64 v[12:13], s[12:13], 0, v[24:25]
	v_lshl_add_u64 v[16:17], v[12:13], 0, v[132:133]
	v_cvt_pk_bf16_f32 v12, v28, v20
	v_cvt_pk_bf16_f32 v13, v18, v19
	v_cvt_pk_bf16_f32 v14, v21, v22
	v_cvt_pk_bf16_f32 v15, v29, v15
	global_store_dwordx4 v[16:17], v[12:15], off
	s_waitcnt vmcnt(15)
	s_nop 1
	v_mov_b64_e32 v[12:13], v[232:233]
	v_mov_b64_e32 v[14:15], v[234:235]
	v_lshlrev_b32_e32 v18, 16, v12
	v_and_b32_e32 v12, 0xffff0000, v12
	v_mul_f32_e32 v5, v5, v12
	v_lshlrev_b32_e32 v12, 16, v13
	v_mul_f32_e32 v6, v6, v12
	v_and_b32_e32 v12, 0xffff0000, v13
	v_mul_f32_e32 v7, v7, v12
	v_lshlrev_b32_e32 v12, 16, v14
	v_mul_f32_e32 v8, v8, v12
	v_and_b32_e32 v12, 0xffff0000, v14
	v_mul_f32_e32 v9, v9, v12
	v_lshlrev_b32_e32 v12, 16, v15
	v_mul_f32_e32 v4, v4, v18
	v_mul_f32_e32 v10, v10, v12
	v_and_b32_e32 v12, 0xffff0000, v15
	v_mul_f32_e32 v11, v11, v12
	v_cvt_pk_bf16_f32 v4, v4, v5
	v_cvt_pk_bf16_f32 v5, v6, v7
	v_cvt_pk_bf16_f32 v6, v8, v9
	v_cvt_pk_bf16_f32 v7, v10, v11
	global_store_dwordx4 v[16:17], v[4:7], off offset:256
	s_cbranch_vccnz .LBB0_186
	s_waitcnt vmcnt(0) lgkmcnt(0)
	s_barrier

; template <class Epi, class Sched>
; __device__ __forceinline__ void gemm_simple(PG8_LAS unsigned char* lds, const Gemm g, const Sched& S, const Epi& E, int wave_s) {
;     ...
;         for (; t < nt; t += 2) {
;             const bool last = (t == nt - 2);
;             PG8_TILE(0, cA + (size_t)(t + 1) * kstep, cB + (size_t)(t + 1) * kstep, true);
;             const char* a2 = last ? nA : cA + (size_t)(t + 2) * kstep; const char* b2 = last ? nB : cB + (size_t)(t + 2) * kstep;
;             PG8_TILE(1, a2, b2, (!last || has_next));
.LBB0_221:
	s_waitcnt vmcnt(2) lgkmcnt(0)
	s_barrier
	ds_read_b128 v[146:149], v132
	ds_read_b128 v[178:181], v156
	ds_read_b128 v[170:173], v132 offset:2048
	ds_read_b128 v[186:189], v156 offset:2048
	ds_read_b128 v[194:197], v156 offset:4096
	s_add_u32 s60, s10, s59
	s_addc_u32 s61, s11, 0
	s_add_u32 s24, s60, 0x80
	s_addc_u32 s25, s61, 0
	s_mov_b32 m0, s44
	s_nop 0
	global_load_lds_dwordx4 v140, s[24:25]
	s_mov_b32 m0, s48
	s_nop 0
	global_load_lds_dwordx4 v153, s[24:25]
	s_waitcnt lgkmcnt(3)
	v_mfma_f32_16x16x32_bf16 v[128:131], v[146:149], v[178:181], v[128:131]
	s_waitcnt lgkmcnt(2)
	v_mfma_f32_16x16x32_bf16 v[124:127], v[170:173], v[178:181], v[124:127]
	ds_read_b128 v[202:205], v156 offset:6144
	s_waitcnt lgkmcnt(2)
	v_mfma_f32_16x16x32_bf16 v[112:115], v[146:149], v[186:189], v[112:115]
	v_mfma_f32_16x16x32_bf16 v[108:111], v[170:173], v[186:189], v[108:111]
	ds_read_b128 v[158:161], v132 offset:1024
	ds_read_b128 v[182:185], v156 offset:1024
	s_waitcnt lgkmcnt(3)
	v_mfma_f32_16x16x32_bf16 v[96:99], v[146:149], v[194:197], v[96:99]
	ds_read_b128 v[174:177], v132 offset:3072
	v_mfma_f32_16x16x32_bf16 v[92:95], v[170:173], v[194:197], v[92:95]
	ds_read_b128 v[190:193], v156 offset:3072
	s_waitcnt lgkmcnt(4)
	v_mfma_f32_16x16x32_bf16 v[80:83], v[146:149], v[202:205], v[80:83]
	v_mfma_f32_16x16x32_bf16 v[76:79], v[170:173], v[202:205], v[76:79]
	ds_read_b128 v[198:201], v156 offset:5120
	s_waitcnt lgkmcnt(3)
	v_mfma_f32_16x16x32_bf16 v[128:131], v[158:161], v[182:185], v[128:131]
	s_waitcnt lgkmcnt(2)
	v_mfma_f32_16x16x32_bf16 v[124:127], v[174:177], v[182:185], v[124:127]
	ds_read_b128 v[206:209], v156 offset:7168
	s_waitcnt lgkmcnt(2)
	v_mfma_f32_16x16x32_bf16 v[112:115], v[158:161], v[190:193], v[112:115]
	v_mfma_f32_16x16x32_bf16 v[108:111], v[174:177], v[190:193], v[108:111]
	ds_read_b128 v[210:213], v133
	s_waitcnt lgkmcnt(2)
	v_mfma_f32_16x16x32_bf16 v[96:99], v[158:161], v[198:201], v[96:99]
	ds_read_b128 v[218:221], v133 offset:2048
	v_mfma_f32_16x16x32_bf16 v[92:95], v[174:177], v[198:201], v[92:95]
	s_waitcnt lgkmcnt(2)
	v_mfma_f32_16x16x32_bf16 v[80:83], v[158:161], v[206:209], v[80:83]
	v_mfma_f32_16x16x32_bf16 v[76:79], v[174:177], v[206:209], v[76:79]
	s_add_u32 s62, s20, s59
	s_addc_u32 s63, s21, 0
	s_add_u32 s24, s62, 0x80
	s_addc_u32 s25, s63, 0
	s_mov_b32 m0, s45
	s_nop 0
	global_load_lds_dwordx4 v139, s[24:25]
	s_mov_b32 m0, s49
	s_nop 0
	global_load_lds_dwordx4 v152, s[24:25]
	s_waitcnt lgkmcnt(1)
	v_mfma_f32_16x16x32_bf16 v[120:123], v[210:213], v[178:181], v[120:123]
	s_waitcnt lgkmcnt(0)
	v_mfma_f32_16x16x32_bf16 v[116:119], v[218:221], v[178:181], v[116:119]
	v_mfma_f32_16x16x32_bf16 v[104:107], v[210:213], v[186:189], v[104:107]
	v_mfma_f32_16x16x32_bf16 v[100:103], v[218:221], v[186:189], v[100:103]
	ds_read_b128 v[214:217], v133 offset:1024
	v_mfma_f32_16x16x32_bf16 v[88:91], v[210:213], v[194:197], v[88:91]
	ds_read_b128 v[222:225], v133 offset:3072
	v_mfma_f32_16x16x32_bf16 v[84:87], v[218:221], v[194:197], v[84:87]
	v_mfma_f32_16x16x32_bf16 v[72:75], v[210:213], v[202:205], v[72:75]
	v_mfma_f32_16x16x32_bf16 v[68:71], v[218:221], v[202:205], v[68:71]
	s_waitcnt lgkmcnt(1)
	v_mfma_f32_16x16x32_bf16 v[120:123], v[214:217], v[182:185], v[120:123]
	s_waitcnt lgkmcnt(0)
	v_mfma_f32_16x16x32_bf16 v[116:119], v[222:225], v[182:185], v[116:119]
	v_mfma_f32_16x16x32_bf16 v[104:107], v[214:217], v[190:193], v[104:107]
	v_mfma_f32_16x16x32_bf16 v[100:103], v[222:225], v[190:193], v[100:103]
	v_mfma_f32_16x16x32_bf16 v[88:91], v[214:217], v[198:201], v[88:91]
	v_mfma_f32_16x16x32_bf16 v[84:87], v[222:225], v[198:201], v[84:87]
	v_mfma_f32_16x16x32_bf16 v[72:75], v[214:217], v[206:209], v[72:75]
	v_mfma_f32_16x16x32_bf16 v[68:71], v[222:225], v[206:209], v[68:71]
	s_waitcnt vmcnt(4) lgkmcnt(0)
	s_barrier
	ds_read_b128 v[178:181], v156 offset:16384
	ds_read_b128 v[186:189], v156 offset:18432
	ds_read_b128 v[194:197], v156 offset:20480
	s_add_u32 s24, s60, 0x80080
	s_addc_u32 s25, s61, 0
	s_mov_b32 m0, s46
	s_nop 0
	global_load_lds_dwordx4 v140, s[24:25]
	s_mov_b32 m0, s50
	s_nop 0
	global_load_lds_dwordx4 v153, s[24:25]
	s_waitcnt lgkmcnt(2)
	v_mfma_f32_16x16x32_bf16 v[64:67], v[146:149], v[178:181], v[64:67]
	v_mfma_f32_16x16x32_bf16 v[60:63], v[170:173], v[178:181], v[60:63]
	ds_read_b128 v[202:205], v156 offset:22528
	s_waitcnt lgkmcnt(2)
	v_mfma_f32_16x16x32_bf16 v[48:51], v[146:149], v[186:189], v[48:51]
	v_mfma_f32_16x16x32_bf16 v[44:47], v[170:173], v[186:189], v[44:47]
	ds_read_b128 v[182:185], v156 offset:17408
	s_waitcnt lgkmcnt(2)
	v_mfma_f32_16x16x32_bf16 v[32:35], v[146:149], v[194:197], v[32:35]
	v_mfma_f32_16x16x32_bf16 v[28:31], v[170:173], v[194:197], v[28:31]
	ds_read_b128 v[190:193], v156 offset:19456
	s_waitcnt lgkmcnt(2)
	v_mfma_f32_16x16x32_bf16 v[16:19], v[146:149], v[202:205], v[16:19]
	v_mfma_f32_16x16x32_bf16 v[12:15], v[170:173], v[202:205], v[12:15]
	ds_read_b128 v[198:201], v156 offset:21504
	s_waitcnt lgkmcnt(2)
	v_mfma_f32_16x16x32_bf16 v[64:67], v[158:161], v[182:185], v[64:67]
	v_mfma_f32_16x16x32_bf16 v[60:63], v[174:177], v[182:185], v[60:63]
	ds_read_b128 v[206:209], v156 offset:23552
	s_waitcnt lgkmcnt(2)
	v_mfma_f32_16x16x32_bf16 v[48:51], v[158:161], v[190:193], v[48:51]
	v_mfma_f32_16x16x32_bf16 v[44:47], v[174:177], v[190:193], v[44:47]
	s_waitcnt lgkmcnt(1)
	v_mfma_f32_16x16x32_bf16 v[32:35], v[158:161], v[198:201], v[32:35]
	v_mfma_f32_16x16x32_bf16 v[28:31], v[174:177], v[198:201], v[28:31]
	s_waitcnt lgkmcnt(0)
	v_mfma_f32_16x16x32_bf16 v[16:19], v[158:161], v[206:209], v[16:19]
	v_mfma_f32_16x16x32_bf16 v[12:15], v[174:177], v[206:209], v[12:15]
	s_add_u32 s24, s62, 0x80080
	s_addc_u32 s25, s63, 0
	s_mov_b32 m0, s47
	s_nop 0
	global_load_lds_dwordx4 v139, s[24:25]
	s_mov_b32 m0, s51
	s_nop 0
	global_load_lds_dwordx4 v152, s[24:25]
	v_mfma_f32_16x16x32_bf16 v[56:59], v[210:213], v[178:181], v[56:59]
	s_add_u32 s24, s62, 0x100
	s_addc_u32 s25, s63, 0
	s_add_u32 s60, s60, 0x100
	v_mfma_f32_16x16x32_bf16 v[52:55], v[218:221], v[178:181], v[52:55]
	s_addc_u32 s61, s61, 0
	v_mfma_f32_16x16x32_bf16 v[40:43], v[210:213], v[186:189], v[40:43]
	v_mfma_f32_16x16x32_bf16 v[36:39], v[218:221], v[186:189], v[36:39]
	v_mfma_f32_16x16x32_bf16 v[24:27], v[210:213], v[194:197], v[24:27]
	v_mfma_f32_16x16x32_bf16 v[20:23], v[218:221], v[194:197], v[20:23]
	v_mfma_f32_16x16x32_bf16 v[4:7], v[210:213], v[202:205], v[4:7]
	v_mfma_f32_16x16x32_bf16 v[8:11], v[218:221], v[202:205], v[8:11]
	v_mfma_f32_16x16x32_bf16 v[56:59], v[214:217], v[182:185], v[56:59]
	v_mfma_f32_16x16x32_bf16 v[52:55], v[222:225], v[182:185], v[52:55]
	v_mfma_f32_16x16x32_bf16 v[40:43], v[214:217], v[190:193], v[40:43]
	v_mfma_f32_16x16x32_bf16 v[36:39], v[222:225], v[190:193], v[36:39]
	v_mfma_f32_16x16x32_bf16 v[24:27], v[214:217], v[198:201], v[24:27]
	v_mfma_f32_16x16x32_bf16 v[20:23], v[222:225], v[198:201], v[20:23]
	v_mfma_f32_16x16x32_bf16 v[4:7], v[214:217], v[206:209], v[4:7]
	v_mfma_f32_16x16x32_bf16 v[8:11], v[222:225], v[206:209], v[8:11]
	s_waitcnt vmcnt(2) lgkmcnt(0)
	s_barrier
; template <class Epi, class Sched>
; __device__ __forceinline__ void gemm_simple(PG8_LAS unsigned char* lds, const Gemm g, const Sched& S, const Epi& E, int wave_s) {
;     ...
;         for (; t < nt; t += 2) {
;             const bool last = (t == nt - 2);
;             PG8_TILE(0, cA + (size_t)(t + 1) * kstep, cB + (size_t)(t + 1) * kstep, true);
;             const char* a2 = last ? nA : cA + (size_t)(t + 2) * kstep; const char* b2 = last ? nB : cB + (size_t)(t + 2) * kstep;
;             PG8_TILE(1, a2, b2, (!last || has_next));
	ds_read_b128 v[146:149], v134
	ds_read_b128 v[178:181], v156 offset:32768
	ds_read_b128 v[170:173], v134 offset:2048
	ds_read_b128 v[186:189], v156 offset:34816
	ds_read_b128 v[194:197], v156 offset:36864
	s_cmp_eq_u32 s59, s22
	s_cselect_b32 s25, s13, s25
	s_cselect_b32 s24, s56, s24
	s_cselect_b32 s61, s5, s61
	s_cselect_b32 s60, s57, s60
	s_mov_b32 m0, s29
	s_nop 0
	global_load_lds_dwordx4 v140, s[60:61]
	s_mov_b32 m0, s35
	s_nop 0
	global_load_lds_dwordx4 v153, s[60:61]
	s_waitcnt lgkmcnt(3)
	v_mfma_f32_16x16x32_bf16 v[128:131], v[146:149], v[178:181], v[128:131]
	s_waitcnt lgkmcnt(2)
	v_mfma_f32_16x16x32_bf16 v[124:127], v[170:173], v[178:181], v[124:127]
	ds_read_b128 v[202:205], v156 offset:38912
	s_waitcnt lgkmcnt(2)
	v_mfma_f32_16x16x32_bf16 v[112:115], v[146:149], v[186:189], v[112:115]
	v_mfma_f32_16x16x32_bf16 v[108:111], v[170:173], v[186:189], v[108:111]
	ds_read_b128 v[158:161], v134 offset:1024
	ds_read_b128 v[182:185], v156 offset:33792
	s_waitcnt lgkmcnt(3)
	v_mfma_f32_16x16x32_bf16 v[96:99], v[146:149], v[194:197], v[96:99]
	ds_read_b128 v[174:177], v134 offset:3072
	v_mfma_f32_16x16x32_bf16 v[92:95], v[170:173], v[194:197], v[92:95]
	ds_read_b128 v[190:193], v156 offset:35840
	s_waitcnt lgkmcnt(4)
	v_mfma_f32_16x16x32_bf16 v[80:83], v[146:149], v[202:205], v[80:83]
	v_mfma_f32_16x16x32_bf16 v[76:79], v[170:173], v[202:205], v[76:79]
	ds_read_b128 v[198:201], v156 offset:37888
	s_waitcnt lgkmcnt(3)
	v_mfma_f32_16x16x32_bf16 v[128:131], v[158:161], v[182:185], v[128:131]
	s_waitcnt lgkmcnt(2)
	v_mfma_f32_16x16x32_bf16 v[124:127], v[174:177], v[182:185], v[124:127]
	ds_read_b128 v[206:209], v156 offset:39936
	s_waitcnt lgkmcnt(2)
	v_mfma_f32_16x16x32_bf16 v[112:115], v[158:161], v[190:193], v[112:115]
	v_mfma_f32_16x16x32_bf16 v[108:111], v[174:177], v[190:193], v[108:111]
	ds_read_b128 v[210:213], v135
	s_waitcnt lgkmcnt(2)
	v_mfma_f32_16x16x32_bf16 v[96:99], v[158:161], v[198:201], v[96:99]
	ds_read_b128 v[218:221], v135 offset:2048
	v_mfma_f32_16x16x32_bf16 v[92:95], v[174:177], v[198:201], v[92:95]
	s_waitcnt lgkmcnt(2)
	v_mfma_f32_16x16x32_bf16 v[80:83], v[158:161], v[206:209], v[80:83]
	v_mfma_f32_16x16x32_bf16 v[76:79], v[174:177], v[206:209], v[76:79]
	s_mov_b32 m0, s19
	s_nop 0
	global_load_lds_dwordx4 v139, s[24:25]
	s_mov_b32 m0, s36
	s_nop 0
	global_load_lds_dwordx4 v152, s[24:25]
	s_waitcnt lgkmcnt(1)
	v_mfma_f32_16x16x32_bf16 v[120:123], v[210:213], v[178:181], v[120:123]
	s_waitcnt lgkmcnt(0)
	v_mfma_f32_16x16x32_bf16 v[116:119], v[218:221], v[178:181], v[116:119]
	v_mfma_f32_16x16x32_bf16 v[104:107], v[210:213], v[186:189], v[104:107]
	v_mfma_f32_16x16x32_bf16 v[100:103], v[218:221], v[186:189], v[100:103]
	ds_read_b128 v[214:217], v135 offset:1024
	v_mfma_f32_16x16x32_bf16 v[88:91], v[210:213], v[194:197], v[88:91]
	ds_read_b128 v[222:225], v135 offset:3072
	v_mfma_f32_16x16x32_bf16 v[84:87], v[218:221], v[194:197], v[84:87]
	v_mfma_f32_16x16x32_bf16 v[72:75], v[210:213], v[202:205], v[72:75]
	v_mfma_f32_16x16x32_bf16 v[68:71], v[218:221], v[202:205], v[68:71]
	s_waitcnt lgkmcnt(1)
	v_mfma_f32_16x16x32_bf16 v[120:123], v[214:217], v[182:185], v[120:123]
	s_waitcnt lgkmcnt(0)
	v_mfma_f32_16x16x32_bf16 v[116:119], v[222:225], v[182:185], v[116:119]
	v_mfma_f32_16x16x32_bf16 v[104:107], v[214:217], v[190:193], v[104:107]
	v_mfma_f32_16x16x32_bf16 v[100:103], v[222:225], v[190:193], v[100:103]
	v_mfma_f32_16x16x32_bf16 v[88:91], v[214:217], v[198:201], v[88:91]
	v_mfma_f32_16x16x32_bf16 v[84:87], v[222:225], v[198:201], v[84:87]
	v_mfma_f32_16x16x32_bf16 v[72:75], v[214:217], v[206:209], v[72:75]
	v_mfma_f32_16x16x32_bf16 v[68:71], v[222:225], v[206:209], v[68:71]
	s_waitcnt vmcnt(4) lgkmcnt(0)
	s_barrier
; #define LAS __attribute__((address_space(3)))
; __device__ __forceinline__ void rstd_table(const float* ssq, LAS unsigned char* lds, const Unit& u, int tid, int par) {
;     if (tid < 256) { const f32x4* p = (const f32x4*)(ssq + (size_t)(u.pm * 256 + tid) * 32); f32x4 a = p[0];
; #pragma unroll
;         for (int i = 1; i < 8; ++i) a += p[i];
;         ((LAS float*)(lds + 131072 + par * 1024))[tid] = 1.0f / sqrtf(((a[0] + a[1]) + (a[2] + a[3])) * (1.0f / DM) + 1e-6f); }
	ds_read_b128 v[178:181], v156 offset:49152
	ds_read_b128 v[186:189], v156 offset:51200
	ds_read_b128 v[194:197], v156 offset:53248
	s_add_u32 s60, s60, 0x80000
	s_addc_u32 s61, s61, 0
	s_mov_b32 m0, s37
	s_nop 0
	global_load_lds_dwordx4 v140, s[60:61]
	s_mov_b32 m0, s38
	s_nop 0
	global_load_lds_dwordx4 v153, s[60:61]
	s_waitcnt lgkmcnt(2)
	v_mfma_f32_16x16x32_bf16 v[64:67], v[146:149], v[178:181], v[64:67]
	v_mfma_f32_16x16x32_bf16 v[60:63], v[170:173], v[178:181], v[60:63]
	ds_read_b128 v[202:205], v156 offset:55296
	s_waitcnt lgkmcnt(2)
	v_mfma_f32_16x16x32_bf16 v[48:51], v[146:149], v[186:189], v[48:51]
	v_mfma_f32_16x16x32_bf16 v[44:47], v[170:173], v[186:189], v[44:47]
	ds_read_b128 v[182:185], v156 offset:50176
	s_waitcnt lgkmcnt(2)
	v_mfma_f32_16x16x32_bf16 v[32:35], v[146:149], v[194:197], v[32:35]
	v_mfma_f32_16x16x32_bf16 v[28:31], v[170:173], v[194:197], v[28:31]
	ds_read_b128 v[190:193], v156 offset:52224
	s_waitcnt lgkmcnt(2)
	v_mfma_f32_16x16x32_bf16 v[16:19], v[146:149], v[202:205], v[16:19]
	v_mfma_f32_16x16x32_bf16 v[12:15], v[170:173], v[202:205], v[12:15]
	ds_read_b128 v[198:201], v156 offset:54272
	s_waitcnt lgkmcnt(2)
	v_mfma_f32_16x16x32_bf16 v[64:67], v[158:161], v[182:185], v[64:67]
	v_mfma_f32_16x16x32_bf16 v[60:63], v[174:177], v[182:185], v[60:63]
	ds_read_b128 v[206:209], v156 offset:56320
	s_waitcnt lgkmcnt(2)
	v_mfma_f32_16x16x32_bf16 v[48:51], v[158:161], v[190:193], v[48:51]
	v_mfma_f32_16x16x32_bf16 v[44:47], v[174:177], v[190:193], v[44:47]
	s_waitcnt lgkmcnt(1)
	v_mfma_f32_16x16x32_bf16 v[32:35], v[158:161], v[198:201], v[32:35]
	v_mfma_f32_16x16x32_bf16 v[28:31], v[174:177], v[198:201], v[28:31]
	s_waitcnt lgkmcnt(0)
	v_mfma_f32_16x16x32_bf16 v[16:19], v[158:161], v[206:209], v[16:19]
	v_mfma_f32_16x16x32_bf16 v[12:15], v[174:177], v[206:209], v[12:15]
	s_add_u32 s24, s24, 0x80000
	s_addc_u32 s25, s25, 0
	s_mov_b32 m0, s39
	s_nop 0
	global_load_lds_dwordx4 v139, s[24:25]
	s_mov_b32 m0, s40
	s_nop 0
	global_load_lds_dwordx4 v152, s[24:25]
	v_mfma_f32_16x16x32_bf16 v[56:59], v[210:213], v[178:181], v[56:59]
	s_add_i32 s58, s58, 2
	s_add_u32 s22, s22, 0xffffff00
	s_addc_u32 s23, s23, -1
	v_mfma_f32_16x16x32_bf16 v[52:55], v[218:221], v[178:181], v[52:55]
	s_add_u32 s20, s20, 0x100
	s_addc_u32 s21, s21, 0
	s_add_u32 s10, s10, 0x100
	v_mfma_f32_16x16x32_bf16 v[40:43], v[210:213], v[186:189], v[40:43]
	s_addc_u32 s11, s11, 0
	s_cmp_lt_u32 s58, 30
	v_mfma_f32_16x16x32_bf16 v[36:39], v[218:221], v[186:189], v[36:39]
	v_mfma_f32_16x16x32_bf16 v[24:27], v[210:213], v[194:197], v[24:27]
	v_mfma_f32_16x16x32_bf16 v[20:23], v[218:221], v[194:197], v[20:23]
	v_mfma_f32_16x16x32_bf16 v[4:7], v[210:213], v[202:205], v[4:7]
	v_mfma_f32_16x16x32_bf16 v[8:11], v[218:221], v[202:205], v[8:11]
	v_mfma_f32_16x16x32_bf16 v[56:59], v[214:217], v[182:185], v[56:59]
	v_mfma_f32_16x16x32_bf16 v[52:55], v[222:225], v[182:185], v[52:55]
	v_mfma_f32_16x16x32_bf16 v[40:43], v[214:217], v[190:193], v[40:43]
	v_mfma_f32_16x16x32_bf16 v[36:39], v[222:225], v[190:193], v[36:39]
	v_mfma_f32_16x16x32_bf16 v[24:27], v[214:217], v[198:201], v[24:27]
	v_mfma_f32_16x16x32_bf16 v[20:23], v[222:225], v[198:201], v[20:23]
	v_mfma_f32_16x16x32_bf16 v[4:7], v[214:217], v[206:209], v[4:7]
	v_mfma_f32_16x16x32_bf16 v[8:11], v[222:225], v[206:209], v[8:11]
	s_cbranch_scc1 .LBB0_221
	s_nor_b64 s[10:11], s[6:7], s[8:9]
	s_and_saveexec_b64 s[20:21], s[10:11]
	s_cbranch_execz .LBB0_211
	v_lshl_add_u32 v132, s12, 8, v138
	v_ashrrev_i32_e32 v133, 31, v132
	v_readlane_b32 s10, v255, 2
	v_lshlrev_b64 v[132:133], 7, v[132:133]
	v_readlane_b32 s11, v255, 3
	s_lshl_b32 s5, s53, 10
	s_and_b32 s5, s5, 0x400
	v_lshl_add_u64 v[136:137], s[10:11], 0, v[132:133]
	global_load_dwordx4 v[132:135], v[136:137], off offset:48
	global_load_dwordx4 v[146:149], v[136:137], off offset:32
	global_load_dwordx4 v[158:161], v[136:137], off
	global_load_dwordx4 v[170:173], v[136:137], off offset:16
	s_waitcnt vmcnt(0)
	v_pk_add_f32 v[142:143], v[160:161], v[172:173]
	v_pk_add_f32 v[144:145], v[158:159], v[170:171]
	v_pk_add_f32 v[142:143], v[142:143], v[148:149]
	v_pk_add_f32 v[144:145], v[144:145], v[146:147]
	v_pk_add_f32 v[142:143], v[142:143], v[134:135]
	v_pk_add_f32 v[144:145], v[144:145], v[132:133]
	global_load_dwordx4 v[132:135], v[136:137], off offset:112
	global_load_dwordx4 v[146:149], v[136:137], off offset:96
	global_load_dwordx4 v[158:161], v[136:137], off offset:80
	global_load_dwordx4 v[170:173], v[136:137], off offset:64
	s_waitcnt vmcnt(0)
	v_pk_add_f32 v[136:137], v[142:143], v[172:173]
	v_pk_add_f32 v[142:143], v[144:145], v[170:171]
	v_pk_add_f32 v[136:137], v[136:137], v[160:161]
	v_pk_add_f32 v[142:143], v[142:143], v[158:159]
	v_pk_add_f32 v[136:137], v[136:137], v[148:149]
	v_pk_add_f32 v[142:143], v[142:143], v[146:147]
	v_pk_add_f32 v[134:135], v[136:137], v[134:135]
	v_pk_add_f32 v[132:133], v[142:143], v[132:133]
	s_nop 0
	v_pk_mov_b32 v[136:137], v[132:133], v[134:135] op_sel:[1,0]
	v_mov_b32_e32 v133, v135
	v_pk_add_f32 v[132:133], v[136:137], v[132:133]
	s_nop 0
	v_add_f32_e32 v132, v132, v133
	v_fmamk_f32 v132, v132, 0x3a000000, v164
	v_cmp_gt_f32_e32 vcc, s69, v132
	v_mul_f32_e32 v133, 0x4f800000, v132
	s_nop 0
	v_cndmask_b32_e32 v132, v132, v133, vcc
	v_sqrt_f32_e32 v133, v132
	s_nop 0
	v_add_u32_e32 v134, -1, v133
	v_fma_f32 v135, -v134, v133, v132
	v_cmp_ge_f32_e64 s[10:11], 0, v135
	v_add_u32_e32 v135, 1, v133
	s_nop 0
	v_cndmask_b32_e64 v134, v133, v134, s[10:11]
	v_fma_f32 v133, -v135, v133, v132
	v_cmp_lt_f32_e64 s[10:11], 0, v133
	s_nop 1
	v_cndmask_b32_e64 v133, v134, v135, s[10:11]
	v_mul_f32_e32 v134, 0x37800000, v133
	v_cndmask_b32_e32 v133, v133, v134, vcc
	v_cmp_class_f32_e32 vcc, v132, v165
	s_nop 1
	v_cndmask_b32_e32 v132, v133, v132, vcc
	v_div_scale_f32 v133, s[10:11], v132, v132, 1.0
	v_rcp_f32_e32 v134, v133
	s_nop 0
	v_fma_f32 v135, -v133, v134, 1.0
	v_fmac_f32_e32 v134, v135, v134
	v_div_scale_f32 v135, vcc, 1.0, v132, 1.0
	v_mul_f32_e32 v136, v135, v134
	v_fma_f32 v137, -v133, v136, v135
	v_fmac_f32_e32 v136, v137, v134
	v_fma_f32 v133, -v133, v136, v135
	v_div_fmas_f32 v133, v133, v134, v136
	v_div_fixup_f32 v132, v133, v132, 1.0
	v_add_u32_e32 v133, s5, v154
	ds_write_b32 v133, v132
	s_branch .LBB0_211

; template <class Epi, class Sched>
; __device__ __forceinline__ void gemm_simple(PG8_LAS unsigned char* lds, const Gemm g, const Sched& S, const Epi& E, int wave_s) {
;     ...
;         for (; t < nt; t += 2) {
;             const bool last = (t == nt - 2);
;             PG8_TILE(0, cA + (size_t)(t + 1) * kstep, cB + (size_t)(t + 1) * kstep, true);
.LBB0_275:
	s_waitcnt vmcnt(2) lgkmcnt(0)
	s_barrier
	ds_read_b128 v[136:139], v132
	ds_read_b128 v[156:159], v174
	ds_read_b128 v[146:149], v132 offset:2048
	ds_read_b128 v[180:183], v174 offset:2048
	ds_read_b128 v[188:191], v174 offset:4096
	s_add_u32 s63, s10, s62
	s_addc_u32 s64, s11, 0
	s_add_u32 s28, s63, 0x80
	s_addc_u32 s29, s64, 0
	s_mov_b32 m0, s49
	s_nop 0
	global_load_lds_dwordx4 v163, s[28:29]
	s_mov_b32 m0, s53
	s_nop 0
	global_load_lds_dwordx4 v171, s[28:29]
	s_waitcnt lgkmcnt(3)
	v_mfma_f32_16x16x32_bf16 v[128:131], v[136:139], v[156:159], v[128:131]
	s_waitcnt lgkmcnt(2)
	v_mfma_f32_16x16x32_bf16 v[124:127], v[146:149], v[156:159], v[124:127]
	ds_read_b128 v[196:199], v174 offset:6144
	s_waitcnt lgkmcnt(2)
	v_mfma_f32_16x16x32_bf16 v[112:115], v[136:139], v[180:183], v[112:115]
	v_mfma_f32_16x16x32_bf16 v[108:111], v[146:149], v[180:183], v[108:111]
	ds_read_b128 v[142:145], v132 offset:1024
	ds_read_b128 v[176:179], v174 offset:1024
	s_waitcnt lgkmcnt(3)
	v_mfma_f32_16x16x32_bf16 v[96:99], v[136:139], v[188:191], v[96:99]
	ds_read_b128 v[152:155], v132 offset:3072
	v_mfma_f32_16x16x32_bf16 v[92:95], v[146:149], v[188:191], v[92:95]
	ds_read_b128 v[184:187], v174 offset:3072
	s_waitcnt lgkmcnt(4)
	v_mfma_f32_16x16x32_bf16 v[80:83], v[136:139], v[196:199], v[80:83]
	v_mfma_f32_16x16x32_bf16 v[76:79], v[146:149], v[196:199], v[76:79]
	ds_read_b128 v[192:195], v174 offset:5120
	s_waitcnt lgkmcnt(3)
	v_mfma_f32_16x16x32_bf16 v[128:131], v[142:145], v[176:179], v[128:131]
	s_waitcnt lgkmcnt(2)
	v_mfma_f32_16x16x32_bf16 v[124:127], v[152:155], v[176:179], v[124:127]
	ds_read_b128 v[200:203], v174 offset:7168
	s_waitcnt lgkmcnt(2)
	v_mfma_f32_16x16x32_bf16 v[112:115], v[142:145], v[184:187], v[112:115]
	v_mfma_f32_16x16x32_bf16 v[108:111], v[152:155], v[184:187], v[108:111]
	ds_read_b128 v[204:207], v133
	s_waitcnt lgkmcnt(2)
	v_mfma_f32_16x16x32_bf16 v[96:99], v[142:145], v[192:195], v[96:99]
	ds_read_b128 v[212:215], v133 offset:2048
	v_mfma_f32_16x16x32_bf16 v[92:95], v[152:155], v[192:195], v[92:95]
	s_waitcnt lgkmcnt(2)
	v_mfma_f32_16x16x32_bf16 v[80:83], v[142:145], v[200:203], v[80:83]
	v_mfma_f32_16x16x32_bf16 v[76:79], v[152:155], v[200:203], v[76:79]
	s_add_u32 s65, s24, s62
	s_addc_u32 s66, s25, 0
	s_add_u32 s28, s65, 0x80
	s_addc_u32 s29, s66, 0
	s_mov_b32 m0, s50
	s_nop 0
	global_load_lds_dwordx4 v162, s[28:29]
	s_mov_b32 m0, s54
	s_nop 0
	global_load_lds_dwordx4 v170, s[28:29]
	s_waitcnt lgkmcnt(1)
	v_mfma_f32_16x16x32_bf16 v[120:123], v[204:207], v[156:159], v[120:123]
	s_waitcnt lgkmcnt(0)
	v_mfma_f32_16x16x32_bf16 v[116:119], v[212:215], v[156:159], v[116:119]
	v_mfma_f32_16x16x32_bf16 v[104:107], v[204:207], v[180:183], v[104:107]
	v_mfma_f32_16x16x32_bf16 v[100:103], v[212:215], v[180:183], v[100:103]
	ds_read_b128 v[208:211], v133 offset:1024
	v_mfma_f32_16x16x32_bf16 v[88:91], v[204:207], v[188:191], v[88:91]
	ds_read_b128 v[216:219], v133 offset:3072
	v_mfma_f32_16x16x32_bf16 v[84:87], v[212:215], v[188:191], v[84:87]
	v_mfma_f32_16x16x32_bf16 v[72:75], v[204:207], v[196:199], v[72:75]
	v_mfma_f32_16x16x32_bf16 v[68:71], v[212:215], v[196:199], v[68:71]
	s_waitcnt lgkmcnt(1)
	v_mfma_f32_16x16x32_bf16 v[120:123], v[208:211], v[176:179], v[120:123]
	s_waitcnt lgkmcnt(0)
	v_mfma_f32_16x16x32_bf16 v[116:119], v[216:219], v[176:179], v[116:119]
	v_mfma_f32_16x16x32_bf16 v[104:107], v[208:211], v[184:187], v[104:107]
	v_mfma_f32_16x16x32_bf16 v[100:103], v[216:219], v[184:187], v[100:103]
	v_mfma_f32_16x16x32_bf16 v[88:91], v[208:211], v[192:195], v[88:91]
	v_mfma_f32_16x16x32_bf16 v[84:87], v[216:219], v[192:195], v[84:87]
	v_mfma_f32_16x16x32_bf16 v[72:75], v[208:211], v[200:203], v[72:75]
	v_mfma_f32_16x16x32_bf16 v[68:71], v[216:219], v[200:203], v[68:71]
	s_waitcnt vmcnt(4) lgkmcnt(0)
	s_barrier
	ds_read_b128 v[156:159], v174 offset:16384
	ds_read_b128 v[180:183], v174 offset:18432
	ds_read_b128 v[188:191], v174 offset:20480
	s_add_u32 s28, s63, 0x80080
	s_addc_u32 s29, s64, 0
	s_mov_b32 m0, s51
	s_nop 0
	global_load_lds_dwordx4 v163, s[28:29]
	s_mov_b32 m0, s55
	s_nop 0
	global_load_lds_dwordx4 v171, s[28:29]
	s_waitcnt lgkmcnt(2)
	v_mfma_f32_16x16x32_bf16 v[64:67], v[136:139], v[156:159], v[64:67]
	v_mfma_f32_16x16x32_bf16 v[60:63], v[146:149], v[156:159], v[60:63]
	ds_read_b128 v[196:199], v174 offset:22528
	s_waitcnt lgkmcnt(2)
	v_mfma_f32_16x16x32_bf16 v[48:51], v[136:139], v[180:183], v[48:51]
	v_mfma_f32_16x16x32_bf16 v[44:47], v[146:149], v[180:183], v[44:47]
	ds_read_b128 v[176:179], v174 offset:17408
	s_waitcnt lgkmcnt(2)
	v_mfma_f32_16x16x32_bf16 v[32:35], v[136:139], v[188:191], v[32:35]
	v_mfma_f32_16x16x32_bf16 v[28:31], v[146:149], v[188:191], v[28:31]
	ds_read_b128 v[184:187], v174 offset:19456
	s_waitcnt lgkmcnt(2)
	v_mfma_f32_16x16x32_bf16 v[16:19], v[136:139], v[196:199], v[16:19]
	v_mfma_f32_16x16x32_bf16 v[12:15], v[146:149], v[196:199], v[12:15]
	ds_read_b128 v[192:195], v174 offset:21504
	s_waitcnt lgkmcnt(2)
	v_mfma_f32_16x16x32_bf16 v[64:67], v[142:145], v[176:179], v[64:67]
	v_mfma_f32_16x16x32_bf16 v[60:63], v[152:155], v[176:179], v[60:63]
	ds_read_b128 v[200:203], v174 offset:23552
	s_waitcnt lgkmcnt(2)
	v_mfma_f32_16x16x32_bf16 v[48:51], v[142:145], v[184:187], v[48:51]
	v_mfma_f32_16x16x32_bf16 v[44:47], v[152:155], v[184:187], v[44:47]
	s_waitcnt lgkmcnt(1)
	v_mfma_f32_16x16x32_bf16 v[32:35], v[142:145], v[192:195], v[32:35]
	v_mfma_f32_16x16x32_bf16 v[28:31], v[152:155], v[192:195], v[28:31]
	s_waitcnt lgkmcnt(0)
	v_mfma_f32_16x16x32_bf16 v[16:19], v[142:145], v[200:203], v[16:19]
	v_mfma_f32_16x16x32_bf16 v[12:15], v[152:155], v[200:203], v[12:15]
	s_add_u32 s28, s65, 0x80080
	s_addc_u32 s29, s66, 0
	s_mov_b32 m0, s52
	s_nop 0
	global_load_lds_dwordx4 v162, s[28:29]
	s_mov_b32 m0, s56
	s_nop 0
	global_load_lds_dwordx4 v170, s[28:29]
	v_mfma_f32_16x16x32_bf16 v[56:59], v[204:207], v[156:159], v[56:59]
	s_add_u32 s28, s65, 0x100
	s_addc_u32 s29, s66, 0
	s_add_u32 s63, s63, 0x100
	v_mfma_f32_16x16x32_bf16 v[52:55], v[212:215], v[156:159], v[52:55]
	s_addc_u32 s64, s64, 0
	v_mfma_f32_16x16x32_bf16 v[40:43], v[204:207], v[180:183], v[40:43]
	v_mfma_f32_16x16x32_bf16 v[36:39], v[212:215], v[180:183], v[36:39]
	v_mfma_f32_16x16x32_bf16 v[24:27], v[204:207], v[188:191], v[24:27]
	v_mfma_f32_16x16x32_bf16 v[20:23], v[212:215], v[188:191], v[20:23]
	v_mfma_f32_16x16x32_bf16 v[8:11], v[204:207], v[196:199], v[8:11]
	v_mfma_f32_16x16x32_bf16 v[4:7], v[212:215], v[196:199], v[4:7]
	v_mfma_f32_16x16x32_bf16 v[56:59], v[208:211], v[176:179], v[56:59]
	v_mfma_f32_16x16x32_bf16 v[52:55], v[216:219], v[176:179], v[52:55]
	v_mfma_f32_16x16x32_bf16 v[40:43], v[208:211], v[184:187], v[40:43]
	v_mfma_f32_16x16x32_bf16 v[36:39], v[216:219], v[184:187], v[36:39]
	v_mfma_f32_16x16x32_bf16 v[24:27], v[208:211], v[192:195], v[24:27]
	v_mfma_f32_16x16x32_bf16 v[20:23], v[216:219], v[192:195], v[20:23]
	v_mfma_f32_16x16x32_bf16 v[8:11], v[208:211], v[200:203], v[8:11]
	v_mfma_f32_16x16x32_bf16 v[4:7], v[216:219], v[200:203], v[4:7]
	s_waitcnt vmcnt(2) lgkmcnt(0)
	s_barrier
; template <class Epi, class Sched>
; __device__ __forceinline__ void gemm_simple(PG8_LAS unsigned char* lds, const Gemm g, const Sched& S, const Epi& E, int wave_s) {
;     ...
;             const char* a2 = last ? nA : cA + (size_t)(t + 2) * kstep; const char* b2 = last ? nB : cB + (size_t)(t + 2) * kstep;
;             PG8_TILE(1, a2, b2, (!last || has_next));
	ds_read_b128 v[136:139], v134
	ds_read_b128 v[156:159], v174 offset:32768
	ds_read_b128 v[146:149], v134 offset:2048
	ds_read_b128 v[180:183], v174 offset:34816
	ds_read_b128 v[188:191], v174 offset:36864
	s_cmp_eq_u32 s62, s26
	s_cselect_b32 s29, s15, s29
	s_cselect_b32 s28, s35, s28
	s_cselect_b32 s65, s13, s64
	s_cselect_b32 s64, s60, s63
	s_mov_b32 m0, s38
	s_nop 0
	global_load_lds_dwordx4 v163, s[64:65]
	s_mov_b32 m0, s39
	s_nop 0
	global_load_lds_dwordx4 v171, s[64:65]
	s_waitcnt lgkmcnt(3)
	v_mfma_f32_16x16x32_bf16 v[128:131], v[136:139], v[156:159], v[128:131]
	s_waitcnt lgkmcnt(2)
	v_mfma_f32_16x16x32_bf16 v[124:127], v[146:149], v[156:159], v[124:127]
	ds_read_b128 v[196:199], v174 offset:38912
	s_waitcnt lgkmcnt(2)
	v_mfma_f32_16x16x32_bf16 v[112:115], v[136:139], v[180:183], v[112:115]
	v_mfma_f32_16x16x32_bf16 v[108:111], v[146:149], v[180:183], v[108:111]
	ds_read_b128 v[142:145], v134 offset:1024
	ds_read_b128 v[176:179], v174 offset:33792
	s_waitcnt lgkmcnt(3)
	v_mfma_f32_16x16x32_bf16 v[96:99], v[136:139], v[188:191], v[96:99]
	ds_read_b128 v[152:155], v134 offset:3072
	v_mfma_f32_16x16x32_bf16 v[92:95], v[146:149], v[188:191], v[92:95]
	ds_read_b128 v[184:187], v174 offset:35840
	s_waitcnt lgkmcnt(4)
	v_mfma_f32_16x16x32_bf16 v[80:83], v[136:139], v[196:199], v[80:83]
	v_mfma_f32_16x16x32_bf16 v[76:79], v[146:149], v[196:199], v[76:79]
	ds_read_b128 v[192:195], v174 offset:37888
	s_waitcnt lgkmcnt(3)
	v_mfma_f32_16x16x32_bf16 v[128:131], v[142:145], v[176:179], v[128:131]
	s_waitcnt lgkmcnt(2)
	v_mfma_f32_16x16x32_bf16 v[124:127], v[152:155], v[176:179], v[124:127]
	ds_read_b128 v[200:203], v174 offset:39936
	s_waitcnt lgkmcnt(2)
	v_mfma_f32_16x16x32_bf16 v[112:115], v[142:145], v[184:187], v[112:115]
	v_mfma_f32_16x16x32_bf16 v[108:111], v[152:155], v[184:187], v[108:111]
	ds_read_b128 v[204:207], v135
	s_waitcnt lgkmcnt(2)
	v_mfma_f32_16x16x32_bf16 v[96:99], v[142:145], v[192:195], v[96:99]
	ds_read_b128 v[212:215], v135 offset:2048
	v_mfma_f32_16x16x32_bf16 v[92:95], v[152:155], v[192:195], v[92:95]
	s_waitcnt lgkmcnt(2)
	v_mfma_f32_16x16x32_bf16 v[80:83], v[142:145], v[200:203], v[80:83]
	v_mfma_f32_16x16x32_bf16 v[76:79], v[152:155], v[200:203], v[76:79]
	s_mov_b32 m0, s23
	s_nop 0
	global_load_lds_dwordx4 v162, s[28:29]
	s_mov_b32 m0, s40
	s_nop 0
	global_load_lds_dwordx4 v170, s[28:29]
	s_waitcnt lgkmcnt(1)
	v_mfma_f32_16x16x32_bf16 v[120:123], v[204:207], v[156:159], v[120:123]
	s_waitcnt lgkmcnt(0)
	v_mfma_f32_16x16x32_bf16 v[116:119], v[212:215], v[156:159], v[116:119]
	v_mfma_f32_16x16x32_bf16 v[104:107], v[204:207], v[180:183], v[104:107]
	v_mfma_f32_16x16x32_bf16 v[100:103], v[212:215], v[180:183], v[100:103]
	ds_read_b128 v[208:211], v135 offset:1024
	v_mfma_f32_16x16x32_bf16 v[88:91], v[204:207], v[188:191], v[88:91]
	ds_read_b128 v[216:219], v135 offset:3072
	v_mfma_f32_16x16x32_bf16 v[84:87], v[212:215], v[188:191], v[84:87]
	v_mfma_f32_16x16x32_bf16 v[72:75], v[204:207], v[196:199], v[72:75]
	v_mfma_f32_16x16x32_bf16 v[68:71], v[212:215], v[196:199], v[68:71]
	s_waitcnt lgkmcnt(1)
	v_mfma_f32_16x16x32_bf16 v[120:123], v[208:211], v[176:179], v[120:123]
	s_waitcnt lgkmcnt(0)
	v_mfma_f32_16x16x32_bf16 v[116:119], v[216:219], v[176:179], v[116:119]
	v_mfma_f32_16x16x32_bf16 v[104:107], v[208:211], v[184:187], v[104:107]
	v_mfma_f32_16x16x32_bf16 v[100:103], v[216:219], v[184:187], v[100:103]
	v_mfma_f32_16x16x32_bf16 v[88:91], v[208:211], v[192:195], v[88:91]
	v_mfma_f32_16x16x32_bf16 v[84:87], v[216:219], v[192:195], v[84:87]
	v_mfma_f32_16x16x32_bf16 v[72:75], v[208:211], v[200:203], v[72:75]
	v_mfma_f32_16x16x32_bf16 v[68:71], v[216:219], v[200:203], v[68:71]
	s_waitcnt vmcnt(4) lgkmcnt(0)
	s_barrier
; #define LAS __attribute__((address_space(3)))
; __device__ __forceinline__ void rstd_table(const float* ssq, LAS unsigned char* lds, const Unit& u, int tid, int par) {
;     if (tid < 256) { const f32x4* p = (const f32x4*)(ssq + (size_t)(u.pm * 256 + tid) * 32); f32x4 a = p[0];
; #pragma unroll
;         for (int i = 1; i < 8; ++i) a += p[i];
;         ((LAS float*)(lds + 131072 + par * 1024))[tid] = 1.0f / sqrtf(((a[0] + a[1]) + (a[2] + a[3])) * (1.0f / DM) + 1e-6f); }
	ds_read_b128 v[156:159], v174 offset:49152
	ds_read_b128 v[180:183], v174 offset:51200
	ds_read_b128 v[188:191], v174 offset:53248
	s_add_u32 s64, s64, 0x80000
	s_addc_u32 s65, s65, 0
	s_mov_b32 m0, s41
	s_nop 0
	global_load_lds_dwordx4 v163, s[64:65]
	s_mov_b32 m0, s42
	s_nop 0
	global_load_lds_dwordx4 v171, s[64:65]
	s_waitcnt lgkmcnt(2)
	v_mfma_f32_16x16x32_bf16 v[64:67], v[136:139], v[156:159], v[64:67]
	v_mfma_f32_16x16x32_bf16 v[60:63], v[146:149], v[156:159], v[60:63]
	ds_read_b128 v[196:199], v174 offset:55296
	s_waitcnt lgkmcnt(2)
	v_mfma_f32_16x16x32_bf16 v[48:51], v[136:139], v[180:183], v[48:51]
	v_mfma_f32_16x16x32_bf16 v[44:47], v[146:149], v[180:183], v[44:47]
	ds_read_b128 v[176:179], v174 offset:50176
	s_waitcnt lgkmcnt(2)
	v_mfma_f32_16x16x32_bf16 v[32:35], v[136:139], v[188:191], v[32:35]
	v_mfma_f32_16x16x32_bf16 v[28:31], v[146:149], v[188:191], v[28:31]
	ds_read_b128 v[184:187], v174 offset:52224
	s_waitcnt lgkmcnt(2)
	v_mfma_f32_16x16x32_bf16 v[16:19], v[136:139], v[196:199], v[16:19]
	v_mfma_f32_16x16x32_bf16 v[12:15], v[146:149], v[196:199], v[12:15]
	ds_read_b128 v[192:195], v174 offset:54272
	s_waitcnt lgkmcnt(2)
	v_mfma_f32_16x16x32_bf16 v[64:67], v[142:145], v[176:179], v[64:67]
	v_mfma_f32_16x16x32_bf16 v[60:63], v[152:155], v[176:179], v[60:63]
	ds_read_b128 v[200:203], v174 offset:56320
	s_waitcnt lgkmcnt(2)
	v_mfma_f32_16x16x32_bf16 v[48:51], v[142:145], v[184:187], v[48:51]
	v_mfma_f32_16x16x32_bf16 v[44:47], v[152:155], v[184:187], v[44:47]
	s_waitcnt lgkmcnt(1)
	v_mfma_f32_16x16x32_bf16 v[32:35], v[142:145], v[192:195], v[32:35]
	v_mfma_f32_16x16x32_bf16 v[28:31], v[152:155], v[192:195], v[28:31]
	s_waitcnt lgkmcnt(0)
	v_mfma_f32_16x16x32_bf16 v[16:19], v[142:145], v[200:203], v[16:19]
	v_mfma_f32_16x16x32_bf16 v[12:15], v[152:155], v[200:203], v[12:15]
	s_add_u32 s28, s28, 0x80000
	s_addc_u32 s29, s29, 0
	s_mov_b32 m0, s43
	s_nop 0
	global_load_lds_dwordx4 v162, s[28:29]
	s_mov_b32 m0, s44
	s_nop 0
	global_load_lds_dwordx4 v170, s[28:29]
	v_mfma_f32_16x16x32_bf16 v[56:59], v[204:207], v[156:159], v[56:59]
	s_add_i32 s61, s61, 2
	s_add_u32 s26, s26, 0xffffff00
	s_addc_u32 s27, s27, -1
	v_mfma_f32_16x16x32_bf16 v[52:55], v[212:215], v[156:159], v[52:55]
	s_add_u32 s24, s24, 0x100
	s_addc_u32 s25, s25, 0
	s_add_u32 s10, s10, 0x100
	v_mfma_f32_16x16x32_bf16 v[40:43], v[204:207], v[180:183], v[40:43]
	s_addc_u32 s11, s11, 0
	s_cmp_lt_u32 s61, 30
	v_mfma_f32_16x16x32_bf16 v[36:39], v[212:215], v[180:183], v[36:39]
	v_mfma_f32_16x16x32_bf16 v[24:27], v[204:207], v[188:191], v[24:27]
	v_mfma_f32_16x16x32_bf16 v[20:23], v[212:215], v[188:191], v[20:23]
	v_mfma_f32_16x16x32_bf16 v[8:11], v[204:207], v[196:199], v[8:11]
	v_mfma_f32_16x16x32_bf16 v[4:7], v[212:215], v[196:199], v[4:7]
	v_mfma_f32_16x16x32_bf16 v[56:59], v[208:211], v[176:179], v[56:59]
	v_mfma_f32_16x16x32_bf16 v[52:55], v[216:219], v[176:179], v[52:55]
	v_mfma_f32_16x16x32_bf16 v[40:43], v[208:211], v[184:187], v[40:43]
	v_mfma_f32_16x16x32_bf16 v[36:39], v[216:219], v[184:187], v[36:39]
	v_mfma_f32_16x16x32_bf16 v[24:27], v[208:211], v[192:195], v[24:27]
	v_mfma_f32_16x16x32_bf16 v[20:23], v[216:219], v[192:195], v[20:23]
	v_mfma_f32_16x16x32_bf16 v[8:11], v[208:211], v[200:203], v[8:11]
	v_mfma_f32_16x16x32_bf16 v[4:7], v[216:219], v[200:203], v[4:7]
	s_cbranch_scc1 .LBB0_275
	s_nor_b64 s[10:11], s[6:7], s[8:9]
	s_and_saveexec_b64 s[24:25], s[10:11]
	s_cbranch_execz .LBB0_278
	v_lshl_add_u32 v132, s14, 8, v140
	v_ashrrev_i32_e32 v133, 31, v132
	v_readlane_b32 s10, v255, 2
	v_lshlrev_b64 v[132:133], 7, v[132:133]
	v_readlane_b32 s11, v255, 3
	s_nop 1
	v_lshl_add_u64 v[152:153], s[10:11], 0, v[132:133]
	global_load_dwordx4 v[132:135], v[152:153], off offset:48
	global_load_dwordx4 v[136:139], v[152:153], off offset:32
	global_load_dwordx4 v[142:145], v[152:153], off
	global_load_dwordx4 v[146:149], v[152:153], off offset:16
	s_waitcnt vmcnt(0)
	v_pk_add_f32 v[144:145], v[144:145], v[148:149]
	v_pk_add_f32 v[142:143], v[142:143], v[146:147]
	v_pk_add_f32 v[138:139], v[144:145], v[138:139]
	v_pk_add_f32 v[136:137], v[142:143], v[136:137]
	v_pk_add_f32 v[154:155], v[138:139], v[134:135]
	v_pk_add_f32 v[156:157], v[136:137], v[132:133]
	global_load_dwordx4 v[132:135], v[152:153], off offset:112
	global_load_dwordx4 v[136:139], v[152:153], off offset:96
	global_load_dwordx4 v[142:145], v[152:153], off offset:80
	global_load_dwordx4 v[146:149], v[152:153], off offset:64
	s_waitcnt vmcnt(0)
	v_pk_add_f32 v[148:149], v[154:155], v[148:149]
	v_pk_add_f32 v[146:147], v[156:157], v[146:147]
	v_pk_add_f32 v[144:145], v[148:149], v[144:145]
	v_pk_add_f32 v[142:143], v[146:147], v[142:143]
	v_pk_add_f32 v[138:139], v[144:145], v[138:139]
	v_pk_add_f32 v[136:137], v[142:143], v[136:137]
	v_pk_add_f32 v[134:135], v[138:139], v[134:135]
	v_pk_add_f32 v[132:133], v[136:137], v[132:133]
	s_nop 0
	v_pk_mov_b32 v[136:137], v[132:133], v[134:135] op_sel:[1,0]
	v_mov_b32_e32 v133, v135
	v_pk_add_f32 v[132:133], v[136:137], v[132:133]
	s_nop 0
	v_add_f32_e32 v132, v132, v133
	v_fmamk_f32 v132, v132, 0x3a000000, v164
	v_cmp_gt_f32_e32 vcc, s69, v132
	v_mul_f32_e32 v133, 0x4f800000, v132
	s_nop 0
	v_cndmask_b32_e32 v132, v132, v133, vcc
	v_sqrt_f32_e32 v133, v132
	s_nop 0
	v_add_u32_e32 v134, -1, v133
	v_fma_f32 v135, -v134, v133, v132
	v_cmp_ge_f32_e64 s[10:11], 0, v135
	v_add_u32_e32 v135, 1, v133
	s_nop 0
	v_cndmask_b32_e64 v134, v133, v134, s[10:11]
	v_fma_f32 v133, -v135, v133, v132
	v_cmp_lt_f32_e64 s[10:11], 0, v133
	s_nop 1
	v_cndmask_b32_e64 v133, v134, v135, s[10:11]
	v_mul_f32_e32 v134, 0x37800000, v133
	v_cndmask_b32_e32 v133, v133, v134, vcc
	v_cmp_class_f32_e32 vcc, v132, v165
	s_nop 1
	v_cndmask_b32_e32 v132, v133, v132, vcc
	v_div_scale_f32 v133, s[10:11], v132, v132, 1.0
	v_rcp_f32_e32 v134, v133
	s_lshl_b32 s10, s59, 10
	s_and_b32 s10, s10, 0x400
	v_fma_f32 v135, -v133, v134, 1.0
	v_fmac_f32_e32 v134, v135, v134
	v_div_scale_f32 v135, vcc, 1.0, v132, 1.0
	v_mul_f32_e32 v136, v135, v134
	v_fma_f32 v137, -v133, v136, v135
	v_fmac_f32_e32 v136, v137, v134
	v_fma_f32 v133, -v133, v136, v135
	v_div_fmas_f32 v133, v133, v134, v136
	v_div_fixup_f32 v132, v133, v132, 1.0
	v_add_u32_e32 v133, s10, v172
	ds_write_b32 v133, v132

; template <class Epi, class Sched>
; __device__ __forceinline__ void gemm_simple(PG8_LAS unsigned char* lds, const Gemm g, const Sched& S, const Epi& E, int wave_s) {
;     ...
;         for (; t < nt; t += 2) {
;             const bool last = (t == nt - 2);
;             PG8_TILE(0, cA + (size_t)(t + 1) * kstep, cB + (size_t)(t + 1) * kstep, true);
.LBB0_307:
	s_waitcnt vmcnt(2) lgkmcnt(0)
	s_barrier
	ds_read_b128 v[136:139], v132
	ds_read_b128 v[178:181], v177
	ds_read_b128 v[156:159], v132 offset:2048
	ds_read_b128 v[186:189], v177 offset:2048
	ds_read_b128 v[194:197], v177 offset:4096
	s_add_u32 s60, s10, s59
	s_addc_u32 s61, s11, 0
	s_add_u32 s24, s60, 0x80
	s_addc_u32 s25, s61, 0
	s_mov_b32 m0, s43
	s_nop 0
	global_load_lds_dwordx4 v172, s[24:25]
	s_mov_b32 m0, s49
	s_nop 0
	global_load_lds_dwordx4 v174, s[24:25]
	s_waitcnt lgkmcnt(3)
	v_mfma_f32_16x16x32_bf16 v[120:123], v[136:139], v[178:181], v[120:123]
	s_waitcnt lgkmcnt(2)
	v_mfma_f32_16x16x32_bf16 v[116:119], v[156:159], v[178:181], v[116:119]
	ds_read_b128 v[202:205], v177 offset:6144
	s_waitcnt lgkmcnt(2)
	v_mfma_f32_16x16x32_bf16 v[104:107], v[136:139], v[186:189], v[104:107]
	v_mfma_f32_16x16x32_bf16 v[100:103], v[156:159], v[186:189], v[100:103]
	ds_read_b128 v[152:155], v132 offset:1024
	ds_read_b128 v[182:185], v177 offset:1024
	s_waitcnt lgkmcnt(3)
	v_mfma_f32_16x16x32_bf16 v[88:91], v[136:139], v[194:197], v[88:91]
	ds_read_b128 v[160:163], v132 offset:3072
	v_mfma_f32_16x16x32_bf16 v[84:87], v[156:159], v[194:197], v[84:87]
	ds_read_b128 v[190:193], v177 offset:3072
	s_waitcnt lgkmcnt(4)
	v_mfma_f32_16x16x32_bf16 v[72:75], v[136:139], v[202:205], v[72:75]
	v_mfma_f32_16x16x32_bf16 v[68:71], v[156:159], v[202:205], v[68:71]
	ds_read_b128 v[198:201], v177 offset:5120
	s_waitcnt lgkmcnt(3)
	v_mfma_f32_16x16x32_bf16 v[120:123], v[152:155], v[182:185], v[120:123]
	s_waitcnt lgkmcnt(2)
	v_mfma_f32_16x16x32_bf16 v[116:119], v[160:163], v[182:185], v[116:119]
	ds_read_b128 v[206:209], v177 offset:7168
	s_waitcnt lgkmcnt(2)
	v_mfma_f32_16x16x32_bf16 v[104:107], v[152:155], v[190:193], v[104:107]
	v_mfma_f32_16x16x32_bf16 v[100:103], v[160:163], v[190:193], v[100:103]
	ds_read_b128 v[210:213], v133
	s_waitcnt lgkmcnt(2)
	v_mfma_f32_16x16x32_bf16 v[88:91], v[152:155], v[198:201], v[88:91]
	ds_read_b128 v[218:221], v133 offset:2048
	v_mfma_f32_16x16x32_bf16 v[84:87], v[160:163], v[198:201], v[84:87]
	s_waitcnt lgkmcnt(2)
	v_mfma_f32_16x16x32_bf16 v[72:75], v[152:155], v[206:209], v[72:75]
	v_mfma_f32_16x16x32_bf16 v[68:71], v[160:163], v[206:209], v[68:71]
	s_add_u32 s62, s20, s59
	s_addc_u32 s63, s21, 0
	s_add_u32 s24, s62, 0x80
	s_addc_u32 s25, s63, 0
	s_mov_b32 m0, s44
	s_nop 0
	global_load_lds_dwordx4 v171, s[24:25]
	s_mov_b32 m0, s50
	s_nop 0
	global_load_lds_dwordx4 v173, s[24:25]
	s_waitcnt lgkmcnt(1)
	v_mfma_f32_16x16x32_bf16 v[128:131], v[210:213], v[178:181], v[128:131]
	s_waitcnt lgkmcnt(0)
	v_mfma_f32_16x16x32_bf16 v[124:127], v[218:221], v[178:181], v[124:127]
	v_mfma_f32_16x16x32_bf16 v[112:115], v[210:213], v[186:189], v[112:115]
	v_mfma_f32_16x16x32_bf16 v[108:111], v[218:221], v[186:189], v[108:111]
	ds_read_b128 v[214:217], v133 offset:1024
	v_mfma_f32_16x16x32_bf16 v[96:99], v[210:213], v[194:197], v[96:99]
	ds_read_b128 v[222:225], v133 offset:3072
	v_mfma_f32_16x16x32_bf16 v[92:95], v[218:221], v[194:197], v[92:95]
	v_mfma_f32_16x16x32_bf16 v[80:83], v[210:213], v[202:205], v[80:83]
	v_mfma_f32_16x16x32_bf16 v[76:79], v[218:221], v[202:205], v[76:79]
	s_waitcnt lgkmcnt(1)
	v_mfma_f32_16x16x32_bf16 v[128:131], v[214:217], v[182:185], v[128:131]
	s_waitcnt lgkmcnt(0)
	v_mfma_f32_16x16x32_bf16 v[124:127], v[222:225], v[182:185], v[124:127]
	v_mfma_f32_16x16x32_bf16 v[112:115], v[214:217], v[190:193], v[112:115]
	v_mfma_f32_16x16x32_bf16 v[108:111], v[222:225], v[190:193], v[108:111]
	v_mfma_f32_16x16x32_bf16 v[96:99], v[214:217], v[198:201], v[96:99]
	v_mfma_f32_16x16x32_bf16 v[92:95], v[222:225], v[198:201], v[92:95]
	v_mfma_f32_16x16x32_bf16 v[80:83], v[214:217], v[206:209], v[80:83]
	v_mfma_f32_16x16x32_bf16 v[76:79], v[222:225], v[206:209], v[76:79]
	s_waitcnt vmcnt(4) lgkmcnt(0)
	s_barrier
	ds_read_b128 v[178:181], v177 offset:16384
	ds_read_b128 v[186:189], v177 offset:18432
	ds_read_b128 v[194:197], v177 offset:20480
	s_add_u32 s24, s60, 0x80080
	s_addc_u32 s25, s61, 0
	s_mov_b32 m0, s45
	s_nop 0
	global_load_lds_dwordx4 v172, s[24:25]
	s_mov_b32 m0, s51
	s_nop 0
	global_load_lds_dwordx4 v174, s[24:25]
	s_waitcnt lgkmcnt(2)
	v_mfma_f32_16x16x32_bf16 v[56:59], v[136:139], v[178:181], v[56:59]
	v_mfma_f32_16x16x32_bf16 v[52:55], v[156:159], v[178:181], v[52:55]
	ds_read_b128 v[202:205], v177 offset:22528
	s_waitcnt lgkmcnt(2)
	v_mfma_f32_16x16x32_bf16 v[40:43], v[136:139], v[186:189], v[40:43]
	v_mfma_f32_16x16x32_bf16 v[36:39], v[156:159], v[186:189], v[36:39]
	ds_read_b128 v[182:185], v177 offset:17408
	s_waitcnt lgkmcnt(2)
	v_mfma_f32_16x16x32_bf16 v[24:27], v[136:139], v[194:197], v[24:27]
	v_mfma_f32_16x16x32_bf16 v[20:23], v[156:159], v[194:197], v[20:23]
	ds_read_b128 v[190:193], v177 offset:19456
	s_waitcnt lgkmcnt(2)
	v_mfma_f32_16x16x32_bf16 v[8:11], v[136:139], v[202:205], v[8:11]
	v_mfma_f32_16x16x32_bf16 v[4:7], v[156:159], v[202:205], v[4:7]
	ds_read_b128 v[198:201], v177 offset:21504
	s_waitcnt lgkmcnt(2)
	v_mfma_f32_16x16x32_bf16 v[56:59], v[152:155], v[182:185], v[56:59]
	v_mfma_f32_16x16x32_bf16 v[52:55], v[160:163], v[182:185], v[52:55]
	ds_read_b128 v[206:209], v177 offset:23552
	s_waitcnt lgkmcnt(2)
	v_mfma_f32_16x16x32_bf16 v[40:43], v[152:155], v[190:193], v[40:43]
	v_mfma_f32_16x16x32_bf16 v[36:39], v[160:163], v[190:193], v[36:39]
	s_waitcnt lgkmcnt(1)
	v_mfma_f32_16x16x32_bf16 v[24:27], v[152:155], v[198:201], v[24:27]
	v_mfma_f32_16x16x32_bf16 v[20:23], v[160:163], v[198:201], v[20:23]
	s_waitcnt lgkmcnt(0)
	v_mfma_f32_16x16x32_bf16 v[8:11], v[152:155], v[206:209], v[8:11]
	v_mfma_f32_16x16x32_bf16 v[4:7], v[160:163], v[206:209], v[4:7]
	s_add_u32 s24, s62, 0x80080
	s_addc_u32 s25, s63, 0
	s_mov_b32 m0, s46
	s_nop 0
	global_load_lds_dwordx4 v171, s[24:25]
	s_mov_b32 m0, s52
	s_nop 0
	global_load_lds_dwordx4 v173, s[24:25]
	v_mfma_f32_16x16x32_bf16 v[64:67], v[210:213], v[178:181], v[64:67]
	s_add_u32 s24, s62, 0x100
	s_addc_u32 s25, s63, 0
	s_add_u32 s60, s60, 0x100
	v_mfma_f32_16x16x32_bf16 v[60:63], v[218:221], v[178:181], v[60:63]
	s_addc_u32 s61, s61, 0
	v_mfma_f32_16x16x32_bf16 v[48:51], v[210:213], v[186:189], v[48:51]
	v_mfma_f32_16x16x32_bf16 v[44:47], v[218:221], v[186:189], v[44:47]
	v_mfma_f32_16x16x32_bf16 v[32:35], v[210:213], v[194:197], v[32:35]
	v_mfma_f32_16x16x32_bf16 v[28:31], v[218:221], v[194:197], v[28:31]
	v_mfma_f32_16x16x32_bf16 v[12:15], v[210:213], v[202:205], v[12:15]
	v_mfma_f32_16x16x32_bf16 v[16:19], v[218:221], v[202:205], v[16:19]
	v_mfma_f32_16x16x32_bf16 v[64:67], v[214:217], v[182:185], v[64:67]
	v_mfma_f32_16x16x32_bf16 v[60:63], v[222:225], v[182:185], v[60:63]
	v_mfma_f32_16x16x32_bf16 v[48:51], v[214:217], v[190:193], v[48:51]
	v_mfma_f32_16x16x32_bf16 v[44:47], v[222:225], v[190:193], v[44:47]
	v_mfma_f32_16x16x32_bf16 v[32:35], v[214:217], v[198:201], v[32:35]
	v_mfma_f32_16x16x32_bf16 v[28:31], v[222:225], v[198:201], v[28:31]
	v_mfma_f32_16x16x32_bf16 v[12:15], v[214:217], v[206:209], v[12:15]
	v_mfma_f32_16x16x32_bf16 v[16:19], v[222:225], v[206:209], v[16:19]
	s_waitcnt vmcnt(2) lgkmcnt(0)
	s_barrier
; template <class Epi, class Sched>
; __device__ __forceinline__ void gemm_simple(PG8_LAS unsigned char* lds, const Gemm g, const Sched& S, const Epi& E, int wave_s) {
;     ...
;             const char* a2 = last ? nA : cA + (size_t)(t + 2) * kstep; const char* b2 = last ? nB : cB + (size_t)(t + 2) * kstep;
;             PG8_TILE(1, a2, b2, (!last || has_next));
	ds_read_b128 v[136:139], v134
	ds_read_b128 v[178:181], v177 offset:32768
	ds_read_b128 v[156:159], v134 offset:2048
	ds_read_b128 v[186:189], v177 offset:34816
	ds_read_b128 v[194:197], v177 offset:36864
	s_cmp_eq_u32 s59, s22
	s_cselect_b32 s25, s13, s25
	s_cselect_b32 s24, s56, s24
	s_cselect_b32 s61, s5, s61
	s_cselect_b32 s60, s57, s60
	s_mov_b32 m0, s27
	s_nop 0
	global_load_lds_dwordx4 v172, s[60:61]
	s_mov_b32 m0, s28
	s_nop 0
	global_load_lds_dwordx4 v174, s[60:61]
	s_waitcnt lgkmcnt(3)
	v_mfma_f32_16x16x32_bf16 v[120:123], v[136:139], v[178:181], v[120:123]
	s_waitcnt lgkmcnt(2)
	v_mfma_f32_16x16x32_bf16 v[116:119], v[156:159], v[178:181], v[116:119]
	ds_read_b128 v[202:205], v177 offset:38912
	s_waitcnt lgkmcnt(2)
	v_mfma_f32_16x16x32_bf16 v[104:107], v[136:139], v[186:189], v[104:107]
	v_mfma_f32_16x16x32_bf16 v[100:103], v[156:159], v[186:189], v[100:103]
	ds_read_b128 v[152:155], v134 offset:1024
	ds_read_b128 v[182:185], v177 offset:33792
	s_waitcnt lgkmcnt(3)
	v_mfma_f32_16x16x32_bf16 v[88:91], v[136:139], v[194:197], v[88:91]
	ds_read_b128 v[160:163], v134 offset:3072
	v_mfma_f32_16x16x32_bf16 v[84:87], v[156:159], v[194:197], v[84:87]
	ds_read_b128 v[190:193], v177 offset:35840
	s_waitcnt lgkmcnt(4)
	v_mfma_f32_16x16x32_bf16 v[72:75], v[136:139], v[202:205], v[72:75]
	v_mfma_f32_16x16x32_bf16 v[68:71], v[156:159], v[202:205], v[68:71]
	ds_read_b128 v[198:201], v177 offset:37888
	s_waitcnt lgkmcnt(3)
	v_mfma_f32_16x16x32_bf16 v[120:123], v[152:155], v[182:185], v[120:123]
	s_waitcnt lgkmcnt(2)
	v_mfma_f32_16x16x32_bf16 v[116:119], v[160:163], v[182:185], v[116:119]
	ds_read_b128 v[206:209], v177 offset:39936
	s_waitcnt lgkmcnt(2)
	v_mfma_f32_16x16x32_bf16 v[104:107], v[152:155], v[190:193], v[104:107]
	v_mfma_f32_16x16x32_bf16 v[100:103], v[160:163], v[190:193], v[100:103]
	ds_read_b128 v[210:213], v135
	s_waitcnt lgkmcnt(2)
	v_mfma_f32_16x16x32_bf16 v[88:91], v[152:155], v[198:201], v[88:91]
	ds_read_b128 v[218:221], v135 offset:2048
	v_mfma_f32_16x16x32_bf16 v[84:87], v[160:163], v[198:201], v[84:87]
	s_waitcnt lgkmcnt(2)
	v_mfma_f32_16x16x32_bf16 v[72:75], v[152:155], v[206:209], v[72:75]
	v_mfma_f32_16x16x32_bf16 v[68:71], v[160:163], v[206:209], v[68:71]
	s_mov_b32 m0, s19
	s_nop 0
	global_load_lds_dwordx4 v171, s[24:25]
	s_mov_b32 m0, s29
	s_nop 0
	global_load_lds_dwordx4 v173, s[24:25]
	s_waitcnt lgkmcnt(1)
	v_mfma_f32_16x16x32_bf16 v[128:131], v[210:213], v[178:181], v[128:131]
	s_waitcnt lgkmcnt(0)
	v_mfma_f32_16x16x32_bf16 v[124:127], v[218:221], v[178:181], v[124:127]
	v_mfma_f32_16x16x32_bf16 v[112:115], v[210:213], v[186:189], v[112:115]
	v_mfma_f32_16x16x32_bf16 v[108:111], v[218:221], v[186:189], v[108:111]
	ds_read_b128 v[214:217], v135 offset:1024
	v_mfma_f32_16x16x32_bf16 v[96:99], v[210:213], v[194:197], v[96:99]
	ds_read_b128 v[222:225], v135 offset:3072
	v_mfma_f32_16x16x32_bf16 v[92:95], v[218:221], v[194:197], v[92:95]
	v_mfma_f32_16x16x32_bf16 v[80:83], v[210:213], v[202:205], v[80:83]
	v_mfma_f32_16x16x32_bf16 v[76:79], v[218:221], v[202:205], v[76:79]
	s_waitcnt lgkmcnt(1)
	v_mfma_f32_16x16x32_bf16 v[128:131], v[214:217], v[182:185], v[128:131]
	s_waitcnt lgkmcnt(0)
	v_mfma_f32_16x16x32_bf16 v[124:127], v[222:225], v[182:185], v[124:127]
	v_mfma_f32_16x16x32_bf16 v[112:115], v[214:217], v[190:193], v[112:115]
	v_mfma_f32_16x16x32_bf16 v[108:111], v[222:225], v[190:193], v[108:111]
	v_mfma_f32_16x16x32_bf16 v[96:99], v[214:217], v[198:201], v[96:99]
	v_mfma_f32_16x16x32_bf16 v[92:95], v[222:225], v[198:201], v[92:95]
	v_mfma_f32_16x16x32_bf16 v[80:83], v[214:217], v[206:209], v[80:83]
	v_mfma_f32_16x16x32_bf16 v[76:79], v[222:225], v[206:209], v[76:79]
	s_waitcnt vmcnt(4) lgkmcnt(0)
	s_barrier
; #define LAS __attribute__((address_space(3)))
; __device__ __forceinline__ void rstd_table(const float* ssq, LAS unsigned char* lds, const Unit& u, int tid, int par) {
;     if (tid < 256) { const f32x4* p = (const f32x4*)(ssq + (size_t)(u.pm * 256 + tid) * 32); f32x4 a = p[0];
; #pragma unroll
;         for (int i = 1; i < 8; ++i) a += p[i];
;         ((LAS float*)(lds + 131072 + par * 1024))[tid] = 1.0f / sqrtf(((a[0] + a[1]) + (a[2] + a[3])) * (1.0f / DM) + 1e-6f); }
	ds_read_b128 v[178:181], v177 offset:49152
	ds_read_b128 v[186:189], v177 offset:51200
	ds_read_b128 v[194:197], v177 offset:53248
	s_add_u32 s60, s60, 0x80000
	s_addc_u32 s61, s61, 0
	s_mov_b32 m0, s36
	s_nop 0
	global_load_lds_dwordx4 v172, s[60:61]
	s_mov_b32 m0, s37
	s_nop 0
	global_load_lds_dwordx4 v174, s[60:61]
	s_waitcnt lgkmcnt(2)
	v_mfma_f32_16x16x32_bf16 v[56:59], v[136:139], v[178:181], v[56:59]
	v_mfma_f32_16x16x32_bf16 v[52:55], v[156:159], v[178:181], v[52:55]
	ds_read_b128 v[202:205], v177 offset:55296
	s_waitcnt lgkmcnt(2)
	v_mfma_f32_16x16x32_bf16 v[40:43], v[136:139], v[186:189], v[40:43]
	v_mfma_f32_16x16x32_bf16 v[36:39], v[156:159], v[186:189], v[36:39]
	ds_read_b128 v[182:185], v177 offset:50176
	s_waitcnt lgkmcnt(2)
	v_mfma_f32_16x16x32_bf16 v[24:27], v[136:139], v[194:197], v[24:27]
	v_mfma_f32_16x16x32_bf16 v[20:23], v[156:159], v[194:197], v[20:23]
	ds_read_b128 v[190:193], v177 offset:52224
	s_waitcnt lgkmcnt(2)
	v_mfma_f32_16x16x32_bf16 v[8:11], v[136:139], v[202:205], v[8:11]
	v_mfma_f32_16x16x32_bf16 v[4:7], v[156:159], v[202:205], v[4:7]
	ds_read_b128 v[198:201], v177 offset:54272
	s_waitcnt lgkmcnt(2)
	v_mfma_f32_16x16x32_bf16 v[56:59], v[152:155], v[182:185], v[56:59]
	v_mfma_f32_16x16x32_bf16 v[52:55], v[160:163], v[182:185], v[52:55]
	ds_read_b128 v[206:209], v177 offset:56320
	s_waitcnt lgkmcnt(2)
	v_mfma_f32_16x16x32_bf16 v[40:43], v[152:155], v[190:193], v[40:43]
	v_mfma_f32_16x16x32_bf16 v[36:39], v[160:163], v[190:193], v[36:39]
	s_waitcnt lgkmcnt(1)
	v_mfma_f32_16x16x32_bf16 v[24:27], v[152:155], v[198:201], v[24:27]
	v_mfma_f32_16x16x32_bf16 v[20:23], v[160:163], v[198:201], v[20:23]
	s_waitcnt lgkmcnt(0)
	v_mfma_f32_16x16x32_bf16 v[8:11], v[152:155], v[206:209], v[8:11]
	v_mfma_f32_16x16x32_bf16 v[4:7], v[160:163], v[206:209], v[4:7]
	s_add_u32 s24, s24, 0x80000
	s_addc_u32 s25, s25, 0
	s_mov_b32 m0, s38
	s_nop 0
	global_load_lds_dwordx4 v171, s[24:25]
	s_mov_b32 m0, s39
	s_nop 0
	global_load_lds_dwordx4 v173, s[24:25]
	v_mfma_f32_16x16x32_bf16 v[64:67], v[210:213], v[178:181], v[64:67]
	s_add_i32 s58, s58, 2
	s_add_u32 s22, s22, 0xffffff00
	s_addc_u32 s23, s23, -1
	v_mfma_f32_16x16x32_bf16 v[60:63], v[218:221], v[178:181], v[60:63]
	s_add_u32 s20, s20, 0x100
	s_addc_u32 s21, s21, 0
	s_add_u32 s10, s10, 0x100
	v_mfma_f32_16x16x32_bf16 v[48:51], v[210:213], v[186:189], v[48:51]
	s_addc_u32 s11, s11, 0
	s_cmp_lt_u32 s58, 30
	v_mfma_f32_16x16x32_bf16 v[44:47], v[218:221], v[186:189], v[44:47]
	v_mfma_f32_16x16x32_bf16 v[32:35], v[210:213], v[194:197], v[32:35]
	v_mfma_f32_16x16x32_bf16 v[28:31], v[218:221], v[194:197], v[28:31]
	v_mfma_f32_16x16x32_bf16 v[12:15], v[210:213], v[202:205], v[12:15]
	v_mfma_f32_16x16x32_bf16 v[16:19], v[218:221], v[202:205], v[16:19]
	v_mfma_f32_16x16x32_bf16 v[64:67], v[214:217], v[182:185], v[64:67]
	v_mfma_f32_16x16x32_bf16 v[60:63], v[222:225], v[182:185], v[60:63]
	v_mfma_f32_16x16x32_bf16 v[48:51], v[214:217], v[190:193], v[48:51]
	v_mfma_f32_16x16x32_bf16 v[44:47], v[222:225], v[190:193], v[44:47]
	v_mfma_f32_16x16x32_bf16 v[32:35], v[214:217], v[198:201], v[32:35]
	v_mfma_f32_16x16x32_bf16 v[28:31], v[222:225], v[198:201], v[28:31]
	v_mfma_f32_16x16x32_bf16 v[12:15], v[214:217], v[206:209], v[12:15]
	v_mfma_f32_16x16x32_bf16 v[16:19], v[222:225], v[206:209], v[16:19]
	s_cbranch_scc1 .LBB0_307
	s_nor_b64 s[10:11], s[6:7], s[8:9]
	s_and_saveexec_b64 s[20:21], s[10:11]
	s_cbranch_execz .LBB0_310
	v_lshl_add_u32 v132, s12, 8, v170
	v_ashrrev_i32_e32 v133, 31, v132
	v_readlane_b32 s10, v255, 2
	v_lshlrev_b64 v[132:133], 7, v[132:133]
	v_readlane_b32 s11, v255, 3
	s_lshl_b32 s5, s54, 10
	s_and_b32 s5, s5, 0x400
	v_lshl_add_u64 v[142:143], s[10:11], 0, v[132:133]
	global_load_dwordx4 v[132:135], v[142:143], off offset:48
	global_load_dwordx4 v[136:139], v[142:143], off offset:32
	global_load_dwordx4 v[152:155], v[142:143], off
	global_load_dwordx4 v[156:159], v[142:143], off offset:16
	s_waitcnt vmcnt(0)
	v_pk_add_f32 v[144:145], v[154:155], v[158:159]
	v_pk_add_f32 v[146:147], v[152:153], v[156:157]
	v_pk_add_f32 v[138:139], v[144:145], v[138:139]
	v_pk_add_f32 v[136:137], v[146:147], v[136:137]
	v_pk_add_f32 v[144:145], v[138:139], v[134:135]
	v_pk_add_f32 v[146:147], v[136:137], v[132:133]
	global_load_dwordx4 v[132:135], v[142:143], off offset:112
	global_load_dwordx4 v[136:139], v[142:143], off offset:96
	global_load_dwordx4 v[152:155], v[142:143], off offset:80
	global_load_dwordx4 v[156:159], v[142:143], off offset:64
	s_waitcnt vmcnt(0)
	v_pk_add_f32 v[142:143], v[144:145], v[158:159]
	v_pk_add_f32 v[144:145], v[146:147], v[156:157]
	v_pk_add_f32 v[142:143], v[142:143], v[154:155]
	v_pk_add_f32 v[144:145], v[144:145], v[152:153]
	v_pk_add_f32 v[138:139], v[142:143], v[138:139]
	v_pk_add_f32 v[136:137], v[144:145], v[136:137]
	v_pk_add_f32 v[134:135], v[138:139], v[134:135]
	v_pk_add_f32 v[132:133], v[136:137], v[132:133]
	s_nop 0
	v_pk_mov_b32 v[136:137], v[132:133], v[134:135] op_sel:[1,0]
	v_mov_b32_e32 v133, v135
	v_pk_add_f32 v[132:133], v[136:137], v[132:133]
	s_nop 0
	v_add_f32_e32 v132, v132, v133
	v_fmamk_f32 v132, v132, 0x3a000000, v164
	v_cmp_gt_f32_e32 vcc, s69, v132
	v_mul_f32_e32 v133, 0x4f800000, v132
	s_nop 0
	v_cndmask_b32_e32 v132, v132, v133, vcc
	v_sqrt_f32_e32 v133, v132
	s_nop 0
	v_add_u32_e32 v134, -1, v133
	v_fma_f32 v135, -v134, v133, v132
	v_cmp_ge_f32_e64 s[10:11], 0, v135
	v_add_u32_e32 v135, 1, v133
	s_nop 0
	v_cndmask_b32_e64 v134, v133, v134, s[10:11]
	v_fma_f32 v133, -v135, v133, v132
	v_cmp_lt_f32_e64 s[10:11], 0, v133
	s_nop 1
	v_cndmask_b32_e64 v133, v134, v135, s[10:11]
	v_mul_f32_e32 v134, 0x37800000, v133
	v_cndmask_b32_e32 v133, v133, v134, vcc
	v_cmp_class_f32_e32 vcc, v132, v165
	s_nop 1
	v_cndmask_b32_e32 v132, v133, v132, vcc
	v_div_scale_f32 v133, s[10:11], v132, v132, 1.0
	v_rcp_f32_e32 v134, v133
	s_nop 0
	v_fma_f32 v135, -v133, v134, 1.0
	v_fmac_f32_e32 v134, v135, v134
	v_div_scale_f32 v135, vcc, 1.0, v132, 1.0
	v_mul_f32_e32 v136, v135, v134
	v_fma_f32 v137, -v133, v136, v135
	v_fmac_f32_e32 v136, v137, v134
	v_fma_f32 v133, -v133, v136, v135
	v_div_fmas_f32 v133, v133, v134, v136
	v_div_fixup_f32 v132, v133, v132, 1.0
	v_add_u32_e32 v133, s5, v175
	ds_write_b32 v133, v132
